# Hyena FFT stagger: waves 4-7 sleep 16x64 cycles at the head of the two three-pass chains per channel
# baseline (speedup 1.0000x reference)
; #define LAS __attribute__((address_space(3)))
; #define WG_SYNC() do { asm volatile("s_waitcnt lgkmcnt(0)" ::: "memory"); __builtin_amdgcn_s_barrier(); asm volatile("" ::: "memory"); } while (0)
; template <bool INV> __device__ __forceinline__ void dft16(f32x2 (&x)[16]) {
;     constexpr float C1 = 0.92387953251128674f, S1 = 0.38268343236508977f, C2 = 0.70710678118654752f;
; #pragma unroll
;     for (int b = 0; b < 4; ++b) dft4<INV>(x[b], x[4 + b], x[8 + b], x[12 + b]);
; template <bool LO> __device__ __forceinline__ void fft_fwd1(f32x2 (&x)[16], LAS f32x2* B, int n2, const f32x2 (&w)[16]) {
;     asm volatile("" : "+v"(n2));
;     if (LO) dft16_fwd_lo(x); else dft16<false>(x);
; __device__ __forceinline__ void hy_stage(LAS float* plane, const bf16_t* PHY, int cg, int jc, int tid) {
;     ...
;     const u32x4* src = (const u32x4*)(PHY + (size_t)cg * MT * 4);
; #pragma unroll
;     for (int k = 0; k < 8; ++k) { const int i = tid + 512 * k; const u32x4 v = src[i];
;         const unsigned w0 = (jc & 2) ? v.y : v.x, w1 = (jc & 2) ? v.w : v.z;
;         f32x2 o; o.x = (jc & 1) ? bf_hi(w0) : bf_lo(w0); o.y = (jc & 1) ? bf_hi(w1) : bf_lo(w1);
; __device__ __forceinline__ void hyena_fft(LAS unsigned char* lds, int layer, int G, const int wave_s) {
;     ...
;         for (int c = c_lo; c < c_hi; ++c) { const int unit = c >> 2, jc = c & 3;
;             WG_SYNC();
;             { f32x2 x[16]; const unsigned* tf = TF + (size_t)c * SEQ; const unsigned* tb = TB + (size_t)c * SEQ;
; #pragma unroll
;               for (int r = 0; r < 8; ++r) { const unsigned w = tf[n2 + 512 * r]; x[r] = (f32x2){bf_lo(w), bf_hi(w)}; }
; #pragma unroll
;               for (int r = 8; r < 16; ++r) { const int l = FN - 512 * r - n2; const unsigned w = l < SEQ ? tb[l] : 0u; x[r] = (f32x2){bf_lo(w), bf_hi(w)}; }
;               __builtin_amdgcn_sched_barrier(0); fft_fwd1<false>(x, Fb, n2, w1p); __builtin_amdgcn_sched_barrier(0); }
;             hy_stage(pl0, PHY, 2 * (HY / 4) + unit, jc, tid); __builtin_amdgcn_sched_barrier(0); hy_stage(pl1, PHY, unit, jc, tid); __builtin_amdgcn_sched_barrier(0);
.Lhfft_loop:
	s_lshr_b32 s43, s80, 2
	s_mul_i32 s73, s43, 0x11000
	s_and_b32 s43, s80, 2
	s_lshl_b32 s43, s43, 1
	s_add_u32 s73, s73, s43
	s_and_b32 s43, s80, 1
	s_mov_b32 s15, 0x1000c0c
	s_cmp_eq_u32 s43, 0
	s_cselect_b32 s15, s15, 0x3020c0c
	s_lshl_b32 s43, s80, 14
	s_add_u32 s46, s36, s43
	s_addc_u32 s47, s37, 0
	s_add_u32 s50, s46, 0x4000000
	s_addc_u32 s51, s47, 0
	s_waitcnt lgkmcnt(0)
	s_barrier
	s_add_u32 s60, s46, 0
	s_addc_u32 s61, s47, 0
	global_load_dword v176, v212, s[60:61]
	global_load_dword v178, v212, s[60:61] offset:2048
	s_add_u32 s60, s46, 0x1000
	s_addc_u32 s61, s47, 0
	global_load_dword v180, v212, s[60:61]
	global_load_dword v182, v212, s[60:61] offset:2048
	s_add_u32 s60, s46, 0x2000
	s_addc_u32 s61, s47, 0
	global_load_dword v184, v212, s[60:61]
	global_load_dword v186, v212, s[60:61] offset:2048
	s_add_u32 s60, s46, 0x3000
	s_addc_u32 s61, s47, 0
	global_load_dword v188, v212, s[60:61]
	global_load_dword v166, v212, s[60:61] offset:2048
	s_add_u32 s62, s50, 0x3000
	s_addc_u32 s63, s51, 0
	global_load_dword v177, v214, s[62:63] offset:2048
	global_load_dword v179, v214, s[62:63]
	s_add_u32 s62, s50, 0x2000
	s_addc_u32 s63, s51, 0
	global_load_dword v181, v214, s[62:63] offset:2048
	global_load_dword v183, v214, s[62:63]
	s_add_u32 s62, s50, 0x1000
	s_addc_u32 s63, s51, 0
	global_load_dword v185, v214, s[62:63] offset:2048
	global_load_dword v187, v214, s[62:63]
	s_add_u32 s62, s50, 0
	s_addc_u32 s63, s51, 0
	global_load_dword v189, v214, s[62:63] offset:2048
	global_load_dword v167, v214, s[62:63]
	s_add_u32 s56, s38, s73
	s_addc_u32 s57, s39, 0
	s_add_u32 s56, s56, 0x2200000
	s_addc_u32 s57, s57, 0
	global_load_dwordx3 v[58:60], v216, s[56:57]
	global_load_dwordx3 v[62:64], v218, s[56:57]
	global_load_dwordx3 v[66:68], v220, s[56:57]
	global_load_dwordx3 v[70:72], v222, s[56:57]
	global_load_dwordx3 v[74:76], v240, s[56:57]
	global_load_dwordx3 v[78:80], v242, s[56:57]
	global_load_dwordx3 v[82:84], v244, s[56:57]
	global_load_dwordx3 v[86:88], v61, s[56:57]
	s_waitcnt vmcnt(23)
	v_and_b32_e32 v101, 0xffff0000, v176
	v_lshlrev_b32_e32 v100, 16, v176
	s_waitcnt vmcnt(22)
	v_and_b32_e32 v103, 0xffff0000, v178
	v_lshlrev_b32_e32 v102, 16, v178
	s_waitcnt vmcnt(21)
	v_and_b32_e32 v105, 0xffff0000, v180
	v_lshlrev_b32_e32 v104, 16, v180
	s_waitcnt vmcnt(20)
	v_and_b32_e32 v107, 0xffff0000, v182
	v_lshlrev_b32_e32 v106, 16, v182
	s_waitcnt vmcnt(19)
	v_and_b32_e32 v109, 0xffff0000, v184
	v_lshlrev_b32_e32 v108, 16, v184
	s_waitcnt vmcnt(18)
	v_and_b32_e32 v111, 0xffff0000, v186
	v_lshlrev_b32_e32 v110, 16, v186
	s_waitcnt vmcnt(17)
	v_and_b32_e32 v113, 0xffff0000, v188
	v_lshlrev_b32_e32 v112, 16, v188
	s_waitcnt vmcnt(16)
	v_and_b32_e32 v115, 0xffff0000, v166
	v_lshlrev_b32_e32 v114, 16, v166
	s_waitcnt vmcnt(15)
	v_cndmask_b32_e64 v177, v177, 0, s[10:11]
	v_and_b32_e32 v117, 0xffff0000, v177
	v_lshlrev_b32_e32 v116, 16, v177
	s_waitcnt vmcnt(14)
	v_and_b32_e32 v119, 0xffff0000, v179
	v_lshlrev_b32_e32 v118, 16, v179
	s_waitcnt vmcnt(13)
	v_and_b32_e32 v121, 0xffff0000, v181
	v_lshlrev_b32_e32 v120, 16, v181
	s_waitcnt vmcnt(12)
	v_and_b32_e32 v123, 0xffff0000, v183
	v_lshlrev_b32_e32 v122, 16, v183
	s_waitcnt vmcnt(11)
	v_and_b32_e32 v125, 0xffff0000, v185
	v_lshlrev_b32_e32 v124, 16, v185
	s_waitcnt vmcnt(10)
	v_and_b32_e32 v127, 0xffff0000, v187
	v_lshlrev_b32_e32 v126, 16, v187
	s_waitcnt vmcnt(9)
	v_and_b32_e32 v129, 0xffff0000, v189
	v_lshlrev_b32_e32 v128, 16, v189
	s_waitcnt vmcnt(8)
	v_and_b32_e32 v131, 0xffff0000, v167
	v_lshlrev_b32_e32 v130, 16, v167
	v_pk_add_f32 v[168:169], v[100:101], v[116:117]
	v_pk_add_f32 v[174:175], v[100:101], v[116:117] neg_lo:[0,1] neg_hi:[0,1]
	v_pk_add_f32 v[176:177], v[108:109], v[124:125]
	v_pk_add_f32 v[178:179], v[108:109], v[124:125] neg_lo:[0,1] neg_hi:[0,1]
	v_pk_add_f32 v[100:101], v[168:169], v[176:177]
	v_pk_add_f32 v[116:117], v[168:169], v[176:177] neg_lo:[0,1] neg_hi:[0,1]
	v_pk_add_f32 v[108:109], v[174:175], v[178:179] op_sel:[0,1] op_sel_hi:[1,0] neg_hi:[0,1]
	v_pk_add_f32 v[124:125], v[174:175], v[178:179] op_sel:[0,1] op_sel_hi:[1,0] neg_lo:[0,1]
	v_pk_add_f32 v[180:181], v[102:103], v[118:119]
	v_pk_add_f32 v[182:183], v[102:103], v[118:119] neg_lo:[0,1] neg_hi:[0,1]
	v_pk_add_f32 v[184:185], v[110:111], v[126:127]
	v_pk_add_f32 v[186:187], v[110:111], v[126:127] neg_lo:[0,1] neg_hi:[0,1]
	v_pk_add_f32 v[102:103], v[180:181], v[184:185]
	v_pk_add_f32 v[118:119], v[180:181], v[184:185] neg_lo:[0,1] neg_hi:[0,1]
	v_pk_add_f32 v[110:111], v[182:183], v[186:187] op_sel:[0,1] op_sel_hi:[1,0] neg_hi:[0,1]
	v_pk_add_f32 v[126:127], v[182:183], v[186:187] op_sel:[0,1] op_sel_hi:[1,0] neg_lo:[0,1]
	v_pk_add_f32 v[188:189], v[104:105], v[120:121]
	v_pk_add_f32 v[166:167], v[104:105], v[120:121] neg_lo:[0,1] neg_hi:[0,1]
	v_pk_add_f32 v[168:169], v[112:113], v[128:129]
	v_pk_add_f32 v[174:175], v[112:113], v[128:129] neg_lo:[0,1] neg_hi:[0,1]
	v_pk_add_f32 v[104:105], v[188:189], v[168:169]
	v_pk_add_f32 v[120:121], v[188:189], v[168:169] neg_lo:[0,1] neg_hi:[0,1]
	v_pk_add_f32 v[112:113], v[166:167], v[174:175] op_sel:[0,1] op_sel_hi:[1,0] neg_hi:[0,1]
	v_pk_add_f32 v[128:129], v[166:167], v[174:175] op_sel:[0,1] op_sel_hi:[1,0] neg_lo:[0,1]
	v_pk_add_f32 v[176:177], v[106:107], v[122:123]
	v_pk_add_f32 v[178:179], v[106:107], v[122:123] neg_lo:[0,1] neg_hi:[0,1]
	v_pk_add_f32 v[180:181], v[114:115], v[130:131]
	v_pk_add_f32 v[182:183], v[114:115], v[130:131] neg_lo:[0,1] neg_hi:[0,1]
	v_pk_add_f32 v[106:107], v[176:177], v[180:181]
	v_pk_add_f32 v[122:123], v[176:177], v[180:181] neg_lo:[0,1] neg_hi:[0,1]
	v_pk_add_f32 v[114:115], v[178:179], v[182:183] op_sel:[0,1] op_sel_hi:[1,0] neg_hi:[0,1]
; __device__ __forceinline__ f32x2 cmul(f32x2 a, f32x2 b) { return (f32x2){a.x * b.x - a.y * b.y, a.x * b.y + a.y * b.x}; }
; template <bool INV> __device__ __forceinline__ f32x2 cmul_tw(f32x2 a, f32x2 w) { return INV ? cmulc(a, w) : cmul(a, w); }
; template <bool INV> __device__ __forceinline__ void dft16(f32x2 (&x)[16]) {
;     ...
;     const f32x2 w1 = {C1, -S1}, w2 = {C2, -C2}, w3 = {S1, -C1}, w4 = {0.f, -1.f}, w6 = {-C2, -C2}, w9 = {-C1, S1};
;     x[4 * 1 + 1] = cmul_tw<INV>(x[5], w1); x[4 * 1 + 2] = cmul_tw<INV>(x[6], w2); x[4 * 1 + 3] = cmul_tw<INV>(x[7], w3);
;     x[4 * 2 + 1] = cmul_tw<INV>(x[9], w2); x[4 * 2 + 2] = cmul_tw<INV>(x[10], w4); x[4 * 2 + 3] = cmul_tw<INV>(x[11], w6);
;     x[4 * 3 + 1] = cmul_tw<INV>(x[13], w3); x[4 * 3 + 2] = cmul_tw<INV>(x[14], w6); x[4 * 3 + 3] = cmul_tw<INV>(x[15], w9);
; #pragma unroll
;     for (int c = 0; c < 4; ++c) dft4<INV>(x[4 * c], x[4 * c + 1], x[4 * c + 2], x[4 * c + 3]);
;     f32x2 y[16];
; #pragma unroll
;     for (int k = 0; k < 16; ++k) y[k] = x[4 * (k & 3) + (k >> 2)];
; #pragma unroll
;     for (int k = 0; k < 16; ++k) x[k] = y[k];
; template <bool LO> __device__ __forceinline__ void fft_fwd1(f32x2 (&x)[16], LAS f32x2* B, int n2, const f32x2 (&w)[16]) {
;     ...
;     if (LO) dft16_fwd_lo(x); else dft16<false>(x);
;     B[fpad(n2)] = x[0];
; #pragma unroll
;     for (int k = 1; k < 16; ++k) B[fpad(512 * k + n2)] = cmul(x[k], w[k]);
	v_pk_add_f32 v[130:131], v[178:179], v[182:183] op_sel:[0,1] op_sel_hi:[1,0] neg_lo:[0,1]
	v_pk_mul_f32 v[184:185], v[110:111], s[68:69] op_sel:[1,1] op_sel_hi:[0,1]
	v_pk_fma_f32 v[110:111], v[110:111], s[68:69], v[184:185] op_sel_hi:[1,0,1] neg_lo:[0,0,1]
	v_pk_mul_f32 v[186:187], v[112:113], s[84:85] op_sel:[1,1] op_sel_hi:[0,1]
	v_pk_fma_f32 v[112:113], v[112:113], s[84:85], v[186:187] op_sel_hi:[1,0,1] neg_lo:[0,0,1]
	v_pk_mul_f32 v[188:189], v[114:115], s[88:89] op_sel:[1,1] op_sel_hi:[0,1]
	v_pk_fma_f32 v[114:115], v[114:115], s[88:89], v[188:189] op_sel_hi:[1,0,1] neg_lo:[0,0,1]
	v_pk_mul_f32 v[166:167], v[118:119], s[84:85] op_sel:[1,1] op_sel_hi:[0,1]
	v_pk_fma_f32 v[118:119], v[118:119], s[84:85], v[166:167] op_sel_hi:[1,0,1] neg_lo:[0,0,1]
	v_pk_mul_f32 v[168:169], v[122:123], s[90:91] op_sel:[1,1] op_sel_hi:[0,1]
	v_pk_fma_f32 v[122:123], v[122:123], s[90:91], v[168:169] op_sel_hi:[1,0,1] neg_lo:[0,0,1]
	v_pk_mul_f32 v[174:175], v[126:127], s[88:89] op_sel:[1,1] op_sel_hi:[0,1]
	v_pk_fma_f32 v[126:127], v[126:127], s[88:89], v[174:175] op_sel_hi:[1,0,1] neg_lo:[0,0,1]
	v_pk_mul_f32 v[176:177], v[128:129], s[90:91] op_sel:[1,1] op_sel_hi:[0,1]
	v_pk_fma_f32 v[128:129], v[128:129], s[90:91], v[176:177] op_sel_hi:[1,0,1] neg_lo:[0,0,1]
	v_pk_mul_f32 v[178:179], v[130:131], s[98:99] op_sel:[1,1] op_sel_hi:[0,1]
	v_pk_fma_f32 v[130:131], v[130:131], s[98:99], v[178:179] op_sel_hi:[1,0,1] neg_lo:[0,0,1]
	v_pk_add_f32 v[180:181], v[100:101], v[104:105]
	v_pk_add_f32 v[182:183], v[100:101], v[104:105] neg_lo:[0,1] neg_hi:[0,1]
	v_pk_add_f32 v[184:185], v[102:103], v[106:107]
	v_pk_add_f32 v[186:187], v[102:103], v[106:107] neg_lo:[0,1] neg_hi:[0,1]
	v_pk_add_f32 v[100:101], v[180:181], v[184:185]
	v_pk_add_f32 v[104:105], v[180:181], v[184:185] neg_lo:[0,1] neg_hi:[0,1]
	v_pk_add_f32 v[102:103], v[182:183], v[186:187] op_sel:[0,1] op_sel_hi:[1,0] neg_hi:[0,1]
	v_pk_add_f32 v[106:107], v[182:183], v[186:187] op_sel:[0,1] op_sel_hi:[1,0] neg_lo:[0,1]
	v_pk_add_f32 v[188:189], v[108:109], v[112:113]
	v_pk_add_f32 v[166:167], v[108:109], v[112:113] neg_lo:[0,1] neg_hi:[0,1]
	v_pk_add_f32 v[168:169], v[110:111], v[114:115]
	v_pk_add_f32 v[174:175], v[110:111], v[114:115] neg_lo:[0,1] neg_hi:[0,1]
	v_pk_add_f32 v[108:109], v[188:189], v[168:169]
	v_pk_add_f32 v[112:113], v[188:189], v[168:169] neg_lo:[0,1] neg_hi:[0,1]
	v_pk_add_f32 v[110:111], v[166:167], v[174:175] op_sel:[0,1] op_sel_hi:[1,0] neg_hi:[0,1]
	v_pk_add_f32 v[114:115], v[166:167], v[174:175] op_sel:[0,1] op_sel_hi:[1,0] neg_lo:[0,1]
	v_pk_add_f32 v[176:177], v[116:117], v[120:121] op_sel:[0,1] op_sel_hi:[1,0] neg_hi:[0,1]
	v_pk_add_f32 v[178:179], v[116:117], v[120:121] op_sel:[0,1] op_sel_hi:[1,0] neg_lo:[0,1]
	v_pk_add_f32 v[180:181], v[118:119], v[122:123]
	v_pk_add_f32 v[182:183], v[118:119], v[122:123] neg_lo:[0,1] neg_hi:[0,1]
	v_pk_add_f32 v[116:117], v[176:177], v[180:181]
	v_pk_add_f32 v[120:121], v[176:177], v[180:181] neg_lo:[0,1] neg_hi:[0,1]
	v_pk_add_f32 v[118:119], v[178:179], v[182:183] op_sel:[0,1] op_sel_hi:[1,0] neg_hi:[0,1]
	v_pk_add_f32 v[122:123], v[178:179], v[182:183] op_sel:[0,1] op_sel_hi:[1,0] neg_lo:[0,1]
	v_pk_add_f32 v[184:185], v[124:125], v[128:129]
	v_pk_add_f32 v[186:187], v[124:125], v[128:129] neg_lo:[0,1] neg_hi:[0,1]
	v_pk_add_f32 v[188:189], v[126:127], v[130:131]
	v_pk_add_f32 v[166:167], v[126:127], v[130:131] neg_lo:[0,1] neg_hi:[0,1]
	v_pk_add_f32 v[124:125], v[184:185], v[188:189]
	v_pk_add_f32 v[128:129], v[184:185], v[188:189] neg_lo:[0,1] neg_hi:[0,1]
	v_pk_add_f32 v[126:127], v[186:187], v[166:167] op_sel:[0,1] op_sel_hi:[1,0] neg_hi:[0,1]
	v_pk_add_f32 v[130:131], v[186:187], v[166:167] op_sel:[0,1] op_sel_hi:[1,0] neg_lo:[0,1]
	v_add_u32_e32 v65, 0x10800, v3
	ds_write_b64 v65, v[100:101]
	v_pk_mul_f32 v[174:175], v[108:109], v[6:7] op_sel:[1,1] op_sel_hi:[0,1]
	v_pk_fma_f32 v[168:169], v[108:109], v[6:7], v[174:175] op_sel_hi:[1,0,1] neg_lo:[0,0,1]
	ds_write_b64 v65, v[168:169] offset:4224
	v_pk_mul_f32 v[178:179], v[116:117], v[8:9] op_sel:[1,1] op_sel_hi:[0,1]
	v_pk_fma_f32 v[176:177], v[116:117], v[8:9], v[178:179] op_sel_hi:[1,0,1] neg_lo:[0,0,1]
	ds_write_b64 v65, v[176:177] offset:8448
	v_pk_mul_f32 v[182:183], v[124:125], v[10:11] op_sel:[1,1] op_sel_hi:[0,1]
	v_pk_fma_f32 v[180:181], v[124:125], v[10:11], v[182:183] op_sel_hi:[1,0,1] neg_lo:[0,0,1]
	ds_write_b64 v65, v[180:181] offset:12672
	v_pk_mul_f32 v[186:187], v[102:103], v[12:13] op_sel:[1,1] op_sel_hi:[0,1]
	v_pk_fma_f32 v[184:185], v[102:103], v[12:13], v[186:187] op_sel_hi:[1,0,1] neg_lo:[0,0,1]
	ds_write_b64 v65, v[184:185] offset:16896
	v_pk_mul_f32 v[166:167], v[110:111], v[14:15] op_sel:[1,1] op_sel_hi:[0,1]
	v_pk_fma_f32 v[188:189], v[110:111], v[14:15], v[166:167] op_sel_hi:[1,0,1] neg_lo:[0,0,1]
	ds_write_b64 v65, v[188:189] offset:21120
	v_pk_mul_f32 v[168:169], v[118:119], v[16:17] op_sel:[1,1] op_sel_hi:[0,1]
	v_pk_fma_f32 v[174:175], v[118:119], v[16:17], v[168:169] op_sel_hi:[1,0,1] neg_lo:[0,0,1]
	ds_write_b64 v65, v[174:175] offset:25344
	v_pk_mul_f32 v[176:177], v[126:127], v[18:19] op_sel:[1,1] op_sel_hi:[0,1]
	v_pk_fma_f32 v[178:179], v[126:127], v[18:19], v[176:177] op_sel_hi:[1,0,1] neg_lo:[0,0,1]
	ds_write_b64 v65, v[178:179] offset:29568
	v_pk_mul_f32 v[180:181], v[104:105], v[20:21] op_sel:[1,1] op_sel_hi:[0,1]
	v_pk_fma_f32 v[182:183], v[104:105], v[20:21], v[180:181] op_sel_hi:[1,0,1] neg_lo:[0,0,1]
	ds_write_b64 v65, v[182:183] offset:33792
	v_pk_mul_f32 v[184:185], v[112:113], v[22:23] op_sel:[1,1] op_sel_hi:[0,1]
	v_pk_fma_f32 v[186:187], v[112:113], v[22:23], v[184:185] op_sel_hi:[1,0,1] neg_lo:[0,0,1]
	ds_write_b64 v65, v[186:187] offset:38016
	v_pk_mul_f32 v[188:189], v[120:121], v[24:25] op_sel:[1,1] op_sel_hi:[0,1]
	v_pk_fma_f32 v[166:167], v[120:121], v[24:25], v[188:189] op_sel_hi:[1,0,1] neg_lo:[0,0,1]
	ds_write_b64 v65, v[166:167] offset:42240
	v_pk_mul_f32 v[174:175], v[128:129], v[26:27] op_sel:[1,1] op_sel_hi:[0,1]
	v_pk_fma_f32 v[168:169], v[128:129], v[26:27], v[174:175] op_sel_hi:[1,0,1] neg_lo:[0,0,1]
	ds_write_b64 v65, v[168:169] offset:46464
	v_pk_mul_f32 v[178:179], v[106:107], v[28:29] op_sel:[1,1] op_sel_hi:[0,1]
	v_pk_fma_f32 v[176:177], v[106:107], v[28:29], v[178:179] op_sel_hi:[1,0,1] neg_lo:[0,0,1]
	ds_write_b64 v65, v[176:177] offset:50688
	v_pk_mul_f32 v[182:183], v[114:115], v[30:31] op_sel:[1,1] op_sel_hi:[0,1]
	v_pk_fma_f32 v[180:181], v[114:115], v[30:31], v[182:183] op_sel_hi:[1,0,1] neg_lo:[0,0,1]
	ds_write_b64 v65, v[180:181] offset:54912
	v_pk_mul_f32 v[186:187], v[122:123], v[32:33] op_sel:[1,1] op_sel_hi:[0,1]
	v_pk_fma_f32 v[184:185], v[122:123], v[32:33], v[186:187] op_sel_hi:[1,0,1] neg_lo:[0,0,1]
	ds_write_b64 v65, v[184:185] offset:59136
	v_pk_mul_f32 v[166:167], v[130:131], v[34:35] op_sel:[1,1] op_sel_hi:[0,1]
	v_pk_fma_f32 v[188:189], v[130:131], v[34:35], v[166:167] op_sel_hi:[1,0,1] neg_lo:[0,0,1]
	ds_write_b64 v65, v[188:189] offset:63360
	s_waitcnt vmcnt(7)
; #define LAS __attribute__((address_space(3)))
; #define WG_SYNC() do { asm volatile("s_waitcnt lgkmcnt(0)" ::: "memory"); __builtin_amdgcn_s_barrier(); asm volatile("" ::: "memory"); } while (0)
; __device__ __forceinline__ void hy_stage(LAS float* plane, const bf16_t* PHY, int cg, int jc, int tid) {
;     ...
;     for (int k = 0; k < 8; ++k) { const int i = tid + 512 * k; const u32x4 v = src[i];
;         const unsigned w0 = (jc & 2) ? v.y : v.x, w1 = (jc & 2) ? v.w : v.z;
;         f32x2 o; o.x = (jc & 1) ? bf_hi(w0) : bf_lo(w0); o.y = (jc & 1) ? bf_hi(w1) : bf_lo(w1);
;         *(LAS f32x2*)(plane + 2 * i) = o; }
; __device__ __forceinline__ void hy_sconv(const LAS float* plane, float w0, float w1, float w2, float cb, int n2, float (&u)[8][2]) {
;     asm volatile("" : "+v"(n2));
; #pragma unroll
;     for (int r = 0; r < 8; ++r)
; #pragma unroll
;         for (int b = 0; b < 2; ++b) { const int t = n2 + 512 * r, row = b * SEQ + t;
;             float a = cb + w1 * plane[row];
;             if (t > 0) a += w0 * plane[row - 1];
;             if (t < SEQ - 1) a += w2 * plane[row + 1];
;             u[r][b] = a; }
; }
; __device__ __forceinline__ void hyena_fft(LAS unsigned char* lds, int layer, int G, const int wave_s) {
;     ...
;             hy_stage(pl0, PHY, 2 * (HY / 4) + unit, jc, tid); __builtin_amdgcn_sched_barrier(0); hy_stage(pl1, PHY, unit, jc, tid); __builtin_amdgcn_sched_barrier(0);
;             WG_SYNC();
;             float uz[8][2], ux[8][2];
;             hy_sconv(pl0, cw[2 * HY + c], cw[3 * HY + 2 * HY + c], cw[6 * HY + 2 * HY + c], cb[2 * HY + c], n2, uz);
	v_perm_b32 v174, 0, v58, s15
	v_perm_b32 v175, 0, v60, s15
	ds_write_b64 v206, v[174:175]
	s_waitcnt vmcnt(6)
	v_perm_b32 v168, 0, v62, s15
	v_perm_b32 v169, 0, v64, s15
	ds_write_b64 v206, v[168:169] offset:4096
	s_waitcnt vmcnt(5)
	v_perm_b32 v178, 0, v66, s15
	v_perm_b32 v179, 0, v68, s15
	ds_write_b64 v206, v[178:179] offset:8192
	s_waitcnt vmcnt(4)
	v_perm_b32 v176, 0, v70, s15
	v_perm_b32 v177, 0, v72, s15
	ds_write_b64 v206, v[176:177] offset:12288
	s_waitcnt vmcnt(3)
	v_perm_b32 v182, 0, v74, s15
	v_perm_b32 v183, 0, v76, s15
	ds_write_b64 v206, v[182:183] offset:16384
	s_waitcnt vmcnt(2)
	v_perm_b32 v180, 0, v78, s15
	v_perm_b32 v181, 0, v80, s15
	ds_write_b64 v206, v[180:181] offset:20480
	s_waitcnt vmcnt(1)
	v_perm_b32 v186, 0, v82, s15
	v_perm_b32 v187, 0, v84, s15
	ds_write_b64 v206, v[186:187] offset:24576
	s_waitcnt vmcnt(0)
	v_perm_b32 v184, 0, v86, s15
	v_perm_b32 v185, 0, v88, s15
	ds_write_b64 v206, v[184:185] offset:28672
	s_add_u32 s56, s38, s73
	s_addc_u32 s57, s39, 0
	global_load_dwordx3 v[58:60], v216, s[56:57]
	global_load_dwordx3 v[62:64], v218, s[56:57]
	global_load_dwordx3 v[66:68], v220, s[56:57]
	global_load_dwordx3 v[70:72], v222, s[56:57]
	global_load_dwordx3 v[74:76], v240, s[56:57]
	global_load_dwordx3 v[78:80], v242, s[56:57]
	global_load_dwordx3 v[82:84], v244, s[56:57]
	global_load_dwordx3 v[86:88], v61, s[56:57]
	s_load_dwordx2 s[60:61], s[94:95], 0x48
	s_load_dwordx2 s[62:63], s[94:95], 0x50
	s_load_dwordx2 s[50:51], s[94:95], 0x88
	s_lshl_b32 s43, s80, 2
	s_mul_i32 s53, s76, 0x9000
	s_add_u32 s53, s53, s43
	s_mul_i32 s55, s76, 0x3000
	s_add_u32 s55, s55, s43
	s_waitcnt lgkmcnt(0)
	s_add_u32 s60, s60, s53
	s_addc_u32 s61, s61, 0
	s_add_u32 s62, s62, s55
	s_addc_u32 s63, s63, 0
	s_mul_i32 s53, s76, 0x2000
	s_add_u32 s53, s53, s43
	s_add_u32 s50, s50, s53
	s_addc_u32 s51, s51, 0
	s_load_dword s17, s[60:61], 0x2000
	s_load_dword s23, s[60:61], 0x5000
	s_load_dword s25, s[60:61], 0x8000
	s_load_dword s26, s[62:63], 0x2000
	s_waitcnt lgkmcnt(0)
	s_barrier
	v_mov_b32_e32 v166, s17
	v_mov_b32_e32 v167, s23
	v_mov_b32_e32 v188, s25
	v_mov_b32_e32 v189, s26
	ds_read_b32 v174, v208
	ds_read_b32 v168, v210
	ds_read_b32 v178, v208 offset:4
	ds_read_b32 v175, v208 offset:16384
	ds_read_b32 v169, v210 offset:16384
	ds_read_b32 v179, v208 offset:16388
	ds_read_b32 v176, v208 offset:2048
	ds_read_b32 v182, v208 offset:2044
	ds_read_b32 v180, v208 offset:2052
	ds_read_b32 v177, v208 offset:18432
	ds_read_b32 v183, v208 offset:18428
	ds_read_b32 v181, v208 offset:18436
	s_waitcnt lgkmcnt(10)
	v_cndmask_b32_e64 v168, v168, 0, s[10:11]
	s_waitcnt lgkmcnt(7)
	v_cndmask_b32_e64 v169, v169, 0, s[10:11]
	v_pk_fma_f32 v[132:133], v[166:167], v[174:175], v[188:189] op_sel:[1,0,1]
	v_pk_fma_f32 v[132:133], v[166:167], v[168:169], v[132:133] op_sel_hi:[0,1,1]
	s_waitcnt lgkmcnt(6)
	v_pk_fma_f32 v[132:133], v[188:189], v[178:179], v[132:133] op_sel_hi:[0,1,1]
	s_waitcnt lgkmcnt(2)
	v_pk_fma_f32 v[134:135], v[166:167], v[176:177], v[188:189] op_sel:[1,0,1]
	s_waitcnt lgkmcnt(1)
	v_pk_fma_f32 v[134:135], v[166:167], v[182:183], v[134:135] op_sel_hi:[0,1,1]
	s_waitcnt lgkmcnt(0)
	v_pk_fma_f32 v[134:135], v[188:189], v[180:181], v[134:135] op_sel_hi:[0,1,1]
	ds_read_b32 v186, v208 offset:4096
	ds_read_b32 v184, v208 offset:4092
	ds_read_b32 v174, v208 offset:4100
	ds_read_b32 v187, v208 offset:20480
	ds_read_b32 v185, v208 offset:20476
	ds_read_b32 v175, v208 offset:20484
	ds_read_b32 v168, v208 offset:6144
	ds_read_b32 v178, v208 offset:6140
	ds_read_b32 v176, v208 offset:6148
	ds_read_b32 v169, v208 offset:22528
	ds_read_b32 v179, v208 offset:22524
	ds_read_b32 v177, v208 offset:22532
	s_waitcnt lgkmcnt(8)
	v_pk_fma_f32 v[136:137], v[166:167], v[186:187], v[188:189] op_sel:[1,0,1]
	s_waitcnt lgkmcnt(7)
	v_pk_fma_f32 v[136:137], v[166:167], v[184:185], v[136:137] op_sel_hi:[0,1,1]
	s_waitcnt lgkmcnt(6)
	v_pk_fma_f32 v[136:137], v[188:189], v[174:175], v[136:137] op_sel_hi:[0,1,1]
	s_waitcnt lgkmcnt(2)
	v_pk_fma_f32 v[138:139], v[166:167], v[168:169], v[188:189] op_sel:[1,0,1]
	s_waitcnt lgkmcnt(1)
	v_pk_fma_f32 v[138:139], v[166:167], v[178:179], v[138:139] op_sel_hi:[0,1,1]
	s_waitcnt lgkmcnt(0)
	v_pk_fma_f32 v[138:139], v[188:189], v[176:177], v[138:139] op_sel_hi:[0,1,1]
	ds_read_b32 v182, v208 offset:8192
	ds_read_b32 v180, v208 offset:8188
	ds_read_b32 v186, v208 offset:8196
	ds_read_b32 v183, v208 offset:24576
	ds_read_b32 v181, v208 offset:24572
	ds_read_b32 v187, v208 offset:24580
	ds_read_b32 v184, v208 offset:10240
	ds_read_b32 v174, v208 offset:10236
	ds_read_b32 v168, v208 offset:10244
	ds_read_b32 v185, v208 offset:26624
	ds_read_b32 v175, v208 offset:26620
	ds_read_b32 v169, v208 offset:26628
	s_waitcnt lgkmcnt(8)
	v_pk_fma_f32 v[140:141], v[166:167], v[182:183], v[188:189] op_sel:[1,0,1]
	s_waitcnt lgkmcnt(7)
	v_pk_fma_f32 v[140:141], v[166:167], v[180:181], v[140:141] op_sel_hi:[0,1,1]
	s_waitcnt lgkmcnt(6)
	v_pk_fma_f32 v[140:141], v[188:189], v[186:187], v[140:141] op_sel_hi:[0,1,1]
	s_waitcnt lgkmcnt(2)
	v_pk_fma_f32 v[142:143], v[166:167], v[184:185], v[188:189] op_sel:[1,0,1]
	s_waitcnt lgkmcnt(1)
	v_pk_fma_f32 v[142:143], v[166:167], v[174:175], v[142:143] op_sel_hi:[0,1,1]
	s_waitcnt lgkmcnt(0)
	v_pk_fma_f32 v[142:143], v[188:189], v[168:169], v[142:143] op_sel_hi:[0,1,1]
	ds_read_b32 v178, v208 offset:12288
	ds_read_b32 v176, v208 offset:12284
	ds_read_b32 v182, v208 offset:12292
	ds_read_b32 v179, v208 offset:28672
	ds_read_b32 v177, v208 offset:28668
	ds_read_b32 v183, v208 offset:28676
	ds_read_b32 v180, v208 offset:14336
	ds_read_b32 v186, v208 offset:14332
	ds_read_b32 v184, v208 offset:14340
	ds_read_b32 v181, v208 offset:30720
	ds_read_b32 v187, v208 offset:30716
	ds_read_b32 v185, v208 offset:30724
	s_waitcnt lgkmcnt(8)
; #define LAS __attribute__((address_space(3)))
; #define WG_SYNC() do { asm volatile("s_waitcnt lgkmcnt(0)" ::: "memory"); __builtin_amdgcn_s_barrier(); asm volatile("" ::: "memory"); } while (0)
; #define WAVE_FENCE() do { asm volatile("s_waitcnt lgkmcnt(0)" ::: "memory"); __builtin_amdgcn_sched_barrier(0); } while (0)
; __device__ __forceinline__ void fft_fwd2(LAS f32x2* B, const LAS f32x2* TW2, int tid) {
;     asm volatile("" : "+v"(tid));
;     const int b = tid >> 5, n2 = tid & 31, base = 512 * b + n2; f32x2 x[16];
; #pragma unroll
;     for (int r = 0; r < 16; ++r) x[r] = B[fpad(base + 32 * r)];
;     dft16<false>(x);
; __device__ __forceinline__ void hy_sconv(const LAS float* plane, float w0, float w1, float w2, float cb, int n2, float (&u)[8][2]) {
;     asm volatile("" : "+v"(n2));
; #pragma unroll
;     for (int r = 0; r < 8; ++r)
; #pragma unroll
;         for (int b = 0; b < 2; ++b) { const int t = n2 + 512 * r, row = b * SEQ + t;
;             float a = cb + w1 * plane[row];
;             if (t > 0) a += w0 * plane[row - 1];
;             if (t < SEQ - 1) a += w2 * plane[row + 1];
;             u[r][b] = a; }
; }
; __device__ __forceinline__ void hyena_fft(LAS unsigned char* lds, int layer, int G, const int wave_s) {
;     ...
;             hy_stage(pl0, PHY, 2 * (HY / 4) + unit, jc, tid); __builtin_amdgcn_sched_barrier(0); hy_stage(pl1, PHY, unit, jc, tid); __builtin_amdgcn_sched_barrier(0);
;             WG_SYNC();
;             float uz[8][2], ux[8][2];
;             hy_sconv(pl0, cw[2 * HY + c], cw[3 * HY + 2 * HY + c], cw[6 * HY + 2 * HY + c], cb[2 * HY + c], n2, uz);
;             __builtin_amdgcn_sched_barrier(0); hy_sconv(pl1, cw[c], cw[3 * HY + c], cw[6 * HY + c], cb[c], n2, ux); __builtin_amdgcn_sched_barrier(0);
;             fft_fwd2(Fb, TW2, tid); WAVE_FENCE(); fft_pair32<2>(Fb, Fb, wave, lane); __builtin_amdgcn_sched_barrier(0);
	v_pk_fma_f32 v[144:145], v[166:167], v[178:179], v[188:189] op_sel:[1,0,1]
	s_waitcnt lgkmcnt(7)
	v_pk_fma_f32 v[144:145], v[166:167], v[176:177], v[144:145] op_sel_hi:[0,1,1]
	s_waitcnt lgkmcnt(6)
	v_pk_fma_f32 v[144:145], v[188:189], v[182:183], v[144:145] op_sel_hi:[0,1,1]
	s_waitcnt lgkmcnt(3)
	v_cndmask_b32_e64 v184, v184, 0, s[28:29]
	s_waitcnt lgkmcnt(0)
	v_cndmask_b32_e64 v185, v185, 0, s[28:29]
	v_pk_fma_f32 v[146:147], v[166:167], v[180:181], v[188:189] op_sel:[1,0,1]
	v_pk_fma_f32 v[146:147], v[166:167], v[186:187], v[146:147] op_sel_hi:[0,1,1]
	v_pk_fma_f32 v[146:147], v[188:189], v[184:185], v[146:147] op_sel_hi:[0,1,1]
	s_load_dword s17, s[60:61], 0x0
	s_load_dword s23, s[60:61], 0x3000
	s_load_dword s25, s[60:61], 0x6000
	s_load_dword s26, s[62:63], 0x0
	s_waitcnt vmcnt(7)
	v_perm_b32 v174, 0, v58, s15
	v_perm_b32 v175, 0, v60, s15
	ds_write_b64 v206, v[174:175] offset:32768
	s_waitcnt vmcnt(6)
	v_perm_b32 v168, 0, v62, s15
	v_perm_b32 v169, 0, v64, s15
	ds_write_b64 v206, v[168:169] offset:36864
	s_waitcnt vmcnt(5)
	v_perm_b32 v178, 0, v66, s15
	v_perm_b32 v179, 0, v68, s15
	ds_write_b64 v206, v[178:179] offset:40960
	s_waitcnt vmcnt(4)
	v_perm_b32 v176, 0, v70, s15
	v_perm_b32 v177, 0, v72, s15
	ds_write_b64 v206, v[176:177] offset:45056
	s_waitcnt vmcnt(3)
	v_perm_b32 v182, 0, v74, s15
	v_perm_b32 v183, 0, v76, s15
	ds_write_b64 v206, v[182:183] offset:49152
	s_waitcnt vmcnt(2)
	v_perm_b32 v180, 0, v78, s15
	v_perm_b32 v181, 0, v80, s15
	ds_write_b64 v206, v[180:181] offset:53248
	s_waitcnt vmcnt(1)
	v_perm_b32 v186, 0, v82, s15
	v_perm_b32 v187, 0, v84, s15
	ds_write_b64 v206, v[186:187] offset:57344
	s_waitcnt vmcnt(0)
	v_perm_b32 v184, 0, v86, s15
	v_perm_b32 v185, 0, v88, s15
	ds_write_b64 v206, v[184:185] offset:61440
	s_add_u32 s56, s38, s73
	s_addc_u32 s57, s39, 0
	s_add_u32 s56, s56, 0x1100000
	s_addc_u32 s57, s57, 0
	global_load_dwordx3 v[58:60], v216, s[56:57]
	global_load_dwordx3 v[62:64], v218, s[56:57]
	global_load_dwordx3 v[66:68], v220, s[56:57]
	global_load_dwordx3 v[70:72], v222, s[56:57]
	global_load_dwordx3 v[74:76], v240, s[56:57]
	global_load_dwordx3 v[78:80], v242, s[56:57]
	global_load_dwordx3 v[82:84], v244, s[56:57]
	global_load_dwordx3 v[86:88], v61, s[56:57]
	v_add_u32_e32 v65, 0x10800, v5
	ds_read_b64 v[100:101], v65
	ds_read_b64 v[102:103], v65 offset:1056
	ds_read_b64 v[104:105], v65 offset:2112
	ds_read_b64 v[106:107], v65 offset:3168
	ds_read_b64 v[108:109], v65 offset:264
	ds_read_b64 v[110:111], v65 offset:1320
	ds_read_b64 v[112:113], v65 offset:2376
	ds_read_b64 v[114:115], v65 offset:3432
	ds_read_b64 v[116:117], v65 offset:528
	ds_read_b64 v[118:119], v65 offset:1584
	ds_read_b64 v[120:121], v65 offset:2640
	ds_read_b64 v[122:123], v65 offset:3696
	s_waitcnt lgkmcnt(8)
	ds_read_b64 v[124:125], v65 offset:792
	ds_read_b64 v[126:127], v65 offset:1848
	ds_read_b64 v[128:129], v65 offset:2904
	ds_read_b64 v[130:131], v65 offset:3960
	v_pk_add_f32 v[166:167], v[100:101], v[104:105]
	v_pk_add_f32 v[188:189], v[100:101], v[104:105] neg_lo:[0,1] neg_hi:[0,1]
	v_pk_add_f32 v[174:175], v[102:103], v[106:107]
	v_pk_add_f32 v[168:169], v[102:103], v[106:107] neg_lo:[0,1] neg_hi:[0,1]
	v_pk_add_f32 v[100:101], v[166:167], v[174:175]
	v_pk_add_f32 v[104:105], v[166:167], v[174:175] neg_lo:[0,1] neg_hi:[0,1]
	v_pk_add_f32 v[102:103], v[188:189], v[168:169] op_sel:[0,1] op_sel_hi:[1,0] neg_hi:[0,1]
	v_pk_add_f32 v[106:107], v[188:189], v[168:169] op_sel:[0,1] op_sel_hi:[1,0] neg_lo:[0,1]
	s_waitcnt lgkmcnt(9)
	v_pk_add_f32 v[178:179], v[108:109], v[112:113]
	v_pk_add_f32 v[176:177], v[108:109], v[112:113] neg_lo:[0,1] neg_hi:[0,1]
	s_waitcnt lgkmcnt(8)
	v_pk_add_f32 v[182:183], v[110:111], v[114:115]
	v_pk_add_f32 v[180:181], v[110:111], v[114:115] neg_lo:[0,1] neg_hi:[0,1]
	v_pk_add_f32 v[108:109], v[178:179], v[182:183]
	v_pk_add_f32 v[112:113], v[178:179], v[182:183] neg_lo:[0,1] neg_hi:[0,1]
	v_pk_add_f32 v[110:111], v[176:177], v[180:181] op_sel:[0,1] op_sel_hi:[1,0] neg_hi:[0,1]
	v_pk_add_f32 v[114:115], v[176:177], v[180:181] op_sel:[0,1] op_sel_hi:[1,0] neg_lo:[0,1]
	s_waitcnt lgkmcnt(5)
	v_pk_add_f32 v[186:187], v[116:117], v[120:121]
	v_pk_add_f32 v[184:185], v[116:117], v[120:121] neg_lo:[0,1] neg_hi:[0,1]
	s_waitcnt lgkmcnt(4)
	v_pk_add_f32 v[166:167], v[118:119], v[122:123]
	v_pk_add_f32 v[188:189], v[118:119], v[122:123] neg_lo:[0,1] neg_hi:[0,1]
	v_pk_add_f32 v[116:117], v[186:187], v[166:167]
	v_pk_add_f32 v[120:121], v[186:187], v[166:167] neg_lo:[0,1] neg_hi:[0,1]
	v_pk_add_f32 v[118:119], v[184:185], v[188:189] op_sel:[0,1] op_sel_hi:[1,0] neg_hi:[0,1]
	v_pk_add_f32 v[122:123], v[184:185], v[188:189] op_sel:[0,1] op_sel_hi:[1,0] neg_lo:[0,1]
	s_waitcnt lgkmcnt(1)
	v_pk_add_f32 v[174:175], v[124:125], v[128:129]
	v_pk_add_f32 v[168:169], v[124:125], v[128:129] neg_lo:[0,1] neg_hi:[0,1]
	s_waitcnt lgkmcnt(0)
; __device__ __forceinline__ f32x2 cmul(f32x2 a, f32x2 b) { return (f32x2){a.x * b.x - a.y * b.y, a.x * b.y + a.y * b.x}; }
; template <bool INV> __device__ __forceinline__ f32x2 cmul_tw(f32x2 a, f32x2 w) { return INV ? cmulc(a, w) : cmul(a, w); }
; template <bool INV> __device__ __forceinline__ void dft16(f32x2 (&x)[16]) {
;     ...
;     for (int b = 0; b < 4; ++b) dft4<INV>(x[b], x[4 + b], x[8 + b], x[12 + b]);
;     const f32x2 w1 = {C1, -S1}, w2 = {C2, -C2}, w3 = {S1, -C1}, w4 = {0.f, -1.f}, w6 = {-C2, -C2}, w9 = {-C1, S1};
;     x[4 * 1 + 1] = cmul_tw<INV>(x[5], w1); x[4 * 1 + 2] = cmul_tw<INV>(x[6], w2); x[4 * 1 + 3] = cmul_tw<INV>(x[7], w3);
;     x[4 * 2 + 1] = cmul_tw<INV>(x[9], w2); x[4 * 2 + 2] = cmul_tw<INV>(x[10], w4); x[4 * 2 + 3] = cmul_tw<INV>(x[11], w6);
;     x[4 * 3 + 1] = cmul_tw<INV>(x[13], w3); x[4 * 3 + 2] = cmul_tw<INV>(x[14], w6); x[4 * 3 + 3] = cmul_tw<INV>(x[15], w9);
; #pragma unroll
;     for (int c = 0; c < 4; ++c) dft4<INV>(x[4 * c], x[4 * c + 1], x[4 * c + 2], x[4 * c + 3]);
; __device__ __forceinline__ void fft_fwd2(LAS f32x2* B, const LAS f32x2* TW2, int tid) {
;     ...
;     B[fpad(base)] = x[0];
; #pragma unroll
;     for (int k = 1; k < 16; ++k) B[fpad(base + 32 * k)] = cmul(x[k], TW2[k * 32 + n2]);
	v_pk_add_f32 v[178:179], v[126:127], v[130:131]
	v_pk_add_f32 v[176:177], v[126:127], v[130:131] neg_lo:[0,1] neg_hi:[0,1]
	v_pk_add_f32 v[124:125], v[174:175], v[178:179]
	v_pk_add_f32 v[128:129], v[174:175], v[178:179] neg_lo:[0,1] neg_hi:[0,1]
	v_pk_add_f32 v[126:127], v[168:169], v[176:177] op_sel:[0,1] op_sel_hi:[1,0] neg_hi:[0,1]
	v_pk_add_f32 v[130:131], v[168:169], v[176:177] op_sel:[0,1] op_sel_hi:[1,0] neg_lo:[0,1]
	v_pk_mul_f32 v[182:183], v[110:111], s[68:69] op_sel:[1,1] op_sel_hi:[0,1]
	v_pk_fma_f32 v[110:111], v[110:111], s[68:69], v[182:183] op_sel_hi:[1,0,1] neg_lo:[0,0,1]
	v_pk_mul_f32 v[180:181], v[118:119], s[84:85] op_sel:[1,1] op_sel_hi:[0,1]
	v_pk_fma_f32 v[118:119], v[118:119], s[84:85], v[180:181] op_sel_hi:[1,0,1] neg_lo:[0,0,1]
	v_pk_mul_f32 v[186:187], v[126:127], s[88:89] op_sel:[1,1] op_sel_hi:[0,1]
	v_pk_fma_f32 v[126:127], v[126:127], s[88:89], v[186:187] op_sel_hi:[1,0,1] neg_lo:[0,0,1]
	v_pk_mul_f32 v[184:185], v[112:113], s[84:85] op_sel:[1,1] op_sel_hi:[0,1]
	v_pk_fma_f32 v[112:113], v[112:113], s[84:85], v[184:185] op_sel_hi:[1,0,1] neg_lo:[0,0,1]
	v_pk_mul_f32 v[166:167], v[128:129], s[90:91] op_sel:[1,1] op_sel_hi:[0,1]
	v_pk_fma_f32 v[128:129], v[128:129], s[90:91], v[166:167] op_sel_hi:[1,0,1] neg_lo:[0,0,1]
	v_pk_mul_f32 v[188:189], v[114:115], s[88:89] op_sel:[1,1] op_sel_hi:[0,1]
	v_pk_fma_f32 v[114:115], v[114:115], s[88:89], v[188:189] op_sel_hi:[1,0,1] neg_lo:[0,0,1]
	v_pk_mul_f32 v[174:175], v[122:123], s[90:91] op_sel:[1,1] op_sel_hi:[0,1]
	v_pk_fma_f32 v[122:123], v[122:123], s[90:91], v[174:175] op_sel_hi:[1,0,1] neg_lo:[0,0,1]
	v_pk_mul_f32 v[168:169], v[130:131], s[98:99] op_sel:[1,1] op_sel_hi:[0,1]
	v_pk_fma_f32 v[130:131], v[130:131], s[98:99], v[168:169] op_sel_hi:[1,0,1] neg_lo:[0,0,1]
	v_pk_add_f32 v[178:179], v[100:101], v[116:117]
	v_pk_add_f32 v[176:177], v[100:101], v[116:117] neg_lo:[0,1] neg_hi:[0,1]
	v_pk_add_f32 v[182:183], v[108:109], v[124:125]
	v_pk_add_f32 v[180:181], v[108:109], v[124:125] neg_lo:[0,1] neg_hi:[0,1]
	v_pk_add_f32 v[100:101], v[178:179], v[182:183]
	v_pk_add_f32 v[116:117], v[178:179], v[182:183] neg_lo:[0,1] neg_hi:[0,1]
	v_pk_add_f32 v[108:109], v[176:177], v[180:181] op_sel:[0,1] op_sel_hi:[1,0] neg_hi:[0,1]
	v_pk_add_f32 v[124:125], v[176:177], v[180:181] op_sel:[0,1] op_sel_hi:[1,0] neg_lo:[0,1]
	v_pk_add_f32 v[186:187], v[102:103], v[118:119]
	v_pk_add_f32 v[184:185], v[102:103], v[118:119] neg_lo:[0,1] neg_hi:[0,1]
	v_pk_add_f32 v[166:167], v[110:111], v[126:127]
	v_pk_add_f32 v[188:189], v[110:111], v[126:127] neg_lo:[0,1] neg_hi:[0,1]
	v_pk_add_f32 v[102:103], v[186:187], v[166:167]
	v_pk_add_f32 v[118:119], v[186:187], v[166:167] neg_lo:[0,1] neg_hi:[0,1]
	v_pk_add_f32 v[110:111], v[184:185], v[188:189] op_sel:[0,1] op_sel_hi:[1,0] neg_hi:[0,1]
	v_pk_add_f32 v[126:127], v[184:185], v[188:189] op_sel:[0,1] op_sel_hi:[1,0] neg_lo:[0,1]
	v_pk_add_f32 v[174:175], v[104:105], v[120:121] op_sel:[0,1] op_sel_hi:[1,0] neg_hi:[0,1]
	v_pk_add_f32 v[168:169], v[104:105], v[120:121] op_sel:[0,1] op_sel_hi:[1,0] neg_lo:[0,1]
	v_pk_add_f32 v[178:179], v[112:113], v[128:129]
	v_pk_add_f32 v[176:177], v[112:113], v[128:129] neg_lo:[0,1] neg_hi:[0,1]
	v_pk_add_f32 v[104:105], v[174:175], v[178:179]
	v_pk_add_f32 v[120:121], v[174:175], v[178:179] neg_lo:[0,1] neg_hi:[0,1]
	v_pk_add_f32 v[112:113], v[168:169], v[176:177] op_sel:[0,1] op_sel_hi:[1,0] neg_hi:[0,1]
	v_pk_add_f32 v[128:129], v[168:169], v[176:177] op_sel:[0,1] op_sel_hi:[1,0] neg_lo:[0,1]
	v_pk_add_f32 v[182:183], v[106:107], v[122:123]
	v_pk_add_f32 v[180:181], v[106:107], v[122:123] neg_lo:[0,1] neg_hi:[0,1]
	v_pk_add_f32 v[186:187], v[114:115], v[130:131]
	v_pk_add_f32 v[184:185], v[114:115], v[130:131] neg_lo:[0,1] neg_hi:[0,1]
	v_pk_add_f32 v[106:107], v[182:183], v[186:187]
	v_pk_add_f32 v[122:123], v[182:183], v[186:187] neg_lo:[0,1] neg_hi:[0,1]
	v_pk_add_f32 v[114:115], v[180:181], v[184:185] op_sel:[0,1] op_sel_hi:[1,0] neg_hi:[0,1]
	v_pk_add_f32 v[130:131], v[180:181], v[184:185] op_sel:[0,1] op_sel_hi:[1,0] neg_lo:[0,1]
	ds_write_b64 v65, v[100:101]
	ds_read_b64 v[166:167], v56 offset:256
	ds_read_b64 v[188:189], v56 offset:512
	ds_read_b64 v[174:175], v56 offset:768
	ds_read_b64 v[168:169], v56 offset:1024
	s_waitcnt lgkmcnt(3)
	v_pk_mul_f32 v[178:179], v[102:103], v[166:167] op_sel:[1,1] op_sel_hi:[0,1]
	v_pk_fma_f32 v[102:103], v[102:103], v[166:167], v[178:179] op_sel_hi:[1,0,1] neg_lo:[0,0,1]
	ds_write_b64 v65, v[102:103] offset:264
	s_waitcnt lgkmcnt(3)
	v_pk_mul_f32 v[176:177], v[104:105], v[188:189] op_sel:[1,1] op_sel_hi:[0,1]
	v_pk_fma_f32 v[104:105], v[104:105], v[188:189], v[176:177] op_sel_hi:[1,0,1] neg_lo:[0,0,1]
	ds_write_b64 v65, v[104:105] offset:528
	s_waitcnt lgkmcnt(3)
	v_pk_mul_f32 v[182:183], v[106:107], v[174:175] op_sel:[1,1] op_sel_hi:[0,1]
	v_pk_fma_f32 v[106:107], v[106:107], v[174:175], v[182:183] op_sel_hi:[1,0,1] neg_lo:[0,0,1]
	ds_write_b64 v65, v[106:107] offset:792
	s_waitcnt lgkmcnt(3)
	v_pk_mul_f32 v[180:181], v[108:109], v[168:169] op_sel:[1,1] op_sel_hi:[0,1]
	v_pk_fma_f32 v[108:109], v[108:109], v[168:169], v[180:181] op_sel_hi:[1,0,1] neg_lo:[0,0,1]
	ds_write_b64 v65, v[108:109] offset:1056
	ds_read_b64 v[186:187], v56 offset:1280
	ds_read_b64 v[184:185], v56 offset:1536
	ds_read_b64 v[178:179], v56 offset:1792
	ds_read_b64 v[176:177], v56 offset:2048
	s_waitcnt lgkmcnt(3)
	v_pk_mul_f32 v[182:183], v[110:111], v[186:187] op_sel:[1,1] op_sel_hi:[0,1]
	v_pk_fma_f32 v[110:111], v[110:111], v[186:187], v[182:183] op_sel_hi:[1,0,1] neg_lo:[0,0,1]
	ds_write_b64 v65, v[110:111] offset:1320
	s_waitcnt lgkmcnt(3)
; #define LAS __attribute__((address_space(3)))
; __device__ __forceinline__ f32x2 cmul(f32x2 a, f32x2 b) { return (f32x2){a.x * b.x - a.y * b.y, a.x * b.y + a.y * b.x}; }
; __device__ __forceinline__ void fft_fwd2(LAS f32x2* B, const LAS f32x2* TW2, int tid) {
;     ...
;     B[fpad(base)] = x[0];
; #pragma unroll
;     for (int k = 1; k < 16; ++k) B[fpad(base + 32 * k)] = cmul(x[k], TW2[k * 32 + n2]);
; __device__ __forceinline__ void hy_sconv(const LAS float* plane, float w0, float w1, float w2, float cb, int n2, float (&u)[8][2]) {
;     asm volatile("" : "+v"(n2));
; #pragma unroll
;     for (int r = 0; r < 8; ++r)
; #pragma unroll
;         for (int b = 0; b < 2; ++b) { const int t = n2 + 512 * r, row = b * SEQ + t;
;             float a = cb + w1 * plane[row];
;             if (t > 0) a += w0 * plane[row - 1];
;             if (t < SEQ - 1) a += w2 * plane[row + 1];
;             u[r][b] = a; }
; }
	v_pk_mul_f32 v[180:181], v[112:113], v[184:185] op_sel:[1,1] op_sel_hi:[0,1]
	v_pk_fma_f32 v[112:113], v[112:113], v[184:185], v[180:181] op_sel_hi:[1,0,1] neg_lo:[0,0,1]
	ds_write_b64 v65, v[112:113] offset:1584
	s_waitcnt lgkmcnt(3)
	v_pk_mul_f32 v[166:167], v[114:115], v[178:179] op_sel:[1,1] op_sel_hi:[0,1]
	v_pk_fma_f32 v[114:115], v[114:115], v[178:179], v[166:167] op_sel_hi:[1,0,1] neg_lo:[0,0,1]
	ds_write_b64 v65, v[114:115] offset:1848
	s_waitcnt lgkmcnt(3)
	v_pk_mul_f32 v[188:189], v[116:117], v[176:177] op_sel:[1,1] op_sel_hi:[0,1]
	v_pk_fma_f32 v[116:117], v[116:117], v[176:177], v[188:189] op_sel_hi:[1,0,1] neg_lo:[0,0,1]
	ds_write_b64 v65, v[116:117] offset:2112
	ds_read_b64 v[174:175], v56 offset:2304
	ds_read_b64 v[168:169], v56 offset:2560
	ds_read_b64 v[182:183], v56 offset:2816
	ds_read_b64 v[180:181], v56 offset:3072
	s_waitcnt lgkmcnt(3)
	v_pk_mul_f32 v[166:167], v[118:119], v[174:175] op_sel:[1,1] op_sel_hi:[0,1]
	v_pk_fma_f32 v[118:119], v[118:119], v[174:175], v[166:167] op_sel_hi:[1,0,1] neg_lo:[0,0,1]
	ds_write_b64 v65, v[118:119] offset:2376
	s_waitcnt lgkmcnt(3)
	v_pk_mul_f32 v[188:189], v[120:121], v[168:169] op_sel:[1,1] op_sel_hi:[0,1]
	v_pk_fma_f32 v[120:121], v[120:121], v[168:169], v[188:189] op_sel_hi:[1,0,1] neg_lo:[0,0,1]
	ds_write_b64 v65, v[120:121] offset:2640
	s_waitcnt lgkmcnt(3)
	v_pk_mul_f32 v[186:187], v[122:123], v[182:183] op_sel:[1,1] op_sel_hi:[0,1]
	v_pk_fma_f32 v[122:123], v[122:123], v[182:183], v[186:187] op_sel_hi:[1,0,1] neg_lo:[0,0,1]
	ds_write_b64 v65, v[122:123] offset:2904
	s_waitcnt lgkmcnt(3)
	v_pk_mul_f32 v[184:185], v[124:125], v[180:181] op_sel:[1,1] op_sel_hi:[0,1]
	v_pk_fma_f32 v[124:125], v[124:125], v[180:181], v[184:185] op_sel_hi:[1,0,1] neg_lo:[0,0,1]
	ds_write_b64 v65, v[124:125] offset:3168
	ds_read_b64 v[178:179], v56 offset:3328
	ds_read_b64 v[176:177], v56 offset:3584
	ds_read_b64 v[166:167], v56 offset:3840
	s_waitcnt lgkmcnt(2)
	v_pk_mul_f32 v[188:189], v[126:127], v[178:179] op_sel:[1,1] op_sel_hi:[0,1]
	v_pk_fma_f32 v[126:127], v[126:127], v[178:179], v[188:189] op_sel_hi:[1,0,1] neg_lo:[0,0,1]
	ds_write_b64 v65, v[126:127] offset:3432
	s_waitcnt lgkmcnt(2)
	v_pk_mul_f32 v[186:187], v[128:129], v[176:177] op_sel:[1,1] op_sel_hi:[0,1]
	v_pk_fma_f32 v[128:129], v[128:129], v[176:177], v[186:187] op_sel_hi:[1,0,1] neg_lo:[0,0,1]
	ds_write_b64 v65, v[128:129] offset:3696
	s_waitcnt lgkmcnt(2)
	v_pk_mul_f32 v[184:185], v[130:131], v[166:167] op_sel:[1,1] op_sel_hi:[0,1]
	v_pk_fma_f32 v[130:131], v[130:131], v[166:167], v[184:185] op_sel_hi:[1,0,1] neg_lo:[0,0,1]
	ds_write_b64 v65, v[130:131] offset:3960
	s_waitcnt lgkmcnt(0)
	s_barrier
	v_mov_b32_e32 v174, s17
	v_mov_b32_e32 v175, s23
	v_mov_b32_e32 v168, s25
	v_mov_b32_e32 v169, s26
	ds_read_b32 v182, v208 offset:32768
	ds_read_b32 v180, v210 offset:32768
	ds_read_b32 v188, v208 offset:32772
	ds_read_b32 v183, v208 offset:49152
	ds_read_b32 v181, v210 offset:49152
	ds_read_b32 v189, v208 offset:49156
	ds_read_b32 v186, v208 offset:34816
	ds_read_b32 v184, v208 offset:34812
	ds_read_b32 v178, v208 offset:34820
	ds_read_b32 v187, v208 offset:51200
	ds_read_b32 v185, v208 offset:51196
	ds_read_b32 v179, v208 offset:51204
	s_waitcnt lgkmcnt(10)
	v_cndmask_b32_e64 v180, v180, 0, s[10:11]
	s_waitcnt lgkmcnt(7)
	v_cndmask_b32_e64 v181, v181, 0, s[10:11]
	v_pk_fma_f32 v[148:149], v[174:175], v[182:183], v[168:169] op_sel:[1,0,1]
	v_pk_fma_f32 v[148:149], v[174:175], v[180:181], v[148:149] op_sel_hi:[0,1,1]
	s_waitcnt lgkmcnt(6)
	v_pk_fma_f32 v[148:149], v[168:169], v[188:189], v[148:149] op_sel_hi:[0,1,1]
	s_waitcnt lgkmcnt(2)
	v_pk_fma_f32 v[150:151], v[174:175], v[186:187], v[168:169] op_sel:[1,0,1]
	s_waitcnt lgkmcnt(1)
	v_pk_fma_f32 v[150:151], v[174:175], v[184:185], v[150:151] op_sel_hi:[0,1,1]
	s_waitcnt lgkmcnt(0)
	v_pk_fma_f32 v[150:151], v[168:169], v[178:179], v[150:151] op_sel_hi:[0,1,1]
	ds_read_b32 v176, v208 offset:36864
	ds_read_b32 v166, v208 offset:36860
	ds_read_b32 v182, v208 offset:36868
	ds_read_b32 v177, v208 offset:53248
	ds_read_b32 v167, v208 offset:53244
	ds_read_b32 v183, v208 offset:53252
	ds_read_b32 v180, v208 offset:38912
	ds_read_b32 v188, v208 offset:38908
	ds_read_b32 v186, v208 offset:38916
	ds_read_b32 v181, v208 offset:55296
	ds_read_b32 v189, v208 offset:55292
	ds_read_b32 v187, v208 offset:55300
	s_waitcnt lgkmcnt(8)
	v_pk_fma_f32 v[152:153], v[174:175], v[176:177], v[168:169] op_sel:[1,0,1]
	s_waitcnt lgkmcnt(7)
	v_pk_fma_f32 v[152:153], v[174:175], v[166:167], v[152:153] op_sel_hi:[0,1,1]
	s_waitcnt lgkmcnt(6)
	v_pk_fma_f32 v[152:153], v[168:169], v[182:183], v[152:153] op_sel_hi:[0,1,1]
	s_waitcnt lgkmcnt(2)
	v_pk_fma_f32 v[154:155], v[174:175], v[180:181], v[168:169] op_sel:[1,0,1]
	s_waitcnt lgkmcnt(1)
	v_pk_fma_f32 v[154:155], v[174:175], v[188:189], v[154:155] op_sel_hi:[0,1,1]
	s_waitcnt lgkmcnt(0)
	v_pk_fma_f32 v[154:155], v[168:169], v[186:187], v[154:155] op_sel_hi:[0,1,1]
	ds_read_b32 v184, v208 offset:40960
	ds_read_b32 v178, v208 offset:40956
	ds_read_b32 v176, v208 offset:40964
	ds_read_b32 v185, v208 offset:57344
	ds_read_b32 v179, v208 offset:57340
	ds_read_b32 v177, v208 offset:57348
	ds_read_b32 v166, v208 offset:43008
	ds_read_b32 v182, v208 offset:43004
	ds_read_b32 v180, v208 offset:43012
	ds_read_b32 v167, v208 offset:59392
	ds_read_b32 v183, v208 offset:59388
	ds_read_b32 v181, v208 offset:59396
	s_waitcnt lgkmcnt(8)
	v_pk_fma_f32 v[158:159], v[174:175], v[184:185], v[168:169] op_sel:[1,0,1]
	s_waitcnt lgkmcnt(7)
	v_pk_fma_f32 v[158:159], v[174:175], v[178:179], v[158:159] op_sel_hi:[0,1,1]
	s_waitcnt lgkmcnt(6)
; #define LAS __attribute__((address_space(3)))
; __device__ __forceinline__ f32x2 cmul(f32x2 a, f32x2 b) { return (f32x2){a.x * b.x - a.y * b.y, a.x * b.y + a.y * b.x}; }
; template <int MODE> __device__ __forceinline__ void fft_pair32(LAS f32x2* B, const LAS f32x2* F, int wave, int lane) {
;     ...
;     const int hi = lane >> 5, blk = 32 * wave + (lane & 31); const float sg = hi ? -1.f : 1.f;
;     LAS f32x2* p = B + 33 * blk; f32x2 v[16];
; #pragma unroll
;     for (int j = 0; j < 16; ++j) { const f32x2 d = p[j] + p[j + 16] * sg;
;         const f32x2 w = {hi ? CS[j] : 1.f, hi ? -SN[j] : 0.f}; v[j] = j == 0 ? d : cmul(d, w); }
;     dft16<false>(v);
; __device__ __forceinline__ void hy_sconv(const LAS float* plane, float w0, float w1, float w2, float cb, int n2, float (&u)[8][2]) {
;     asm volatile("" : "+v"(n2));
; #pragma unroll
;     for (int r = 0; r < 8; ++r)
; #pragma unroll
;         for (int b = 0; b < 2; ++b) { const int t = n2 + 512 * r, row = b * SEQ + t;
;             float a = cb + w1 * plane[row];
;             if (t > 0) a += w0 * plane[row - 1];
;             if (t < SEQ - 1) a += w2 * plane[row + 1];
;             u[r][b] = a; }
; }
	v_pk_fma_f32 v[158:159], v[168:169], v[176:177], v[158:159] op_sel_hi:[0,1,1]
	s_waitcnt lgkmcnt(2)
	v_pk_fma_f32 v[160:161], v[174:175], v[166:167], v[168:169] op_sel:[1,0,1]
	s_waitcnt lgkmcnt(1)
	v_pk_fma_f32 v[160:161], v[174:175], v[182:183], v[160:161] op_sel_hi:[0,1,1]
	s_waitcnt lgkmcnt(0)
	v_pk_fma_f32 v[160:161], v[168:169], v[180:181], v[160:161] op_sel_hi:[0,1,1]
	ds_read_b32 v188, v208 offset:45056
	ds_read_b32 v186, v208 offset:45052
	ds_read_b32 v184, v208 offset:45060
	ds_read_b32 v189, v208 offset:61440
	ds_read_b32 v187, v208 offset:61436
	ds_read_b32 v185, v208 offset:61444
	ds_read_b32 v178, v208 offset:47104
	ds_read_b32 v176, v208 offset:47100
	ds_read_b32 v166, v208 offset:47108
	ds_read_b32 v179, v208 offset:63488
	ds_read_b32 v177, v208 offset:63484
	ds_read_b32 v167, v208 offset:63492
	s_waitcnt lgkmcnt(8)
	v_pk_fma_f32 v[162:163], v[174:175], v[188:189], v[168:169] op_sel:[1,0,1]
	s_waitcnt lgkmcnt(7)
	v_pk_fma_f32 v[162:163], v[174:175], v[186:187], v[162:163] op_sel_hi:[0,1,1]
	s_waitcnt lgkmcnt(6)
	v_pk_fma_f32 v[162:163], v[168:169], v[184:185], v[162:163] op_sel_hi:[0,1,1]
	s_waitcnt lgkmcnt(3)
	v_cndmask_b32_e64 v166, v166, 0, s[28:29]
	s_waitcnt lgkmcnt(0)
	v_cndmask_b32_e64 v167, v167, 0, s[28:29]
	v_pk_fma_f32 v[164:165], v[174:175], v[178:179], v[168:169] op_sel:[1,0,1]
	v_pk_fma_f32 v[164:165], v[174:175], v[176:177], v[164:165] op_sel_hi:[0,1,1]
	v_pk_fma_f32 v[164:165], v[168:169], v[166:167], v[164:165] op_sel_hi:[0,1,1]
	s_load_dword s17, s[60:61], 0x1000
	s_load_dword s23, s[60:61], 0x4000
	s_load_dword s25, s[60:61], 0x7000
	s_load_dword s26, s[62:63], 0x1000
	v_add_u32_e32 v65, 0x10800, v156
	v_add_u32_e32 v69, 0x10800, v196
	ds_read_b64 v[100:101], v65
	ds_read_b64 v[182:183], v65 offset:128
	ds_read_b64 v[102:103], v65 offset:8
	ds_read_b64 v[180:181], v65 offset:136
	ds_read_b64 v[104:105], v65 offset:16
	ds_read_b64 v[188:189], v65 offset:144
	ds_read_b64 v[106:107], v65 offset:24
	ds_read_b64 v[186:187], v65 offset:152
	s_waitcnt lgkmcnt(0)
	v_pk_fma_f32 v[100:101], v[182:183], v[190:191], v[100:101] op_sel_hi:[1,0,1]
	v_pk_fma_f32 v[102:103], v[180:181], v[190:191], v[102:103] op_sel_hi:[1,0,1]
	v_pk_mul_f32 v[184:185], v[102:103], v[36:37] op_sel:[1,1] op_sel_hi:[0,1]
	v_pk_fma_f32 v[102:103], v[102:103], v[36:37], v[184:185] op_sel_hi:[1,0,1] neg_lo:[0,0,1]
	v_pk_fma_f32 v[104:105], v[188:189], v[190:191], v[104:105] op_sel_hi:[1,0,1]
	v_pk_mul_f32 v[178:179], v[104:105], v[38:39] op_sel:[1,1] op_sel_hi:[0,1]
	v_pk_fma_f32 v[104:105], v[104:105], v[38:39], v[178:179] op_sel_hi:[1,0,1] neg_lo:[0,0,1]
	v_pk_fma_f32 v[106:107], v[186:187], v[190:191], v[106:107] op_sel_hi:[1,0,1]
	v_pk_mul_f32 v[176:177], v[106:107], v[40:41] op_sel:[1,1] op_sel_hi:[0,1]
	v_pk_fma_f32 v[106:107], v[106:107], v[40:41], v[176:177] op_sel_hi:[1,0,1] neg_lo:[0,0,1]
	ds_read_b64 v[108:109], v65 offset:32
	ds_read_b64 v[166:167], v65 offset:160
	ds_read_b64 v[110:111], v65 offset:40
	ds_read_b64 v[174:175], v65 offset:168
	ds_read_b64 v[112:113], v65 offset:48
	ds_read_b64 v[168:169], v65 offset:176
	ds_read_b64 v[114:115], v65 offset:56
	ds_read_b64 v[184:185], v65 offset:184
	s_waitcnt lgkmcnt(6)
	v_pk_fma_f32 v[108:109], v[166:167], v[190:191], v[108:109] op_sel_hi:[1,0,1]
	v_pk_mul_f32 v[178:179], v[108:109], v[42:43] op_sel:[1,1] op_sel_hi:[0,1]
	v_pk_fma_f32 v[108:109], v[108:109], v[42:43], v[178:179] op_sel_hi:[1,0,1] neg_lo:[0,0,1]
	s_waitcnt lgkmcnt(4)
	v_pk_fma_f32 v[110:111], v[174:175], v[190:191], v[110:111] op_sel_hi:[1,0,1]
	v_pk_mul_f32 v[176:177], v[110:111], v[44:45] op_sel:[1,1] op_sel_hi:[0,1]
	v_pk_fma_f32 v[110:111], v[110:111], v[44:45], v[176:177] op_sel_hi:[1,0,1] neg_lo:[0,0,1]
	s_waitcnt lgkmcnt(2)
	v_pk_fma_f32 v[112:113], v[168:169], v[190:191], v[112:113] op_sel_hi:[1,0,1]
	v_pk_mul_f32 v[182:183], v[112:113], v[46:47] op_sel:[1,1] op_sel_hi:[0,1]
	v_pk_fma_f32 v[112:113], v[112:113], v[46:47], v[182:183] op_sel_hi:[1,0,1] neg_lo:[0,0,1]
	s_waitcnt lgkmcnt(0)
	v_pk_fma_f32 v[114:115], v[184:185], v[190:191], v[114:115] op_sel_hi:[1,0,1]
	v_pk_mul_f32 v[180:181], v[114:115], v[48:49] op_sel:[1,1] op_sel_hi:[0,1]
	v_pk_fma_f32 v[114:115], v[114:115], v[48:49], v[180:181] op_sel_hi:[1,0,1] neg_lo:[0,0,1]
	ds_read_b64 v[116:117], v65 offset:64
	ds_read_b64 v[188:189], v65 offset:192
	ds_read_b64 v[118:119], v65 offset:72
	ds_read_b64 v[186:187], v65 offset:200
	ds_read_b64 v[120:121], v65 offset:80
	ds_read_b64 v[178:179], v65 offset:208
	ds_read_b64 v[122:123], v65 offset:88
	ds_read_b64 v[176:177], v65 offset:216
	s_waitcnt lgkmcnt(6)
	v_pk_fma_f32 v[116:117], v[188:189], v[190:191], v[116:117] op_sel_hi:[1,0,1]
	v_pk_mul_f32 v[182:183], v[116:117], v[50:51] op_sel:[1,1] op_sel_hi:[0,1]
	v_pk_fma_f32 v[116:117], v[116:117], v[50:51], v[182:183] op_sel_hi:[1,0,1] neg_lo:[0,0,1]
	s_waitcnt lgkmcnt(4)
	v_pk_fma_f32 v[118:119], v[186:187], v[190:191], v[118:119] op_sel_hi:[1,0,1]
	v_pk_mul_f32 v[180:181], v[118:119], v[52:53] op_sel:[1,1] op_sel_hi:[0,1]
	v_pk_fma_f32 v[118:119], v[118:119], v[52:53], v[180:181] op_sel_hi:[1,0,1] neg_lo:[0,0,1]
	s_waitcnt lgkmcnt(2)
	v_pk_fma_f32 v[120:121], v[178:179], v[190:191], v[120:121] op_sel_hi:[1,0,1]
	v_pk_mul_f32 v[166:167], v[120:121], v[54:55] op_sel:[1,1] op_sel_hi:[0,1]
	v_pk_fma_f32 v[120:121], v[120:121], v[54:55], v[166:167] op_sel_hi:[1,0,1] neg_lo:[0,0,1]
	s_waitcnt lgkmcnt(0)
; __device__ __forceinline__ f32x2 cmul(f32x2 a, f32x2 b) { return (f32x2){a.x * b.x - a.y * b.y, a.x * b.y + a.y * b.x}; }
; template <bool INV> __device__ __forceinline__ f32x2 cmul_tw(f32x2 a, f32x2 w) { return INV ? cmulc(a, w) : cmul(a, w); }
; template <bool INV> __device__ __forceinline__ void dft16(f32x2 (&x)[16]) {
;     constexpr float C1 = 0.92387953251128674f, S1 = 0.38268343236508977f, C2 = 0.70710678118654752f;
; #pragma unroll
;     for (int b = 0; b < 4; ++b) dft4<INV>(x[b], x[4 + b], x[8 + b], x[12 + b]);
;     const f32x2 w1 = {C1, -S1}, w2 = {C2, -C2}, w3 = {S1, -C1}, w4 = {0.f, -1.f}, w6 = {-C2, -C2}, w9 = {-C1, S1};
;     x[4 * 1 + 1] = cmul_tw<INV>(x[5], w1); x[4 * 1 + 2] = cmul_tw<INV>(x[6], w2); x[4 * 1 + 3] = cmul_tw<INV>(x[7], w3);
;     x[4 * 2 + 1] = cmul_tw<INV>(x[9], w2); x[4 * 2 + 2] = cmul_tw<INV>(x[10], w4); x[4 * 2 + 3] = cmul_tw<INV>(x[11], w6);
;     x[4 * 3 + 1] = cmul_tw<INV>(x[13], w3); x[4 * 3 + 2] = cmul_tw<INV>(x[14], w6); x[4 * 3 + 3] = cmul_tw<INV>(x[15], w9);
; #pragma unroll
;     for (int c = 0; c < 4; ++c) dft4<INV>(x[4 * c], x[4 * c + 1], x[4 * c + 2], x[4 * c + 3]);
; template <int MODE> __device__ __forceinline__ void fft_pair32(LAS f32x2* B, const LAS f32x2* F, int wave, int lane) {
;     ...
;     for (int j = 0; j < 16; ++j) { const f32x2 d = p[j] + p[j + 16] * sg;
;         const f32x2 w = {hi ? CS[j] : 1.f, hi ? -SN[j] : 0.f}; v[j] = j == 0 ? d : cmul(d, w); }
;     dft16<false>(v);
	v_pk_fma_f32 v[122:123], v[176:177], v[190:191], v[122:123] op_sel_hi:[1,0,1]
	v_pk_mul_f32 v[174:175], v[122:123], v[90:91] op_sel:[1,1] op_sel_hi:[0,1]
	v_pk_fma_f32 v[122:123], v[122:123], v[90:91], v[174:175] op_sel_hi:[1,0,1] neg_lo:[0,0,1]
	ds_read_b64 v[124:125], v65 offset:96
	ds_read_b64 v[168:169], v65 offset:224
	ds_read_b64 v[126:127], v65 offset:104
	ds_read_b64 v[184:185], v65 offset:232
	ds_read_b64 v[128:129], v65 offset:112
	ds_read_b64 v[182:183], v65 offset:240
	ds_read_b64 v[130:131], v65 offset:120
	ds_read_b64 v[180:181], v65 offset:248
	s_waitcnt lgkmcnt(6)
	v_pk_fma_f32 v[124:125], v[168:169], v[190:191], v[124:125] op_sel_hi:[1,0,1]
	v_pk_mul_f32 v[166:167], v[124:125], v[92:93] op_sel:[1,1] op_sel_hi:[0,1]
	v_pk_fma_f32 v[124:125], v[124:125], v[92:93], v[166:167] op_sel_hi:[1,0,1] neg_lo:[0,0,1]
	s_waitcnt lgkmcnt(4)
	v_pk_fma_f32 v[126:127], v[184:185], v[190:191], v[126:127] op_sel_hi:[1,0,1]
	v_pk_mul_f32 v[174:175], v[126:127], v[94:95] op_sel:[1,1] op_sel_hi:[0,1]
	v_pk_fma_f32 v[126:127], v[126:127], v[94:95], v[174:175] op_sel_hi:[1,0,1] neg_lo:[0,0,1]
	s_waitcnt lgkmcnt(2)
	v_pk_fma_f32 v[128:129], v[182:183], v[190:191], v[128:129] op_sel_hi:[1,0,1]
	v_pk_mul_f32 v[188:189], v[128:129], v[96:97] op_sel:[1,1] op_sel_hi:[0,1]
	v_pk_fma_f32 v[128:129], v[128:129], v[96:97], v[188:189] op_sel_hi:[1,0,1] neg_lo:[0,0,1]
	s_waitcnt lgkmcnt(0)
	v_pk_fma_f32 v[130:131], v[180:181], v[190:191], v[130:131] op_sel_hi:[1,0,1]
	v_pk_mul_f32 v[186:187], v[130:131], v[98:99] op_sel:[1,1] op_sel_hi:[0,1]
	v_pk_fma_f32 v[130:131], v[130:131], v[98:99], v[186:187] op_sel_hi:[1,0,1] neg_lo:[0,0,1]
	v_pk_add_f32 v[178:179], v[100:101], v[116:117]
	v_pk_add_f32 v[176:177], v[100:101], v[116:117] neg_lo:[0,1] neg_hi:[0,1]
	v_pk_add_f32 v[166:167], v[108:109], v[124:125]
	v_pk_add_f32 v[174:175], v[108:109], v[124:125] neg_lo:[0,1] neg_hi:[0,1]
	v_pk_add_f32 v[100:101], v[178:179], v[166:167]
	v_pk_add_f32 v[116:117], v[178:179], v[166:167] neg_lo:[0,1] neg_hi:[0,1]
	v_pk_add_f32 v[108:109], v[176:177], v[174:175] op_sel:[0,1] op_sel_hi:[1,0] neg_hi:[0,1]
	v_pk_add_f32 v[124:125], v[176:177], v[174:175] op_sel:[0,1] op_sel_hi:[1,0] neg_lo:[0,1]
	v_pk_add_f32 v[188:189], v[102:103], v[118:119]
	v_pk_add_f32 v[186:187], v[102:103], v[118:119] neg_lo:[0,1] neg_hi:[0,1]
	v_pk_add_f32 v[168:169], v[110:111], v[126:127]
	v_pk_add_f32 v[184:185], v[110:111], v[126:127] neg_lo:[0,1] neg_hi:[0,1]
	v_pk_add_f32 v[102:103], v[188:189], v[168:169]
	v_pk_add_f32 v[118:119], v[188:189], v[168:169] neg_lo:[0,1] neg_hi:[0,1]
	v_pk_add_f32 v[110:111], v[186:187], v[184:185] op_sel:[0,1] op_sel_hi:[1,0] neg_hi:[0,1]
	v_pk_add_f32 v[126:127], v[186:187], v[184:185] op_sel:[0,1] op_sel_hi:[1,0] neg_lo:[0,1]
	v_pk_add_f32 v[182:183], v[104:105], v[120:121]
	v_pk_add_f32 v[180:181], v[104:105], v[120:121] neg_lo:[0,1] neg_hi:[0,1]
	v_pk_add_f32 v[178:179], v[112:113], v[128:129]
	v_pk_add_f32 v[176:177], v[112:113], v[128:129] neg_lo:[0,1] neg_hi:[0,1]
	v_pk_add_f32 v[104:105], v[182:183], v[178:179]
	v_pk_add_f32 v[120:121], v[182:183], v[178:179] neg_lo:[0,1] neg_hi:[0,1]
	v_pk_add_f32 v[112:113], v[180:181], v[176:177] op_sel:[0,1] op_sel_hi:[1,0] neg_hi:[0,1]
	v_pk_add_f32 v[128:129], v[180:181], v[176:177] op_sel:[0,1] op_sel_hi:[1,0] neg_lo:[0,1]
	v_pk_add_f32 v[166:167], v[106:107], v[122:123]
	v_pk_add_f32 v[174:175], v[106:107], v[122:123] neg_lo:[0,1] neg_hi:[0,1]
	v_pk_add_f32 v[188:189], v[114:115], v[130:131]
	v_pk_add_f32 v[186:187], v[114:115], v[130:131] neg_lo:[0,1] neg_hi:[0,1]
	v_pk_add_f32 v[106:107], v[166:167], v[188:189]
	v_pk_add_f32 v[122:123], v[166:167], v[188:189] neg_lo:[0,1] neg_hi:[0,1]
	v_pk_add_f32 v[114:115], v[174:175], v[186:187] op_sel:[0,1] op_sel_hi:[1,0] neg_hi:[0,1]
	v_pk_add_f32 v[130:131], v[174:175], v[186:187] op_sel:[0,1] op_sel_hi:[1,0] neg_lo:[0,1]
	v_pk_mul_f32 v[168:169], v[110:111], s[68:69] op_sel:[1,1] op_sel_hi:[0,1]
	v_pk_fma_f32 v[110:111], v[110:111], s[68:69], v[168:169] op_sel_hi:[1,0,1] neg_lo:[0,0,1]
	v_pk_mul_f32 v[184:185], v[112:113], s[84:85] op_sel:[1,1] op_sel_hi:[0,1]
	v_pk_fma_f32 v[112:113], v[112:113], s[84:85], v[184:185] op_sel_hi:[1,0,1] neg_lo:[0,0,1]
	v_pk_mul_f32 v[182:183], v[114:115], s[88:89] op_sel:[1,1] op_sel_hi:[0,1]
	v_pk_fma_f32 v[114:115], v[114:115], s[88:89], v[182:183] op_sel_hi:[1,0,1] neg_lo:[0,0,1]
	v_pk_mul_f32 v[180:181], v[118:119], s[84:85] op_sel:[1,1] op_sel_hi:[0,1]
	v_pk_fma_f32 v[118:119], v[118:119], s[84:85], v[180:181] op_sel_hi:[1,0,1] neg_lo:[0,0,1]
	v_pk_mul_f32 v[178:179], v[122:123], s[90:91] op_sel:[1,1] op_sel_hi:[0,1]
	v_pk_fma_f32 v[122:123], v[122:123], s[90:91], v[178:179] op_sel_hi:[1,0,1] neg_lo:[0,0,1]
	v_pk_mul_f32 v[176:177], v[126:127], s[88:89] op_sel:[1,1] op_sel_hi:[0,1]
	v_pk_fma_f32 v[126:127], v[126:127], s[88:89], v[176:177] op_sel_hi:[1,0,1] neg_lo:[0,0,1]
	v_pk_mul_f32 v[166:167], v[128:129], s[90:91] op_sel:[1,1] op_sel_hi:[0,1]
	v_pk_fma_f32 v[128:129], v[128:129], s[90:91], v[166:167] op_sel_hi:[1,0,1] neg_lo:[0,0,1]
	v_pk_mul_f32 v[174:175], v[130:131], s[98:99] op_sel:[1,1] op_sel_hi:[0,1]
	v_pk_fma_f32 v[130:131], v[130:131], s[98:99], v[174:175] op_sel_hi:[1,0,1] neg_lo:[0,0,1]
	v_pk_add_f32 v[188:189], v[100:101], v[104:105]
	v_pk_add_f32 v[186:187], v[100:101], v[104:105] neg_lo:[0,1] neg_hi:[0,1]
	v_pk_add_f32 v[168:169], v[102:103], v[106:107]
	v_pk_add_f32 v[184:185], v[102:103], v[106:107] neg_lo:[0,1] neg_hi:[0,1]
	v_pk_add_f32 v[100:101], v[188:189], v[168:169]
	v_pk_add_f32 v[104:105], v[188:189], v[168:169] neg_lo:[0,1] neg_hi:[0,1]
	v_pk_add_f32 v[102:103], v[186:187], v[184:185] op_sel:[0,1] op_sel_hi:[1,0] neg_hi:[0,1]
; __device__ __forceinline__ f32x2 cmul(f32x2 a, f32x2 b) { return (f32x2){a.x * b.x - a.y * b.y, a.x * b.y + a.y * b.x}; }
; __device__ __forceinline__ void dft16_fwd_lo(f32x2 (&x)[16]) {
;     constexpr float C1 = 0.92387953251128674f, S1 = 0.38268343236508977f, C2 = 0.70710678118654752f;
; #pragma unroll
;     for (int b = 0; b < 4; ++b) { const f32x2 x0 = x[b], x1 = x[4 + b]; const f32x2 j1 = {x1.y, -x1.x};
;         x[b] = x0 + x1; x[4 + b] = x0 + j1; x[8 + b] = x0 - x1; x[12 + b] = x0 - j1; }
;     const f32x2 w1 = {C1, -S1}, w2 = {C2, -C2}, w3 = {S1, -C1}, w4 = {0.f, -1.f}, w6 = {-C2, -C2}, w9 = {-C1, S1};
;     x[5] = cmul(x[5], w1); x[6] = cmul(x[6], w2); x[7] = cmul(x[7], w3);
;     x[9] = cmul(x[9], w2); x[10] = cmul(x[10], w4); x[11] = cmul(x[11], w6);
;     x[13] = cmul(x[13], w3); x[14] = cmul(x[14], w6); x[15] = cmul(x[15], w9);
; template <int MODE> __device__ __forceinline__ void fft_pair32(LAS f32x2* B, const LAS f32x2* F, int wave, int lane) {
;     ...
;     if (MODE == 2) {
; #pragma unroll
;         for (int k = 0; k < 16; ++k) p[2 * k + hi] = v[k];
;         return; }
	v_pk_add_f32 v[106:107], v[186:187], v[184:185] op_sel:[0,1] op_sel_hi:[1,0] neg_lo:[0,1]
	v_pk_add_f32 v[182:183], v[108:109], v[112:113]
	v_pk_add_f32 v[180:181], v[108:109], v[112:113] neg_lo:[0,1] neg_hi:[0,1]
	v_pk_add_f32 v[178:179], v[110:111], v[114:115]
	v_pk_add_f32 v[176:177], v[110:111], v[114:115] neg_lo:[0,1] neg_hi:[0,1]
	v_pk_add_f32 v[108:109], v[182:183], v[178:179]
	v_pk_add_f32 v[112:113], v[182:183], v[178:179] neg_lo:[0,1] neg_hi:[0,1]
	v_pk_add_f32 v[110:111], v[180:181], v[176:177] op_sel:[0,1] op_sel_hi:[1,0] neg_hi:[0,1]
	v_pk_add_f32 v[114:115], v[180:181], v[176:177] op_sel:[0,1] op_sel_hi:[1,0] neg_lo:[0,1]
	v_pk_add_f32 v[166:167], v[116:117], v[120:121] op_sel:[0,1] op_sel_hi:[1,0] neg_hi:[0,1]
	v_pk_add_f32 v[174:175], v[116:117], v[120:121] op_sel:[0,1] op_sel_hi:[1,0] neg_lo:[0,1]
	v_pk_add_f32 v[188:189], v[118:119], v[122:123]
	v_pk_add_f32 v[186:187], v[118:119], v[122:123] neg_lo:[0,1] neg_hi:[0,1]
	v_pk_add_f32 v[116:117], v[166:167], v[188:189]
	v_pk_add_f32 v[120:121], v[166:167], v[188:189] neg_lo:[0,1] neg_hi:[0,1]
	v_pk_add_f32 v[118:119], v[174:175], v[186:187] op_sel:[0,1] op_sel_hi:[1,0] neg_hi:[0,1]
	v_pk_add_f32 v[122:123], v[174:175], v[186:187] op_sel:[0,1] op_sel_hi:[1,0] neg_lo:[0,1]
	v_pk_add_f32 v[168:169], v[124:125], v[128:129]
	v_pk_add_f32 v[184:185], v[124:125], v[128:129] neg_lo:[0,1] neg_hi:[0,1]
	v_pk_add_f32 v[182:183], v[126:127], v[130:131]
	v_pk_add_f32 v[180:181], v[126:127], v[130:131] neg_lo:[0,1] neg_hi:[0,1]
	v_pk_add_f32 v[124:125], v[168:169], v[182:183]
	v_pk_add_f32 v[128:129], v[168:169], v[182:183] neg_lo:[0,1] neg_hi:[0,1]
	v_pk_add_f32 v[126:127], v[184:185], v[180:181] op_sel:[0,1] op_sel_hi:[1,0] neg_hi:[0,1]
	v_pk_add_f32 v[130:131], v[184:185], v[180:181] op_sel:[0,1] op_sel_hi:[1,0] neg_lo:[0,1]
	v_pk_mul_f32 v[100:101], v[100:101], v[192:193] op_sel_hi:[1,0]
	ds_write_b64 v69, v[100:101]
	v_pk_mul_f32 v[108:109], v[108:109], v[192:193] op_sel_hi:[1,0]
	ds_write_b64 v69, v[108:109] offset:16
	v_pk_mul_f32 v[116:117], v[116:117], v[192:193] op_sel_hi:[1,0]
	ds_write_b64 v69, v[116:117] offset:32
	v_pk_mul_f32 v[124:125], v[124:125], v[192:193] op_sel_hi:[1,0]
	ds_write_b64 v69, v[124:125] offset:48
	v_pk_mul_f32 v[102:103], v[102:103], v[192:193] op_sel_hi:[1,0]
	ds_write_b64 v69, v[102:103] offset:64
	v_pk_mul_f32 v[110:111], v[110:111], v[192:193] op_sel_hi:[1,0]
	ds_write_b64 v69, v[110:111] offset:80
	v_pk_mul_f32 v[118:119], v[118:119], v[192:193] op_sel_hi:[1,0]
	ds_write_b64 v69, v[118:119] offset:96
	v_pk_mul_f32 v[126:127], v[126:127], v[192:193] op_sel_hi:[1,0]
	ds_write_b64 v69, v[126:127] offset:112
	v_pk_mul_f32 v[104:105], v[104:105], v[192:193] op_sel_hi:[1,0]
	ds_write_b64 v69, v[104:105] offset:128
	v_pk_mul_f32 v[112:113], v[112:113], v[192:193] op_sel_hi:[1,0]
	ds_write_b64 v69, v[112:113] offset:144
	v_pk_mul_f32 v[120:121], v[120:121], v[192:193] op_sel_hi:[1,0]
	ds_write_b64 v69, v[120:121] offset:160
	v_pk_mul_f32 v[128:129], v[128:129], v[192:193] op_sel_hi:[1,0]
	ds_write_b64 v69, v[128:129] offset:176
	v_pk_mul_f32 v[106:107], v[106:107], v[192:193] op_sel_hi:[1,0]
	ds_write_b64 v69, v[106:107] offset:192
	v_pk_mul_f32 v[114:115], v[114:115], v[192:193] op_sel_hi:[1,0]
	ds_write_b64 v69, v[114:115] offset:208
	v_pk_mul_f32 v[122:123], v[122:123], v[192:193] op_sel_hi:[1,0]
	ds_write_b64 v69, v[122:123] offset:224
	v_pk_mul_f32 v[130:131], v[130:131], v[192:193] op_sel_hi:[1,0]
	ds_write_b64 v69, v[130:131] offset:240
	s_waitcnt lgkmcnt(0)
	s_barrier
	v_pk_add_f32 v[104:105], v[132:133], v[140:141] neg_lo:[0,1] neg_hi:[0,1]
	v_pk_add_f32 v[106:107], v[132:133], v[140:141] op_sel:[0,1] op_sel_hi:[1,0] neg_lo:[0,1]
	v_pk_add_f32 v[178:179], v[132:133], v[140:141] op_sel:[0,1] op_sel_hi:[1,0] neg_hi:[0,1]
	v_pk_add_f32 v[100:101], v[132:133], v[140:141]
	v_pk_add_f32 v[112:113], v[134:135], v[142:143] neg_lo:[0,1] neg_hi:[0,1]
	v_pk_add_f32 v[114:115], v[134:135], v[142:143] op_sel:[0,1] op_sel_hi:[1,0] neg_lo:[0,1]
	v_pk_add_f32 v[176:177], v[134:135], v[142:143] op_sel:[0,1] op_sel_hi:[1,0] neg_hi:[0,1]
	v_pk_add_f32 v[108:109], v[134:135], v[142:143]
	v_pk_add_f32 v[120:121], v[136:137], v[144:145] neg_lo:[0,1] neg_hi:[0,1]
	v_pk_add_f32 v[122:123], v[136:137], v[144:145] op_sel:[0,1] op_sel_hi:[1,0] neg_lo:[0,1]
	v_pk_add_f32 v[166:167], v[136:137], v[144:145] op_sel:[0,1] op_sel_hi:[1,0] neg_hi:[0,1]
	v_pk_add_f32 v[116:117], v[136:137], v[144:145]
	v_pk_add_f32 v[128:129], v[138:139], v[146:147] neg_lo:[0,1] neg_hi:[0,1]
	v_pk_add_f32 v[130:131], v[138:139], v[146:147] op_sel:[0,1] op_sel_hi:[1,0] neg_lo:[0,1]
	v_pk_add_f32 v[174:175], v[138:139], v[146:147] op_sel:[0,1] op_sel_hi:[1,0] neg_hi:[0,1]
	v_pk_add_f32 v[124:125], v[138:139], v[146:147]
	v_pk_mul_f32 v[188:189], v[176:177], s[68:69] op_sel:[1,1] op_sel_hi:[0,1]
	v_pk_fma_f32 v[176:177], v[176:177], s[68:69], v[188:189] op_sel_hi:[1,0,1] neg_lo:[0,0,1]
	v_pk_mul_f32 v[186:187], v[166:167], s[84:85] op_sel:[1,1] op_sel_hi:[0,1]
	v_pk_fma_f32 v[166:167], v[166:167], s[84:85], v[186:187] op_sel_hi:[1,0,1] neg_lo:[0,0,1]
	v_pk_mul_f32 v[168:169], v[174:175], s[88:89] op_sel:[1,1] op_sel_hi:[0,1]
	v_pk_fma_f32 v[174:175], v[174:175], s[88:89], v[168:169] op_sel_hi:[1,0,1] neg_lo:[0,0,1]
	v_pk_mul_f32 v[184:185], v[112:113], s[84:85] op_sel:[1,1] op_sel_hi:[0,1]
	v_pk_fma_f32 v[112:113], v[112:113], s[84:85], v[184:185] op_sel_hi:[1,0,1] neg_lo:[0,0,1]
	v_pk_mul_f32 v[182:183], v[128:129], s[90:91] op_sel:[1,1] op_sel_hi:[0,1]
	v_pk_fma_f32 v[128:129], v[128:129], s[90:91], v[182:183] op_sel_hi:[1,0,1] neg_lo:[0,0,1]
	v_pk_mul_f32 v[180:181], v[114:115], s[88:89] op_sel:[1,1] op_sel_hi:[0,1]
; __device__ __forceinline__ f32x2 cmul(f32x2 a, f32x2 b) { return (f32x2){a.x * b.x - a.y * b.y, a.x * b.y + a.y * b.x}; }
; __device__ __forceinline__ void dft16_fwd_lo(f32x2 (&x)[16]) {
;     ...
;     x[5] = cmul(x[5], w1); x[6] = cmul(x[6], w2); x[7] = cmul(x[7], w3);
;     x[9] = cmul(x[9], w2); x[10] = cmul(x[10], w4); x[11] = cmul(x[11], w6);
;     x[13] = cmul(x[13], w3); x[14] = cmul(x[14], w6); x[15] = cmul(x[15], w9);
; #pragma unroll
;     for (int c = 0; c < 4; ++c) dft4<false>(x[4 * c], x[4 * c + 1], x[4 * c + 2], x[4 * c + 3]);
;     f32x2 y[16];
; #pragma unroll
;     for (int k = 0; k < 16; ++k) y[k] = x[4 * (k & 3) + (k >> 2)];
; #pragma unroll
;     for (int k = 0; k < 16; ++k) x[k] = y[k];
; template <bool LO> __device__ __forceinline__ void fft_fwd1(f32x2 (&x)[16], LAS f32x2* B, int n2, const f32x2 (&w)[16]) {
;     ...
;     B[fpad(n2)] = x[0];
; #pragma unroll
;     for (int k = 1; k < 16; ++k) B[fpad(512 * k + n2)] = cmul(x[k], w[k]);
	v_pk_fma_f32 v[114:115], v[114:115], s[88:89], v[180:181] op_sel_hi:[1,0,1] neg_lo:[0,0,1]
	v_pk_mul_f32 v[102:103], v[122:123], s[90:91] op_sel:[1,1] op_sel_hi:[0,1]
	v_pk_fma_f32 v[122:123], v[122:123], s[90:91], v[102:103] op_sel_hi:[1,0,1] neg_lo:[0,0,1]
	v_pk_mul_f32 v[110:111], v[130:131], s[98:99] op_sel:[1,1] op_sel_hi:[0,1]
	v_pk_fma_f32 v[130:131], v[130:131], s[98:99], v[110:111] op_sel_hi:[1,0,1] neg_lo:[0,0,1]
	v_pk_add_f32 v[118:119], v[100:101], v[116:117]
	v_pk_add_f32 v[126:127], v[100:101], v[116:117] neg_lo:[0,1] neg_hi:[0,1]
	v_pk_add_f32 v[188:189], v[108:109], v[124:125]
	v_pk_add_f32 v[186:187], v[108:109], v[124:125] neg_lo:[0,1] neg_hi:[0,1]
	v_pk_add_f32 v[100:101], v[118:119], v[188:189]
	v_pk_add_f32 v[116:117], v[118:119], v[188:189] neg_lo:[0,1] neg_hi:[0,1]
	v_pk_add_f32 v[108:109], v[126:127], v[186:187] op_sel:[0,1] op_sel_hi:[1,0] neg_hi:[0,1]
	v_pk_add_f32 v[124:125], v[126:127], v[186:187] op_sel:[0,1] op_sel_hi:[1,0] neg_lo:[0,1]
	v_pk_add_f32 v[168:169], v[178:179], v[166:167]
	v_pk_add_f32 v[184:185], v[178:179], v[166:167] neg_lo:[0,1] neg_hi:[0,1]
	v_pk_add_f32 v[182:183], v[176:177], v[174:175]
	v_pk_add_f32 v[180:181], v[176:177], v[174:175] neg_lo:[0,1] neg_hi:[0,1]
	v_pk_add_f32 v[178:179], v[168:169], v[182:183]
	v_pk_add_f32 v[166:167], v[168:169], v[182:183] neg_lo:[0,1] neg_hi:[0,1]
	v_pk_add_f32 v[176:177], v[184:185], v[180:181] op_sel:[0,1] op_sel_hi:[1,0] neg_hi:[0,1]
	v_pk_add_f32 v[174:175], v[184:185], v[180:181] op_sel:[0,1] op_sel_hi:[1,0] neg_lo:[0,1]
	v_pk_add_f32 v[102:103], v[104:105], v[120:121] op_sel:[0,1] op_sel_hi:[1,0] neg_hi:[0,1]
	v_pk_add_f32 v[110:111], v[104:105], v[120:121] op_sel:[0,1] op_sel_hi:[1,0] neg_lo:[0,1]
	v_pk_add_f32 v[118:119], v[112:113], v[128:129]
	v_pk_add_f32 v[126:127], v[112:113], v[128:129] neg_lo:[0,1] neg_hi:[0,1]
	v_pk_add_f32 v[104:105], v[102:103], v[118:119]
	v_pk_add_f32 v[120:121], v[102:103], v[118:119] neg_lo:[0,1] neg_hi:[0,1]
	v_pk_add_f32 v[112:113], v[110:111], v[126:127] op_sel:[0,1] op_sel_hi:[1,0] neg_hi:[0,1]
	v_pk_add_f32 v[128:129], v[110:111], v[126:127] op_sel:[0,1] op_sel_hi:[1,0] neg_lo:[0,1]
	v_pk_add_f32 v[188:189], v[106:107], v[122:123]
	v_pk_add_f32 v[186:187], v[106:107], v[122:123] neg_lo:[0,1] neg_hi:[0,1]
	v_pk_add_f32 v[168:169], v[114:115], v[130:131]
	v_pk_add_f32 v[184:185], v[114:115], v[130:131] neg_lo:[0,1] neg_hi:[0,1]
	v_pk_add_f32 v[106:107], v[188:189], v[168:169]
	v_pk_add_f32 v[122:123], v[188:189], v[168:169] neg_lo:[0,1] neg_hi:[0,1]
	v_pk_add_f32 v[114:115], v[186:187], v[184:185] op_sel:[0,1] op_sel_hi:[1,0] neg_hi:[0,1]
	v_pk_add_f32 v[130:131], v[186:187], v[184:185] op_sel:[0,1] op_sel_hi:[1,0] neg_lo:[0,1]
	ds_write_b64 v3, v[100:101]
	v_pk_mul_f32 v[180:181], v[178:179], v[6:7] op_sel:[1,1] op_sel_hi:[0,1]
	v_pk_fma_f32 v[182:183], v[178:179], v[6:7], v[180:181] op_sel_hi:[1,0,1] neg_lo:[0,0,1]
	ds_write_b64 v3, v[182:183] offset:4224
	v_pk_mul_f32 v[110:111], v[104:105], v[8:9] op_sel:[1,1] op_sel_hi:[0,1]
	v_pk_fma_f32 v[102:103], v[104:105], v[8:9], v[110:111] op_sel_hi:[1,0,1] neg_lo:[0,0,1]
	ds_write_b64 v3, v[102:103] offset:8448
	v_pk_mul_f32 v[126:127], v[106:107], v[10:11] op_sel:[1,1] op_sel_hi:[0,1]
	v_pk_fma_f32 v[118:119], v[106:107], v[10:11], v[126:127] op_sel_hi:[1,0,1] neg_lo:[0,0,1]
	ds_write_b64 v3, v[118:119] offset:12672
	v_pk_mul_f32 v[186:187], v[108:109], v[12:13] op_sel:[1,1] op_sel_hi:[0,1]
	v_pk_fma_f32 v[188:189], v[108:109], v[12:13], v[186:187] op_sel_hi:[1,0,1] neg_lo:[0,0,1]
	ds_write_b64 v3, v[188:189] offset:16896
	v_pk_mul_f32 v[184:185], v[176:177], v[14:15] op_sel:[1,1] op_sel_hi:[0,1]
	v_pk_fma_f32 v[168:169], v[176:177], v[14:15], v[184:185] op_sel_hi:[1,0,1] neg_lo:[0,0,1]
	ds_write_b64 v3, v[168:169] offset:21120
	v_pk_mul_f32 v[182:183], v[112:113], v[16:17] op_sel:[1,1] op_sel_hi:[0,1]
	v_pk_fma_f32 v[180:181], v[112:113], v[16:17], v[182:183] op_sel_hi:[1,0,1] neg_lo:[0,0,1]
	ds_write_b64 v3, v[180:181] offset:25344
	v_pk_mul_f32 v[102:103], v[114:115], v[18:19] op_sel:[1,1] op_sel_hi:[0,1]
	v_pk_fma_f32 v[110:111], v[114:115], v[18:19], v[102:103] op_sel_hi:[1,0,1] neg_lo:[0,0,1]
	ds_write_b64 v3, v[110:111] offset:29568
	v_pk_mul_f32 v[118:119], v[116:117], v[20:21] op_sel:[1,1] op_sel_hi:[0,1]
	v_pk_fma_f32 v[126:127], v[116:117], v[20:21], v[118:119] op_sel_hi:[1,0,1] neg_lo:[0,0,1]
	ds_write_b64 v3, v[126:127] offset:33792
	v_pk_mul_f32 v[188:189], v[166:167], v[22:23] op_sel:[1,1] op_sel_hi:[0,1]
	v_pk_fma_f32 v[186:187], v[166:167], v[22:23], v[188:189] op_sel_hi:[1,0,1] neg_lo:[0,0,1]
	ds_write_b64 v3, v[186:187] offset:38016
	v_pk_mul_f32 v[168:169], v[120:121], v[24:25] op_sel:[1,1] op_sel_hi:[0,1]
	v_pk_fma_f32 v[184:185], v[120:121], v[24:25], v[168:169] op_sel_hi:[1,0,1] neg_lo:[0,0,1]
	ds_write_b64 v3, v[184:185] offset:42240
	v_pk_mul_f32 v[180:181], v[122:123], v[26:27] op_sel:[1,1] op_sel_hi:[0,1]
	v_pk_fma_f32 v[182:183], v[122:123], v[26:27], v[180:181] op_sel_hi:[1,0,1] neg_lo:[0,0,1]
	ds_write_b64 v3, v[182:183] offset:46464
	v_pk_mul_f32 v[110:111], v[124:125], v[28:29] op_sel:[1,1] op_sel_hi:[0,1]
	v_pk_fma_f32 v[102:103], v[124:125], v[28:29], v[110:111] op_sel_hi:[1,0,1] neg_lo:[0,0,1]
	ds_write_b64 v3, v[102:103] offset:50688
	v_pk_mul_f32 v[126:127], v[174:175], v[30:31] op_sel:[1,1] op_sel_hi:[0,1]
	v_pk_fma_f32 v[118:119], v[174:175], v[30:31], v[126:127] op_sel_hi:[1,0,1] neg_lo:[0,0,1]
	ds_write_b64 v3, v[118:119] offset:54912
	v_pk_mul_f32 v[186:187], v[128:129], v[32:33] op_sel:[1,1] op_sel_hi:[0,1]
	v_pk_fma_f32 v[188:189], v[128:129], v[32:33], v[186:187] op_sel_hi:[1,0,1] neg_lo:[0,0,1]
	ds_write_b64 v3, v[188:189] offset:59136
	v_pk_mul_f32 v[184:185], v[130:131], v[34:35] op_sel:[1,1] op_sel_hi:[0,1]
	v_pk_fma_f32 v[168:169], v[130:131], v[34:35], v[184:185] op_sel_hi:[1,0,1] neg_lo:[0,0,1]
	ds_write_b64 v3, v[168:169] offset:63360
	s_waitcnt lgkmcnt(0)
	s_barrier
	s_cbranch_vccz .Lhfft_st5
	s_sleep 16
; #define LAS __attribute__((address_space(3)))
; __device__ __forceinline__ f32x2 cmul(f32x2 a, f32x2 b) { return (f32x2){a.x * b.x - a.y * b.y, a.x * b.y + a.y * b.x}; }
; __device__ __forceinline__ void fft_fwd2(LAS f32x2* B, const LAS f32x2* TW2, int tid) {
;     asm volatile("" : "+v"(tid));
;     const int b = tid >> 5, n2 = tid & 31, base = 512 * b + n2; f32x2 x[16];
; #pragma unroll
;     for (int r = 0; r < 16; ++r) x[r] = B[fpad(base + 32 * r)];
;     dft16<false>(x);
;     B[fpad(base)] = x[0];
; #pragma unroll
;     for (int k = 1; k < 16; ++k) B[fpad(base + 32 * k)] = cmul(x[k], TW2[k * 32 + n2]);
; }
.Lhfft_st5:
	ds_read_b64 v[100:101], v5
	ds_read_b64 v[108:109], v5 offset:1056
	ds_read_b64 v[116:117], v5 offset:2112
	ds_read_b64 v[124:125], v5 offset:3168
	ds_read_b64 v[178:179], v5 offset:264
	ds_read_b64 v[176:177], v5 offset:1320
	ds_read_b64 v[166:167], v5 offset:2376
	ds_read_b64 v[174:175], v5 offset:3432
	ds_read_b64 v[104:105], v5 offset:528
	ds_read_b64 v[112:113], v5 offset:1584
	ds_read_b64 v[120:121], v5 offset:2640
	ds_read_b64 v[128:129], v5 offset:3696
	s_waitcnt lgkmcnt(8)
	ds_read_b64 v[106:107], v5 offset:792
	ds_read_b64 v[114:115], v5 offset:1848
	ds_read_b64 v[122:123], v5 offset:2904
	ds_read_b64 v[130:131], v5 offset:3960
	v_pk_add_f32 v[180:181], v[100:101], v[116:117]
	v_pk_add_f32 v[182:183], v[100:101], v[116:117] neg_lo:[0,1] neg_hi:[0,1]
	v_pk_add_f32 v[110:111], v[108:109], v[124:125]
	v_pk_add_f32 v[102:103], v[108:109], v[124:125] neg_lo:[0,1] neg_hi:[0,1]
	v_pk_add_f32 v[100:101], v[180:181], v[110:111]
	v_pk_add_f32 v[116:117], v[180:181], v[110:111] neg_lo:[0,1] neg_hi:[0,1]
	v_pk_add_f32 v[108:109], v[182:183], v[102:103] op_sel:[0,1] op_sel_hi:[1,0] neg_hi:[0,1]
	v_pk_add_f32 v[124:125], v[182:183], v[102:103] op_sel:[0,1] op_sel_hi:[1,0] neg_lo:[0,1]
	s_waitcnt lgkmcnt(9)
	v_pk_add_f32 v[126:127], v[178:179], v[166:167]
	v_pk_add_f32 v[118:119], v[178:179], v[166:167] neg_lo:[0,1] neg_hi:[0,1]
	s_waitcnt lgkmcnt(8)
	v_pk_add_f32 v[186:187], v[176:177], v[174:175]
	v_pk_add_f32 v[188:189], v[176:177], v[174:175] neg_lo:[0,1] neg_hi:[0,1]
	v_pk_add_f32 v[178:179], v[126:127], v[186:187]
	v_pk_add_f32 v[166:167], v[126:127], v[186:187] neg_lo:[0,1] neg_hi:[0,1]
	v_pk_add_f32 v[176:177], v[118:119], v[188:189] op_sel:[0,1] op_sel_hi:[1,0] neg_hi:[0,1]
	v_pk_add_f32 v[174:175], v[118:119], v[188:189] op_sel:[0,1] op_sel_hi:[1,0] neg_lo:[0,1]
	s_waitcnt lgkmcnt(5)
	v_pk_add_f32 v[184:185], v[104:105], v[120:121]
	v_pk_add_f32 v[168:169], v[104:105], v[120:121] neg_lo:[0,1] neg_hi:[0,1]
	s_waitcnt lgkmcnt(4)
	v_pk_add_f32 v[180:181], v[112:113], v[128:129]
	v_pk_add_f32 v[182:183], v[112:113], v[128:129] neg_lo:[0,1] neg_hi:[0,1]
	v_pk_add_f32 v[104:105], v[184:185], v[180:181]
	v_pk_add_f32 v[120:121], v[184:185], v[180:181] neg_lo:[0,1] neg_hi:[0,1]
	v_pk_add_f32 v[112:113], v[168:169], v[182:183] op_sel:[0,1] op_sel_hi:[1,0] neg_hi:[0,1]
	v_pk_add_f32 v[128:129], v[168:169], v[182:183] op_sel:[0,1] op_sel_hi:[1,0] neg_lo:[0,1]
	s_waitcnt lgkmcnt(1)
	v_pk_add_f32 v[110:111], v[106:107], v[122:123]
	v_pk_add_f32 v[102:103], v[106:107], v[122:123] neg_lo:[0,1] neg_hi:[0,1]
	s_waitcnt lgkmcnt(0)
	v_pk_add_f32 v[126:127], v[114:115], v[130:131]
	v_pk_add_f32 v[118:119], v[114:115], v[130:131] neg_lo:[0,1] neg_hi:[0,1]
	v_pk_add_f32 v[106:107], v[110:111], v[126:127]
	v_pk_add_f32 v[122:123], v[110:111], v[126:127] neg_lo:[0,1] neg_hi:[0,1]
	v_pk_add_f32 v[114:115], v[102:103], v[118:119] op_sel:[0,1] op_sel_hi:[1,0] neg_hi:[0,1]
	v_pk_add_f32 v[130:131], v[102:103], v[118:119] op_sel:[0,1] op_sel_hi:[1,0] neg_lo:[0,1]
	v_pk_mul_f32 v[186:187], v[176:177], s[68:69] op_sel:[1,1] op_sel_hi:[0,1]
	v_pk_fma_f32 v[176:177], v[176:177], s[68:69], v[186:187] op_sel_hi:[1,0,1] neg_lo:[0,0,1]
	v_pk_mul_f32 v[188:189], v[112:113], s[84:85] op_sel:[1,1] op_sel_hi:[0,1]
	v_pk_fma_f32 v[112:113], v[112:113], s[84:85], v[188:189] op_sel_hi:[1,0,1] neg_lo:[0,0,1]
	v_pk_mul_f32 v[184:185], v[114:115], s[88:89] op_sel:[1,1] op_sel_hi:[0,1]
	v_pk_fma_f32 v[114:115], v[114:115], s[88:89], v[184:185] op_sel_hi:[1,0,1] neg_lo:[0,0,1]
	v_pk_mul_f32 v[168:169], v[166:167], s[84:85] op_sel:[1,1] op_sel_hi:[0,1]
	v_pk_fma_f32 v[166:167], v[166:167], s[84:85], v[168:169] op_sel_hi:[1,0,1] neg_lo:[0,0,1]
	v_pk_mul_f32 v[180:181], v[122:123], s[90:91] op_sel:[1,1] op_sel_hi:[0,1]
	v_pk_fma_f32 v[122:123], v[122:123], s[90:91], v[180:181] op_sel_hi:[1,0,1] neg_lo:[0,0,1]
	v_pk_mul_f32 v[182:183], v[174:175], s[88:89] op_sel:[1,1] op_sel_hi:[0,1]
	v_pk_fma_f32 v[174:175], v[174:175], s[88:89], v[182:183] op_sel_hi:[1,0,1] neg_lo:[0,0,1]
	v_pk_mul_f32 v[110:111], v[128:129], s[90:91] op_sel:[1,1] op_sel_hi:[0,1]
	v_pk_fma_f32 v[128:129], v[128:129], s[90:91], v[110:111] op_sel_hi:[1,0,1] neg_lo:[0,0,1]
	v_pk_mul_f32 v[102:103], v[130:131], s[98:99] op_sel:[1,1] op_sel_hi:[0,1]
	v_pk_fma_f32 v[130:131], v[130:131], s[98:99], v[102:103] op_sel_hi:[1,0,1] neg_lo:[0,0,1]
	v_pk_add_f32 v[126:127], v[100:101], v[104:105]
	v_pk_add_f32 v[118:119], v[100:101], v[104:105] neg_lo:[0,1] neg_hi:[0,1]
	v_pk_add_f32 v[186:187], v[178:179], v[106:107]
	v_pk_add_f32 v[188:189], v[178:179], v[106:107] neg_lo:[0,1] neg_hi:[0,1]
	v_pk_add_f32 v[100:101], v[126:127], v[186:187]
	v_pk_add_f32 v[104:105], v[126:127], v[186:187] neg_lo:[0,1] neg_hi:[0,1]
	v_pk_add_f32 v[178:179], v[118:119], v[188:189] op_sel:[0,1] op_sel_hi:[1,0] neg_hi:[0,1]
	v_pk_add_f32 v[106:107], v[118:119], v[188:189] op_sel:[0,1] op_sel_hi:[1,0] neg_lo:[0,1]
	v_pk_add_f32 v[184:185], v[108:109], v[112:113]
	v_pk_add_f32 v[168:169], v[108:109], v[112:113] neg_lo:[0,1] neg_hi:[0,1]
	v_pk_add_f32 v[180:181], v[176:177], v[114:115]
	v_pk_add_f32 v[182:183], v[176:177], v[114:115] neg_lo:[0,1] neg_hi:[0,1]
	v_pk_add_f32 v[108:109], v[184:185], v[180:181]
	v_pk_add_f32 v[112:113], v[184:185], v[180:181] neg_lo:[0,1] neg_hi:[0,1]
	v_pk_add_f32 v[176:177], v[168:169], v[182:183] op_sel:[0,1] op_sel_hi:[1,0] neg_hi:[0,1]
	v_pk_add_f32 v[114:115], v[168:169], v[182:183] op_sel:[0,1] op_sel_hi:[1,0] neg_lo:[0,1]
	v_pk_add_f32 v[110:111], v[116:117], v[120:121] op_sel:[0,1] op_sel_hi:[1,0] neg_hi:[0,1]
	v_pk_add_f32 v[102:103], v[116:117], v[120:121] op_sel:[0,1] op_sel_hi:[1,0] neg_lo:[0,1]
	v_pk_add_f32 v[126:127], v[166:167], v[122:123]
	v_pk_add_f32 v[118:119], v[166:167], v[122:123] neg_lo:[0,1] neg_hi:[0,1]
	v_pk_add_f32 v[116:117], v[110:111], v[126:127]
	v_pk_add_f32 v[120:121], v[110:111], v[126:127] neg_lo:[0,1] neg_hi:[0,1]
	v_pk_add_f32 v[166:167], v[102:103], v[118:119] op_sel:[0,1] op_sel_hi:[1,0] neg_hi:[0,1]
	v_pk_add_f32 v[122:123], v[102:103], v[118:119] op_sel:[0,1] op_sel_hi:[1,0] neg_lo:[0,1]
	v_pk_add_f32 v[186:187], v[124:125], v[128:129]
	v_pk_add_f32 v[188:189], v[124:125], v[128:129] neg_lo:[0,1] neg_hi:[0,1]
	v_pk_add_f32 v[184:185], v[174:175], v[130:131]
	v_pk_add_f32 v[168:169], v[174:175], v[130:131] neg_lo:[0,1] neg_hi:[0,1]
	v_pk_add_f32 v[124:125], v[186:187], v[184:185]
	v_pk_add_f32 v[128:129], v[186:187], v[184:185] neg_lo:[0,1] neg_hi:[0,1]
	v_pk_add_f32 v[174:175], v[188:189], v[168:169] op_sel:[0,1] op_sel_hi:[1,0] neg_hi:[0,1]
	v_pk_add_f32 v[130:131], v[188:189], v[168:169] op_sel:[0,1] op_sel_hi:[1,0] neg_lo:[0,1]
	ds_write_b64 v5, v[100:101]
	ds_read_b64 v[180:181], v56 offset:256
	ds_read_b64 v[182:183], v56 offset:512
	ds_read_b64 v[110:111], v56 offset:768
	ds_read_b64 v[102:103], v56 offset:1024
	s_waitcnt lgkmcnt(3)
; #define LAS __attribute__((address_space(3)))
; __device__ __forceinline__ f32x2 cmul(f32x2 a, f32x2 b) { return (f32x2){a.x * b.x - a.y * b.y, a.x * b.y + a.y * b.x}; }
; __device__ __forceinline__ void fft_fwd2(LAS f32x2* B, const LAS f32x2* TW2, int tid) {
;     ...
;     B[fpad(base)] = x[0];
; #pragma unroll
;     for (int k = 1; k < 16; ++k) B[fpad(base + 32 * k)] = cmul(x[k], TW2[k * 32 + n2]);
; template <int MODE> __device__ __forceinline__ void fft_pair32(LAS f32x2* B, const LAS f32x2* F, int wave, int lane) {
;     ...
;     const int hi = lane >> 5, blk = 32 * wave + (lane & 31); const float sg = hi ? -1.f : 1.f;
;     LAS f32x2* p = B + 33 * blk; f32x2 v[16];
; #pragma unroll
;     for (int j = 0; j < 16; ++j) { const f32x2 d = p[j] + p[j + 16] * sg;
;         const f32x2 w = {hi ? CS[j] : 1.f, hi ? -SN[j] : 0.f}; v[j] = j == 0 ? d : cmul(d, w); }
;     dft16<false>(v);
	v_pk_mul_f32 v[126:127], v[108:109], v[180:181] op_sel:[1,1] op_sel_hi:[0,1]
	v_pk_fma_f32 v[108:109], v[108:109], v[180:181], v[126:127] op_sel_hi:[1,0,1] neg_lo:[0,0,1]
	ds_write_b64 v5, v[108:109] offset:264
	s_waitcnt lgkmcnt(3)
	v_pk_mul_f32 v[118:119], v[116:117], v[182:183] op_sel:[1,1] op_sel_hi:[0,1]
	v_pk_fma_f32 v[116:117], v[116:117], v[182:183], v[118:119] op_sel_hi:[1,0,1] neg_lo:[0,0,1]
	ds_write_b64 v5, v[116:117] offset:528
	s_waitcnt lgkmcnt(3)
	v_pk_mul_f32 v[186:187], v[124:125], v[110:111] op_sel:[1,1] op_sel_hi:[0,1]
	v_pk_fma_f32 v[124:125], v[124:125], v[110:111], v[186:187] op_sel_hi:[1,0,1] neg_lo:[0,0,1]
	ds_write_b64 v5, v[124:125] offset:792
	s_waitcnt lgkmcnt(3)
	v_pk_mul_f32 v[188:189], v[178:179], v[102:103] op_sel:[1,1] op_sel_hi:[0,1]
	v_pk_fma_f32 v[178:179], v[178:179], v[102:103], v[188:189] op_sel_hi:[1,0,1] neg_lo:[0,0,1]
	ds_write_b64 v5, v[178:179] offset:1056
	ds_read_b64 v[184:185], v56 offset:1280
	ds_read_b64 v[168:169], v56 offset:1536
	ds_read_b64 v[126:127], v56 offset:1792
	ds_read_b64 v[118:119], v56 offset:2048
	s_waitcnt lgkmcnt(3)
	v_pk_mul_f32 v[186:187], v[176:177], v[184:185] op_sel:[1,1] op_sel_hi:[0,1]
	v_pk_fma_f32 v[176:177], v[176:177], v[184:185], v[186:187] op_sel_hi:[1,0,1] neg_lo:[0,0,1]
	ds_write_b64 v5, v[176:177] offset:1320
	s_waitcnt lgkmcnt(3)
	v_pk_mul_f32 v[188:189], v[166:167], v[168:169] op_sel:[1,1] op_sel_hi:[0,1]
	v_pk_fma_f32 v[166:167], v[166:167], v[168:169], v[188:189] op_sel_hi:[1,0,1] neg_lo:[0,0,1]
	ds_write_b64 v5, v[166:167] offset:1584
	s_waitcnt lgkmcnt(3)
	v_pk_mul_f32 v[180:181], v[174:175], v[126:127] op_sel:[1,1] op_sel_hi:[0,1]
	v_pk_fma_f32 v[174:175], v[174:175], v[126:127], v[180:181] op_sel_hi:[1,0,1] neg_lo:[0,0,1]
	ds_write_b64 v5, v[174:175] offset:1848
	s_waitcnt lgkmcnt(3)
	v_pk_mul_f32 v[182:183], v[104:105], v[118:119] op_sel:[1,1] op_sel_hi:[0,1]
	v_pk_fma_f32 v[104:105], v[104:105], v[118:119], v[182:183] op_sel_hi:[1,0,1] neg_lo:[0,0,1]
	ds_write_b64 v5, v[104:105] offset:2112
	ds_read_b64 v[110:111], v56 offset:2304
	ds_read_b64 v[102:103], v56 offset:2560
	ds_read_b64 v[186:187], v56 offset:2816
	ds_read_b64 v[188:189], v56 offset:3072
	s_waitcnt lgkmcnt(3)
	v_pk_mul_f32 v[180:181], v[112:113], v[110:111] op_sel:[1,1] op_sel_hi:[0,1]
	v_pk_fma_f32 v[112:113], v[112:113], v[110:111], v[180:181] op_sel_hi:[1,0,1] neg_lo:[0,0,1]
	ds_write_b64 v5, v[112:113] offset:2376
	s_waitcnt lgkmcnt(3)
	v_pk_mul_f32 v[182:183], v[120:121], v[102:103] op_sel:[1,1] op_sel_hi:[0,1]
	v_pk_fma_f32 v[120:121], v[120:121], v[102:103], v[182:183] op_sel_hi:[1,0,1] neg_lo:[0,0,1]
	ds_write_b64 v5, v[120:121] offset:2640
	s_waitcnt lgkmcnt(3)
	v_pk_mul_f32 v[184:185], v[128:129], v[186:187] op_sel:[1,1] op_sel_hi:[0,1]
	v_pk_fma_f32 v[128:129], v[128:129], v[186:187], v[184:185] op_sel_hi:[1,0,1] neg_lo:[0,0,1]
	ds_write_b64 v5, v[128:129] offset:2904
	s_waitcnt lgkmcnt(3)
	v_pk_mul_f32 v[168:169], v[106:107], v[188:189] op_sel:[1,1] op_sel_hi:[0,1]
	v_pk_fma_f32 v[106:107], v[106:107], v[188:189], v[168:169] op_sel_hi:[1,0,1] neg_lo:[0,0,1]
	ds_write_b64 v5, v[106:107] offset:3168
	ds_read_b64 v[126:127], v56 offset:3328
	ds_read_b64 v[118:119], v56 offset:3584
	ds_read_b64 v[180:181], v56 offset:3840
	s_waitcnt lgkmcnt(2)
	v_pk_mul_f32 v[182:183], v[114:115], v[126:127] op_sel:[1,1] op_sel_hi:[0,1]
	v_pk_fma_f32 v[114:115], v[114:115], v[126:127], v[182:183] op_sel_hi:[1,0,1] neg_lo:[0,0,1]
	ds_write_b64 v5, v[114:115] offset:3432
	s_waitcnt lgkmcnt(2)
	v_pk_mul_f32 v[184:185], v[122:123], v[118:119] op_sel:[1,1] op_sel_hi:[0,1]
	v_pk_fma_f32 v[122:123], v[122:123], v[118:119], v[184:185] op_sel_hi:[1,0,1] neg_lo:[0,0,1]
	ds_write_b64 v5, v[122:123] offset:3696
	s_waitcnt lgkmcnt(2)
	v_pk_mul_f32 v[168:169], v[130:131], v[180:181] op_sel:[1,1] op_sel_hi:[0,1]
	v_pk_fma_f32 v[130:131], v[130:131], v[180:181], v[168:169] op_sel_hi:[1,0,1] neg_lo:[0,0,1]
	ds_write_b64 v5, v[130:131] offset:3960
	s_waitcnt lgkmcnt(0)
	ds_read_b64 v[100:101], v156
	ds_read_b64 v[110:111], v156 offset:128
	ds_read_b64 v[108:109], v156 offset:8
	ds_read_b64 v[102:103], v156 offset:136
	ds_read_b64 v[116:117], v156 offset:16
	ds_read_b64 v[186:187], v156 offset:144
	ds_read_b64 v[124:125], v156 offset:24
	ds_read_b64 v[188:189], v156 offset:152
	s_waitcnt lgkmcnt(6)
	v_pk_fma_f32 v[100:101], v[110:111], v[190:191], v[100:101] op_sel_hi:[1,0,1]
	s_waitcnt lgkmcnt(4)
	v_pk_fma_f32 v[108:109], v[102:103], v[190:191], v[108:109] op_sel_hi:[1,0,1]
	v_pk_mul_f32 v[182:183], v[108:109], v[36:37] op_sel:[1,1] op_sel_hi:[0,1]
	v_pk_fma_f32 v[108:109], v[108:109], v[36:37], v[182:183] op_sel_hi:[1,0,1] neg_lo:[0,0,1]
	s_waitcnt lgkmcnt(2)
	v_pk_fma_f32 v[116:117], v[186:187], v[190:191], v[116:117] op_sel_hi:[1,0,1]
	v_pk_mul_f32 v[184:185], v[116:117], v[38:39] op_sel:[1,1] op_sel_hi:[0,1]
	v_pk_fma_f32 v[116:117], v[116:117], v[38:39], v[184:185] op_sel_hi:[1,0,1] neg_lo:[0,0,1]
	s_waitcnt lgkmcnt(0)
	v_pk_fma_f32 v[124:125], v[188:189], v[190:191], v[124:125] op_sel_hi:[1,0,1]
	v_pk_mul_f32 v[168:169], v[124:125], v[40:41] op_sel:[1,1] op_sel_hi:[0,1]
	v_pk_fma_f32 v[124:125], v[124:125], v[40:41], v[168:169] op_sel_hi:[1,0,1] neg_lo:[0,0,1]
	ds_read_b64 v[178:179], v156 offset:32
	ds_read_b64 v[126:127], v156 offset:160
	ds_read_b64 v[176:177], v156 offset:40
	ds_read_b64 v[118:119], v156 offset:168
	ds_read_b64 v[166:167], v156 offset:48
	ds_read_b64 v[180:181], v156 offset:176
	ds_read_b64 v[174:175], v156 offset:56
	ds_read_b64 v[182:183], v156 offset:184
	s_waitcnt lgkmcnt(6)
; __device__ __forceinline__ f32x2 cmul(f32x2 a, f32x2 b) { return (f32x2){a.x * b.x - a.y * b.y, a.x * b.y + a.y * b.x}; }
; template <bool INV> __device__ __forceinline__ f32x2 cmul_tw(f32x2 a, f32x2 w) { return INV ? cmulc(a, w) : cmul(a, w); }
; template <bool INV> __device__ __forceinline__ void dft16(f32x2 (&x)[16]) {
;     constexpr float C1 = 0.92387953251128674f, S1 = 0.38268343236508977f, C2 = 0.70710678118654752f;
; #pragma unroll
;     for (int b = 0; b < 4; ++b) dft4<INV>(x[b], x[4 + b], x[8 + b], x[12 + b]);
;     const f32x2 w1 = {C1, -S1}, w2 = {C2, -C2}, w3 = {S1, -C1}, w4 = {0.f, -1.f}, w6 = {-C2, -C2}, w9 = {-C1, S1};
;     x[4 * 1 + 1] = cmul_tw<INV>(x[5], w1); x[4 * 1 + 2] = cmul_tw<INV>(x[6], w2); x[4 * 1 + 3] = cmul_tw<INV>(x[7], w3);
;     x[4 * 2 + 1] = cmul_tw<INV>(x[9], w2); x[4 * 2 + 2] = cmul_tw<INV>(x[10], w4); x[4 * 2 + 3] = cmul_tw<INV>(x[11], w6);
;     x[4 * 3 + 1] = cmul_tw<INV>(x[13], w3); x[4 * 3 + 2] = cmul_tw<INV>(x[14], w6); x[4 * 3 + 3] = cmul_tw<INV>(x[15], w9);
; #pragma unroll
;     for (int c = 0; c < 4; ++c) dft4<INV>(x[4 * c], x[4 * c + 1], x[4 * c + 2], x[4 * c + 3]);
; template <int MODE> __device__ __forceinline__ void fft_pair32(LAS f32x2* B, const LAS f32x2* F, int wave, int lane) {
;     ...
;     for (int j = 0; j < 16; ++j) { const f32x2 d = p[j] + p[j + 16] * sg;
;         const f32x2 w = {hi ? CS[j] : 1.f, hi ? -SN[j] : 0.f}; v[j] = j == 0 ? d : cmul(d, w); }
;     dft16<false>(v);
	v_pk_fma_f32 v[178:179], v[126:127], v[190:191], v[178:179] op_sel_hi:[1,0,1]
	v_pk_mul_f32 v[184:185], v[178:179], v[42:43] op_sel:[1,1] op_sel_hi:[0,1]
	v_pk_fma_f32 v[178:179], v[178:179], v[42:43], v[184:185] op_sel_hi:[1,0,1] neg_lo:[0,0,1]
	s_waitcnt lgkmcnt(4)
	v_pk_fma_f32 v[176:177], v[118:119], v[190:191], v[176:177] op_sel_hi:[1,0,1]
	v_pk_mul_f32 v[168:169], v[176:177], v[44:45] op_sel:[1,1] op_sel_hi:[0,1]
	v_pk_fma_f32 v[176:177], v[176:177], v[44:45], v[168:169] op_sel_hi:[1,0,1] neg_lo:[0,0,1]
	s_waitcnt lgkmcnt(2)
	v_pk_fma_f32 v[166:167], v[180:181], v[190:191], v[166:167] op_sel_hi:[1,0,1]
	v_pk_mul_f32 v[110:111], v[166:167], v[46:47] op_sel:[1,1] op_sel_hi:[0,1]
	v_pk_fma_f32 v[166:167], v[166:167], v[46:47], v[110:111] op_sel_hi:[1,0,1] neg_lo:[0,0,1]
	s_waitcnt lgkmcnt(0)
	v_pk_fma_f32 v[174:175], v[182:183], v[190:191], v[174:175] op_sel_hi:[1,0,1]
	v_pk_mul_f32 v[102:103], v[174:175], v[48:49] op_sel:[1,1] op_sel_hi:[0,1]
	v_pk_fma_f32 v[174:175], v[174:175], v[48:49], v[102:103] op_sel_hi:[1,0,1] neg_lo:[0,0,1]
	ds_read_b64 v[104:105], v156 offset:64
	ds_read_b64 v[186:187], v156 offset:192
	ds_read_b64 v[112:113], v156 offset:72
	ds_read_b64 v[188:189], v156 offset:200
	ds_read_b64 v[120:121], v156 offset:80
	ds_read_b64 v[184:185], v156 offset:208
	ds_read_b64 v[128:129], v156 offset:88
	ds_read_b64 v[168:169], v156 offset:216
	s_waitcnt lgkmcnt(6)
	v_pk_fma_f32 v[104:105], v[186:187], v[190:191], v[104:105] op_sel_hi:[1,0,1]
	v_pk_mul_f32 v[110:111], v[104:105], v[50:51] op_sel:[1,1] op_sel_hi:[0,1]
	v_pk_fma_f32 v[104:105], v[104:105], v[50:51], v[110:111] op_sel_hi:[1,0,1] neg_lo:[0,0,1]
	s_waitcnt lgkmcnt(4)
	v_pk_fma_f32 v[112:113], v[188:189], v[190:191], v[112:113] op_sel_hi:[1,0,1]
	v_pk_mul_f32 v[102:103], v[112:113], v[52:53] op_sel:[1,1] op_sel_hi:[0,1]
	v_pk_fma_f32 v[112:113], v[112:113], v[52:53], v[102:103] op_sel_hi:[1,0,1] neg_lo:[0,0,1]
	s_waitcnt lgkmcnt(2)
	v_pk_fma_f32 v[120:121], v[184:185], v[190:191], v[120:121] op_sel_hi:[1,0,1]
	v_pk_mul_f32 v[126:127], v[120:121], v[54:55] op_sel:[1,1] op_sel_hi:[0,1]
	v_pk_fma_f32 v[120:121], v[120:121], v[54:55], v[126:127] op_sel_hi:[1,0,1] neg_lo:[0,0,1]
	s_waitcnt lgkmcnt(0)
	v_pk_fma_f32 v[128:129], v[168:169], v[190:191], v[128:129] op_sel_hi:[1,0,1]
	v_pk_mul_f32 v[118:119], v[128:129], v[90:91] op_sel:[1,1] op_sel_hi:[0,1]
	v_pk_fma_f32 v[128:129], v[128:129], v[90:91], v[118:119] op_sel_hi:[1,0,1] neg_lo:[0,0,1]
	ds_read_b64 v[106:107], v156 offset:96
	ds_read_b64 v[180:181], v156 offset:224
	ds_read_b64 v[114:115], v156 offset:104
	ds_read_b64 v[182:183], v156 offset:232
	ds_read_b64 v[122:123], v156 offset:112
	ds_read_b64 v[110:111], v156 offset:240
	ds_read_b64 v[130:131], v156 offset:120
	ds_read_b64 v[102:103], v156 offset:248
	s_waitcnt lgkmcnt(6)
	v_pk_fma_f32 v[106:107], v[180:181], v[190:191], v[106:107] op_sel_hi:[1,0,1]
	v_pk_mul_f32 v[126:127], v[106:107], v[92:93] op_sel:[1,1] op_sel_hi:[0,1]
	v_pk_fma_f32 v[106:107], v[106:107], v[92:93], v[126:127] op_sel_hi:[1,0,1] neg_lo:[0,0,1]
	s_waitcnt lgkmcnt(4)
	v_pk_fma_f32 v[114:115], v[182:183], v[190:191], v[114:115] op_sel_hi:[1,0,1]
	v_pk_mul_f32 v[118:119], v[114:115], v[94:95] op_sel:[1,1] op_sel_hi:[0,1]
	v_pk_fma_f32 v[114:115], v[114:115], v[94:95], v[118:119] op_sel_hi:[1,0,1] neg_lo:[0,0,1]
	s_waitcnt lgkmcnt(2)
	v_pk_fma_f32 v[122:123], v[110:111], v[190:191], v[122:123] op_sel_hi:[1,0,1]
	v_pk_mul_f32 v[186:187], v[122:123], v[96:97] op_sel:[1,1] op_sel_hi:[0,1]
	v_pk_fma_f32 v[122:123], v[122:123], v[96:97], v[186:187] op_sel_hi:[1,0,1] neg_lo:[0,0,1]
	s_waitcnt lgkmcnt(0)
	v_pk_fma_f32 v[130:131], v[102:103], v[190:191], v[130:131] op_sel_hi:[1,0,1]
	v_pk_mul_f32 v[188:189], v[130:131], v[98:99] op_sel:[1,1] op_sel_hi:[0,1]
	v_pk_fma_f32 v[130:131], v[130:131], v[98:99], v[188:189] op_sel_hi:[1,0,1] neg_lo:[0,0,1]
	v_pk_add_f32 v[184:185], v[100:101], v[104:105]
	v_pk_add_f32 v[168:169], v[100:101], v[104:105] neg_lo:[0,1] neg_hi:[0,1]
	v_pk_add_f32 v[126:127], v[178:179], v[106:107]
	v_pk_add_f32 v[118:119], v[178:179], v[106:107] neg_lo:[0,1] neg_hi:[0,1]
	v_pk_add_f32 v[100:101], v[184:185], v[126:127]
	v_pk_add_f32 v[104:105], v[184:185], v[126:127] neg_lo:[0,1] neg_hi:[0,1]
	v_pk_add_f32 v[178:179], v[168:169], v[118:119] op_sel:[0,1] op_sel_hi:[1,0] neg_hi:[0,1]
	v_pk_add_f32 v[106:107], v[168:169], v[118:119] op_sel:[0,1] op_sel_hi:[1,0] neg_lo:[0,1]
	v_pk_add_f32 v[186:187], v[108:109], v[112:113]
	v_pk_add_f32 v[188:189], v[108:109], v[112:113] neg_lo:[0,1] neg_hi:[0,1]
	v_pk_add_f32 v[180:181], v[176:177], v[114:115]
	v_pk_add_f32 v[182:183], v[176:177], v[114:115] neg_lo:[0,1] neg_hi:[0,1]
	v_pk_add_f32 v[108:109], v[186:187], v[180:181]
	v_pk_add_f32 v[112:113], v[186:187], v[180:181] neg_lo:[0,1] neg_hi:[0,1]
	v_pk_add_f32 v[176:177], v[188:189], v[182:183] op_sel:[0,1] op_sel_hi:[1,0] neg_hi:[0,1]
	v_pk_add_f32 v[114:115], v[188:189], v[182:183] op_sel:[0,1] op_sel_hi:[1,0] neg_lo:[0,1]
	v_pk_add_f32 v[110:111], v[116:117], v[120:121]
	v_pk_add_f32 v[102:103], v[116:117], v[120:121] neg_lo:[0,1] neg_hi:[0,1]
	v_pk_add_f32 v[184:185], v[166:167], v[122:123]
	v_pk_add_f32 v[168:169], v[166:167], v[122:123] neg_lo:[0,1] neg_hi:[0,1]
	v_pk_add_f32 v[116:117], v[110:111], v[184:185]
	v_pk_add_f32 v[120:121], v[110:111], v[184:185] neg_lo:[0,1] neg_hi:[0,1]
	v_pk_add_f32 v[166:167], v[102:103], v[168:169] op_sel:[0,1] op_sel_hi:[1,0] neg_hi:[0,1]
	v_pk_add_f32 v[122:123], v[102:103], v[168:169] op_sel:[0,1] op_sel_hi:[1,0] neg_lo:[0,1]
	v_pk_add_f32 v[126:127], v[124:125], v[128:129]
	v_pk_add_f32 v[118:119], v[124:125], v[128:129] neg_lo:[0,1] neg_hi:[0,1]
; #define LAS __attribute__((address_space(3)))
; __device__ __forceinline__ f32x2 cmul(f32x2 a, f32x2 b) { return (f32x2){a.x * b.x - a.y * b.y, a.x * b.y + a.y * b.x}; }
; template <bool INV> __device__ __forceinline__ f32x2 cmul_tw(f32x2 a, f32x2 w) { return INV ? cmulc(a, w) : cmul(a, w); }
; template <bool INV> __device__ __forceinline__ void dft16(f32x2 (&x)[16]) {
;     ...
;     x[4 * 1 + 1] = cmul_tw<INV>(x[5], w1); x[4 * 1 + 2] = cmul_tw<INV>(x[6], w2); x[4 * 1 + 3] = cmul_tw<INV>(x[7], w3);
;     x[4 * 2 + 1] = cmul_tw<INV>(x[9], w2); x[4 * 2 + 2] = cmul_tw<INV>(x[10], w4); x[4 * 2 + 3] = cmul_tw<INV>(x[11], w6);
;     x[4 * 3 + 1] = cmul_tw<INV>(x[13], w3); x[4 * 3 + 2] = cmul_tw<INV>(x[14], w6); x[4 * 3 + 3] = cmul_tw<INV>(x[15], w9);
; #pragma unroll
;     for (int c = 0; c < 4; ++c) dft4<INV>(x[4 * c], x[4 * c + 1], x[4 * c + 2], x[4 * c + 3]);
; template <int MODE> __device__ __forceinline__ void fft_pair32(LAS f32x2* B, const LAS f32x2* F, int wave, int lane) {
;     ...
;     const int k1 = blk >> 4, k2 = blk & 15, kb1 = (16 - k1) & 15, b1 = k1 != 0 ? 1 : 0, kb2 = (16 - k2 - b1) & 15, b2 = (k2 != 0 || b1) ? 1 : 0;
;     const LAS f32x2* fa = F + 33 * blk; const LAS f32x2* fb = F + 33 * (16 * kb1 + kb2);
;     const LAS f32x2* fah = fa + hi; const LAS f32x2* fbh = fb + (1 - b2) - hi;
;     constexpr float SC = 1.0f / (2.0f * (float)FN);
; #pragma unroll
;     for (int k = 0; k < 16; ++k) { const f32x2 A = fah[2 * k]; f32x2 Bm = fbh[31 - 2 * k];
;         if (k == 0) { const f32x2 m0 = b2 ? fb[31] : fa[0]; Bm = hi ? Bm : m0; }
;         const f32x2 H = MODE == 0 ? (f32x2){(A.x + Bm.x) * SC, (A.y - Bm.y) * SC} : (f32x2){(A.y + Bm.y) * SC, (Bm.x - A.x) * SC};
;         v[k] = cmul(v[k], H); }
	v_pk_add_f32 v[186:187], v[174:175], v[130:131]
	v_pk_add_f32 v[188:189], v[174:175], v[130:131] neg_lo:[0,1] neg_hi:[0,1]
	v_pk_add_f32 v[124:125], v[126:127], v[186:187]
	v_pk_add_f32 v[128:129], v[126:127], v[186:187] neg_lo:[0,1] neg_hi:[0,1]
	v_pk_add_f32 v[174:175], v[118:119], v[188:189] op_sel:[0,1] op_sel_hi:[1,0] neg_hi:[0,1]
	v_pk_add_f32 v[130:131], v[118:119], v[188:189] op_sel:[0,1] op_sel_hi:[1,0] neg_lo:[0,1]
	v_pk_mul_f32 v[180:181], v[176:177], s[68:69] op_sel:[1,1] op_sel_hi:[0,1]
	v_pk_fma_f32 v[176:177], v[176:177], s[68:69], v[180:181] op_sel_hi:[1,0,1] neg_lo:[0,0,1]
	v_pk_mul_f32 v[182:183], v[166:167], s[84:85] op_sel:[1,1] op_sel_hi:[0,1]
	v_pk_fma_f32 v[166:167], v[166:167], s[84:85], v[182:183] op_sel_hi:[1,0,1] neg_lo:[0,0,1]
	v_pk_mul_f32 v[110:111], v[174:175], s[88:89] op_sel:[1,1] op_sel_hi:[0,1]
	v_pk_fma_f32 v[174:175], v[174:175], s[88:89], v[110:111] op_sel_hi:[1,0,1] neg_lo:[0,0,1]
	v_pk_mul_f32 v[102:103], v[112:113], s[84:85] op_sel:[1,1] op_sel_hi:[0,1]
	v_pk_fma_f32 v[112:113], v[112:113], s[84:85], v[102:103] op_sel_hi:[1,0,1] neg_lo:[0,0,1]
	v_pk_mul_f32 v[184:185], v[128:129], s[90:91] op_sel:[1,1] op_sel_hi:[0,1]
	v_pk_fma_f32 v[128:129], v[128:129], s[90:91], v[184:185] op_sel_hi:[1,0,1] neg_lo:[0,0,1]
	v_pk_mul_f32 v[168:169], v[114:115], s[88:89] op_sel:[1,1] op_sel_hi:[0,1]
	v_pk_fma_f32 v[114:115], v[114:115], s[88:89], v[168:169] op_sel_hi:[1,0,1] neg_lo:[0,0,1]
	v_pk_mul_f32 v[126:127], v[122:123], s[90:91] op_sel:[1,1] op_sel_hi:[0,1]
	v_pk_fma_f32 v[122:123], v[122:123], s[90:91], v[126:127] op_sel_hi:[1,0,1] neg_lo:[0,0,1]
	v_pk_mul_f32 v[118:119], v[130:131], s[98:99] op_sel:[1,1] op_sel_hi:[0,1]
	v_pk_fma_f32 v[130:131], v[130:131], s[98:99], v[118:119] op_sel_hi:[1,0,1] neg_lo:[0,0,1]
	v_pk_add_f32 v[186:187], v[100:101], v[116:117]
	v_pk_add_f32 v[188:189], v[100:101], v[116:117] neg_lo:[0,1] neg_hi:[0,1]
	v_pk_add_f32 v[180:181], v[108:109], v[124:125]
	v_pk_add_f32 v[182:183], v[108:109], v[124:125] neg_lo:[0,1] neg_hi:[0,1]
	v_pk_add_f32 v[100:101], v[186:187], v[180:181]
	v_pk_add_f32 v[116:117], v[186:187], v[180:181] neg_lo:[0,1] neg_hi:[0,1]
	v_pk_add_f32 v[108:109], v[188:189], v[182:183] op_sel:[0,1] op_sel_hi:[1,0] neg_hi:[0,1]
	v_pk_add_f32 v[124:125], v[188:189], v[182:183] op_sel:[0,1] op_sel_hi:[1,0] neg_lo:[0,1]
	v_pk_add_f32 v[110:111], v[178:179], v[166:167]
	v_pk_add_f32 v[102:103], v[178:179], v[166:167] neg_lo:[0,1] neg_hi:[0,1]
	v_pk_add_f32 v[184:185], v[176:177], v[174:175]
	v_pk_add_f32 v[168:169], v[176:177], v[174:175] neg_lo:[0,1] neg_hi:[0,1]
	v_pk_add_f32 v[178:179], v[110:111], v[184:185]
	v_pk_add_f32 v[166:167], v[110:111], v[184:185] neg_lo:[0,1] neg_hi:[0,1]
	v_pk_add_f32 v[176:177], v[102:103], v[168:169] op_sel:[0,1] op_sel_hi:[1,0] neg_hi:[0,1]
	v_pk_add_f32 v[174:175], v[102:103], v[168:169] op_sel:[0,1] op_sel_hi:[1,0] neg_lo:[0,1]
	v_pk_add_f32 v[126:127], v[104:105], v[120:121] op_sel:[0,1] op_sel_hi:[1,0] neg_hi:[0,1]
	v_pk_add_f32 v[118:119], v[104:105], v[120:121] op_sel:[0,1] op_sel_hi:[1,0] neg_lo:[0,1]
	v_pk_add_f32 v[186:187], v[112:113], v[128:129]
	v_pk_add_f32 v[188:189], v[112:113], v[128:129] neg_lo:[0,1] neg_hi:[0,1]
	v_pk_add_f32 v[104:105], v[126:127], v[186:187]
	v_pk_add_f32 v[120:121], v[126:127], v[186:187] neg_lo:[0,1] neg_hi:[0,1]
	v_pk_add_f32 v[112:113], v[118:119], v[188:189] op_sel:[0,1] op_sel_hi:[1,0] neg_hi:[0,1]
	v_pk_add_f32 v[128:129], v[118:119], v[188:189] op_sel:[0,1] op_sel_hi:[1,0] neg_lo:[0,1]
	v_pk_add_f32 v[180:181], v[106:107], v[122:123]
	v_pk_add_f32 v[182:183], v[106:107], v[122:123] neg_lo:[0,1] neg_hi:[0,1]
	v_pk_add_f32 v[110:111], v[114:115], v[130:131]
	v_pk_add_f32 v[102:103], v[114:115], v[130:131] neg_lo:[0,1] neg_hi:[0,1]
	v_pk_add_f32 v[106:107], v[180:181], v[110:111]
	v_pk_add_f32 v[122:123], v[180:181], v[110:111] neg_lo:[0,1] neg_hi:[0,1]
	v_pk_add_f32 v[114:115], v[182:183], v[102:103] op_sel:[0,1] op_sel_hi:[1,0] neg_hi:[0,1]
	v_pk_add_f32 v[130:131], v[182:183], v[102:103] op_sel:[0,1] op_sel_hi:[1,0] neg_lo:[0,1]
	ds_read_b64 v[184:185], v200
	ds_read_b64 v[186:187], v204
	ds_read_b64 v[168:169], v200 offset:16
	ds_read_b64 v[188:189], v202 offset:232
	ds_read_b64 v[126:127], v200 offset:32
	ds_read_b64 v[180:181], v202 offset:216
	ds_read_b64 v[118:119], v200 offset:48
	ds_read_b64 v[182:183], v202 offset:200
	s_waitcnt lgkmcnt(6)
	v_pk_add_f32 v[184:185], v[184:185], v[186:187] neg_hi:[0,1]
	v_pk_mul_f32 v[110:111], v[100:101], v[184:185] op_sel:[1,1] op_sel_hi:[0,1]
	v_pk_fma_f32 v[100:101], v[100:101], v[184:185], v[110:111] op_sel_hi:[1,0,1] neg_lo:[0,0,1]
	s_waitcnt lgkmcnt(4)
	v_pk_add_f32 v[168:169], v[168:169], v[188:189] neg_hi:[0,1]
	v_pk_mul_f32 v[102:103], v[178:179], v[168:169] op_sel:[1,1] op_sel_hi:[0,1]
	v_pk_fma_f32 v[178:179], v[178:179], v[168:169], v[102:103] op_sel_hi:[1,0,1] neg_lo:[0,0,1]
	s_waitcnt lgkmcnt(2)
	v_pk_add_f32 v[126:127], v[126:127], v[180:181] neg_hi:[0,1]
	v_pk_mul_f32 v[110:111], v[104:105], v[126:127] op_sel:[1,1] op_sel_hi:[0,1]
	v_pk_fma_f32 v[104:105], v[104:105], v[126:127], v[110:111] op_sel_hi:[1,0,1] neg_lo:[0,0,1]
	s_waitcnt lgkmcnt(0)
	v_pk_add_f32 v[118:119], v[118:119], v[182:183] neg_hi:[0,1]
	v_pk_mul_f32 v[102:103], v[106:107], v[118:119] op_sel:[1,1] op_sel_hi:[0,1]
	v_pk_fma_f32 v[106:107], v[106:107], v[118:119], v[102:103] op_sel_hi:[1,0,1] neg_lo:[0,0,1]
	ds_read_b64 v[110:111], v200 offset:64
	ds_read_b64 v[126:127], v202 offset:184
	ds_read_b64 v[102:103], v200 offset:80
	ds_read_b64 v[118:119], v202 offset:168
	ds_read_b64 v[184:185], v200 offset:96
	ds_read_b64 v[186:187], v202 offset:152
	ds_read_b64 v[168:169], v200 offset:112
	ds_read_b64 v[188:189], v202 offset:136
	s_waitcnt lgkmcnt(6)
; __device__ __forceinline__ f32x2 cmul(f32x2 a, f32x2 b) { return (f32x2){a.x * b.x - a.y * b.y, a.x * b.y + a.y * b.x}; }
; template <bool INV> __device__ __forceinline__ f32x2 cmul_tw(f32x2 a, f32x2 w) { return INV ? cmulc(a, w) : cmul(a, w); }
; template <bool INV> __device__ __forceinline__ void dft16(f32x2 (&x)[16]) {
;     constexpr float C1 = 0.92387953251128674f, S1 = 0.38268343236508977f, C2 = 0.70710678118654752f;
; #pragma unroll
;     for (int b = 0; b < 4; ++b) dft4<INV>(x[b], x[4 + b], x[8 + b], x[12 + b]);
;     const f32x2 w1 = {C1, -S1}, w2 = {C2, -C2}, w3 = {S1, -C1}, w4 = {0.f, -1.f}, w6 = {-C2, -C2}, w9 = {-C1, S1};
;     x[4 * 1 + 1] = cmul_tw<INV>(x[5], w1); x[4 * 1 + 2] = cmul_tw<INV>(x[6], w2); x[4 * 1 + 3] = cmul_tw<INV>(x[7], w3);
;     x[4 * 2 + 1] = cmul_tw<INV>(x[9], w2); x[4 * 2 + 2] = cmul_tw<INV>(x[10], w4); x[4 * 2 + 3] = cmul_tw<INV>(x[11], w6);
;     x[4 * 3 + 1] = cmul_tw<INV>(x[13], w3); x[4 * 3 + 2] = cmul_tw<INV>(x[14], w6); x[4 * 3 + 3] = cmul_tw<INV>(x[15], w9);
; #pragma unroll
;     for (int c = 0; c < 4; ++c) dft4<INV>(x[4 * c], x[4 * c + 1], x[4 * c + 2], x[4 * c + 3]);
; template <int MODE> __device__ __forceinline__ void fft_pair32(LAS f32x2* B, const LAS f32x2* F, int wave, int lane) {
;     ...
;     for (int k = 0; k < 16; ++k) { const f32x2 A = fah[2 * k]; f32x2 Bm = fbh[31 - 2 * k];
;         if (k == 0) { const f32x2 m0 = b2 ? fb[31] : fa[0]; Bm = hi ? Bm : m0; }
;         const f32x2 H = MODE == 0 ? (f32x2){(A.x + Bm.x) * SC, (A.y - Bm.y) * SC} : (f32x2){(A.y + Bm.y) * SC, (Bm.x - A.x) * SC};
;         v[k] = cmul(v[k], H); }
;     dft16<true>(v);
	v_pk_add_f32 v[110:111], v[110:111], v[126:127] neg_hi:[0,1]
	v_pk_mul_f32 v[180:181], v[108:109], v[110:111] op_sel:[1,1] op_sel_hi:[0,1]
	v_pk_fma_f32 v[108:109], v[108:109], v[110:111], v[180:181] op_sel_hi:[1,0,1] neg_lo:[0,0,1]
	s_waitcnt lgkmcnt(4)
	v_pk_add_f32 v[102:103], v[102:103], v[118:119] neg_hi:[0,1]
	v_pk_mul_f32 v[182:183], v[176:177], v[102:103] op_sel:[1,1] op_sel_hi:[0,1]
	v_pk_fma_f32 v[176:177], v[176:177], v[102:103], v[182:183] op_sel_hi:[1,0,1] neg_lo:[0,0,1]
	s_waitcnt lgkmcnt(2)
	v_pk_add_f32 v[184:185], v[184:185], v[186:187] neg_hi:[0,1]
	v_pk_mul_f32 v[180:181], v[112:113], v[184:185] op_sel:[1,1] op_sel_hi:[0,1]
	v_pk_fma_f32 v[112:113], v[112:113], v[184:185], v[180:181] op_sel_hi:[1,0,1] neg_lo:[0,0,1]
	s_waitcnt lgkmcnt(0)
	v_pk_add_f32 v[168:169], v[168:169], v[188:189] neg_hi:[0,1]
	v_pk_mul_f32 v[182:183], v[114:115], v[168:169] op_sel:[1,1] op_sel_hi:[0,1]
	v_pk_fma_f32 v[114:115], v[114:115], v[168:169], v[182:183] op_sel_hi:[1,0,1] neg_lo:[0,0,1]
	ds_read_b64 v[180:181], v200 offset:128
	ds_read_b64 v[184:185], v202 offset:120
	ds_read_b64 v[182:183], v200 offset:144
	ds_read_b64 v[168:169], v202 offset:104
	ds_read_b64 v[110:111], v200 offset:160
	ds_read_b64 v[126:127], v202 offset:88
	ds_read_b64 v[102:103], v200 offset:176
	ds_read_b64 v[118:119], v202 offset:72
	s_waitcnt lgkmcnt(6)
	v_pk_add_f32 v[180:181], v[180:181], v[184:185] neg_hi:[0,1]
	v_pk_mul_f32 v[186:187], v[116:117], v[180:181] op_sel:[1,1] op_sel_hi:[0,1]
	v_pk_fma_f32 v[116:117], v[116:117], v[180:181], v[186:187] op_sel_hi:[1,0,1] neg_lo:[0,0,1]
	s_waitcnt lgkmcnt(4)
	v_pk_add_f32 v[182:183], v[182:183], v[168:169] neg_hi:[0,1]
	v_pk_mul_f32 v[188:189], v[166:167], v[182:183] op_sel:[1,1] op_sel_hi:[0,1]
	v_pk_fma_f32 v[166:167], v[166:167], v[182:183], v[188:189] op_sel_hi:[1,0,1] neg_lo:[0,0,1]
	s_waitcnt lgkmcnt(2)
	v_pk_add_f32 v[110:111], v[110:111], v[126:127] neg_hi:[0,1]
	v_pk_mul_f32 v[186:187], v[120:121], v[110:111] op_sel:[1,1] op_sel_hi:[0,1]
	v_pk_fma_f32 v[120:121], v[120:121], v[110:111], v[186:187] op_sel_hi:[1,0,1] neg_lo:[0,0,1]
	s_waitcnt lgkmcnt(0)
	v_pk_add_f32 v[102:103], v[102:103], v[118:119] neg_hi:[0,1]
	v_pk_mul_f32 v[188:189], v[122:123], v[102:103] op_sel:[1,1] op_sel_hi:[0,1]
	v_pk_fma_f32 v[122:123], v[122:123], v[102:103], v[188:189] op_sel_hi:[1,0,1] neg_lo:[0,0,1]
	ds_read_b64 v[186:187], v200 offset:192
	ds_read_b64 v[110:111], v202 offset:56
	ds_read_b64 v[188:189], v200 offset:208
	ds_read_b64 v[102:103], v202 offset:40
	ds_read_b64 v[180:181], v200 offset:224
	ds_read_b64 v[184:185], v202 offset:24
	ds_read_b64 v[182:183], v200 offset:240
	ds_read_b64 v[168:169], v202 offset:8
	s_waitcnt lgkmcnt(6)
	v_pk_add_f32 v[186:187], v[186:187], v[110:111] neg_hi:[0,1]
	v_pk_mul_f32 v[126:127], v[124:125], v[186:187] op_sel:[1,1] op_sel_hi:[0,1]
	v_pk_fma_f32 v[124:125], v[124:125], v[186:187], v[126:127] op_sel_hi:[1,0,1] neg_lo:[0,0,1]
	s_waitcnt lgkmcnt(4)
	v_pk_add_f32 v[188:189], v[188:189], v[102:103] neg_hi:[0,1]
	v_pk_mul_f32 v[118:119], v[174:175], v[188:189] op_sel:[1,1] op_sel_hi:[0,1]
	v_pk_fma_f32 v[174:175], v[174:175], v[188:189], v[118:119] op_sel_hi:[1,0,1] neg_lo:[0,0,1]
	s_waitcnt lgkmcnt(2)
	v_pk_add_f32 v[180:181], v[180:181], v[184:185] neg_hi:[0,1]
	v_pk_mul_f32 v[126:127], v[128:129], v[180:181] op_sel:[1,1] op_sel_hi:[0,1]
	v_pk_fma_f32 v[128:129], v[128:129], v[180:181], v[126:127] op_sel_hi:[1,0,1] neg_lo:[0,0,1]
	s_waitcnt lgkmcnt(0)
	v_pk_add_f32 v[182:183], v[182:183], v[168:169] neg_hi:[0,1]
	v_pk_mul_f32 v[118:119], v[130:131], v[182:183] op_sel:[1,1] op_sel_hi:[0,1]
	v_pk_fma_f32 v[130:131], v[130:131], v[182:183], v[118:119] op_sel_hi:[1,0,1] neg_lo:[0,0,1]
	v_pk_add_f32 v[126:127], v[100:101], v[116:117]
	v_pk_add_f32 v[118:119], v[100:101], v[116:117] neg_lo:[0,1] neg_hi:[0,1]
	v_pk_add_f32 v[186:187], v[108:109], v[124:125]
	v_pk_add_f32 v[188:189], v[108:109], v[124:125] neg_lo:[0,1] neg_hi:[0,1]
	v_pk_add_f32 v[100:101], v[126:127], v[186:187]
	v_pk_add_f32 v[116:117], v[126:127], v[186:187] neg_lo:[0,1] neg_hi:[0,1]
	v_pk_add_f32 v[108:109], v[118:119], v[188:189] op_sel:[0,1] op_sel_hi:[1,0] neg_lo:[0,1]
	v_pk_add_f32 v[124:125], v[118:119], v[188:189] op_sel:[0,1] op_sel_hi:[1,0] neg_hi:[0,1]
	v_pk_add_f32 v[180:181], v[178:179], v[166:167]
	v_pk_add_f32 v[182:183], v[178:179], v[166:167] neg_lo:[0,1] neg_hi:[0,1]
	v_pk_add_f32 v[110:111], v[176:177], v[174:175]
	v_pk_add_f32 v[102:103], v[176:177], v[174:175] neg_lo:[0,1] neg_hi:[0,1]
	v_pk_add_f32 v[178:179], v[180:181], v[110:111]
	v_pk_add_f32 v[166:167], v[180:181], v[110:111] neg_lo:[0,1] neg_hi:[0,1]
	v_pk_add_f32 v[176:177], v[182:183], v[102:103] op_sel:[0,1] op_sel_hi:[1,0] neg_lo:[0,1]
	v_pk_add_f32 v[174:175], v[182:183], v[102:103] op_sel:[0,1] op_sel_hi:[1,0] neg_hi:[0,1]
	v_pk_add_f32 v[184:185], v[104:105], v[120:121]
	v_pk_add_f32 v[168:169], v[104:105], v[120:121] neg_lo:[0,1] neg_hi:[0,1]
	v_pk_add_f32 v[126:127], v[112:113], v[128:129]
	v_pk_add_f32 v[118:119], v[112:113], v[128:129] neg_lo:[0,1] neg_hi:[0,1]
	v_pk_add_f32 v[104:105], v[184:185], v[126:127]
	v_pk_add_f32 v[120:121], v[184:185], v[126:127] neg_lo:[0,1] neg_hi:[0,1]
	v_pk_add_f32 v[112:113], v[168:169], v[118:119] op_sel:[0,1] op_sel_hi:[1,0] neg_lo:[0,1]
	v_pk_add_f32 v[128:129], v[168:169], v[118:119] op_sel:[0,1] op_sel_hi:[1,0] neg_hi:[0,1]
	v_pk_add_f32 v[186:187], v[106:107], v[122:123]
	v_pk_add_f32 v[188:189], v[106:107], v[122:123] neg_lo:[0,1] neg_hi:[0,1]
	v_pk_add_f32 v[180:181], v[114:115], v[130:131]
	v_pk_add_f32 v[182:183], v[114:115], v[130:131] neg_lo:[0,1] neg_hi:[0,1]
	v_pk_add_f32 v[106:107], v[186:187], v[180:181]
; __device__ __forceinline__ f32x2 cmulc(f32x2 a, f32x2 b) { return (f32x2){a.x * b.x + a.y * b.y, a.y * b.x - a.x * b.y}; }
; template <bool INV> __device__ __forceinline__ f32x2 cmul_tw(f32x2 a, f32x2 w) { return INV ? cmulc(a, w) : cmul(a, w); }
; template <bool INV> __device__ __forceinline__ void dft16(f32x2 (&x)[16]) {
;     ...
;     x[4 * 1 + 1] = cmul_tw<INV>(x[5], w1); x[4 * 1 + 2] = cmul_tw<INV>(x[6], w2); x[4 * 1 + 3] = cmul_tw<INV>(x[7], w3);
;     x[4 * 2 + 1] = cmul_tw<INV>(x[9], w2); x[4 * 2 + 2] = cmul_tw<INV>(x[10], w4); x[4 * 2 + 3] = cmul_tw<INV>(x[11], w6);
;     x[4 * 3 + 1] = cmul_tw<INV>(x[13], w3); x[4 * 3 + 2] = cmul_tw<INV>(x[14], w6); x[4 * 3 + 3] = cmul_tw<INV>(x[15], w9);
; #pragma unroll
;     for (int c = 0; c < 4; ++c) dft4<INV>(x[4 * c], x[4 * c + 1], x[4 * c + 2], x[4 * c + 3]);
; template <int MODE> __device__ __forceinline__ void fft_pair32(LAS f32x2* B, const LAS f32x2* F, int wave, int lane) {
;     ...
;     for (int j = 0; j < 16; ++j) { const f32x2 w = {hi ? CS[j] : 1.f, hi ? -SN[j] : 0.f}; const f32x2 u = j == 0 ? v[j] : cmulc(v[j], w);
;         const auto rx = __builtin_amdgcn_permlane32_swap(__float_as_uint(u.x), __float_as_uint(u.x), false, false);
;         const auto ry = __builtin_amdgcn_permlane32_swap(__float_as_uint(u.y), __float_as_uint(u.y), false, false);
;         const f32x2 a = {__uint_as_float(rx[0]), __uint_as_float(ry[0])}, b = {__uint_as_float(rx[1]), __uint_as_float(ry[1])};
;         p[16 * hi + j] = a + b * sg; }
	v_pk_add_f32 v[122:123], v[186:187], v[180:181] neg_lo:[0,1] neg_hi:[0,1]
	v_pk_add_f32 v[114:115], v[188:189], v[182:183] op_sel:[0,1] op_sel_hi:[1,0] neg_lo:[0,1]
	v_pk_add_f32 v[130:131], v[188:189], v[182:183] op_sel:[0,1] op_sel_hi:[1,0] neg_hi:[0,1]
	v_pk_mul_f32 v[110:111], v[176:177], s[68:69] op_sel:[1,1] op_sel_hi:[0,1]
	v_pk_fma_f32 v[176:177], v[176:177], s[68:69], v[110:111] op_sel_hi:[1,0,1] neg_hi:[0,0,1]
	v_pk_mul_f32 v[102:103], v[112:113], s[84:85] op_sel:[1,1] op_sel_hi:[0,1]
	v_pk_fma_f32 v[112:113], v[112:113], s[84:85], v[102:103] op_sel_hi:[1,0,1] neg_hi:[0,0,1]
	v_pk_mul_f32 v[184:185], v[114:115], s[88:89] op_sel:[1,1] op_sel_hi:[0,1]
	v_pk_fma_f32 v[114:115], v[114:115], s[88:89], v[184:185] op_sel_hi:[1,0,1] neg_hi:[0,0,1]
	v_pk_mul_f32 v[168:169], v[166:167], s[84:85] op_sel:[1,1] op_sel_hi:[0,1]
	v_pk_fma_f32 v[166:167], v[166:167], s[84:85], v[168:169] op_sel_hi:[1,0,1] neg_hi:[0,0,1]
	v_pk_mul_f32 v[126:127], v[122:123], s[90:91] op_sel:[1,1] op_sel_hi:[0,1]
	v_pk_fma_f32 v[122:123], v[122:123], s[90:91], v[126:127] op_sel_hi:[1,0,1] neg_hi:[0,0,1]
	v_pk_mul_f32 v[118:119], v[174:175], s[88:89] op_sel:[1,1] op_sel_hi:[0,1]
	v_pk_fma_f32 v[174:175], v[174:175], s[88:89], v[118:119] op_sel_hi:[1,0,1] neg_hi:[0,0,1]
	v_pk_mul_f32 v[186:187], v[128:129], s[90:91] op_sel:[1,1] op_sel_hi:[0,1]
	v_pk_fma_f32 v[128:129], v[128:129], s[90:91], v[186:187] op_sel_hi:[1,0,1] neg_hi:[0,0,1]
	v_pk_mul_f32 v[188:189], v[130:131], s[98:99] op_sel:[1,1] op_sel_hi:[0,1]
	v_pk_fma_f32 v[130:131], v[130:131], s[98:99], v[188:189] op_sel_hi:[1,0,1] neg_hi:[0,0,1]
	v_pk_add_f32 v[180:181], v[100:101], v[104:105]
	v_pk_add_f32 v[182:183], v[100:101], v[104:105] neg_lo:[0,1] neg_hi:[0,1]
	v_pk_add_f32 v[110:111], v[178:179], v[106:107]
	v_pk_add_f32 v[102:103], v[178:179], v[106:107] neg_lo:[0,1] neg_hi:[0,1]
	v_pk_add_f32 v[100:101], v[180:181], v[110:111]
	v_pk_add_f32 v[104:105], v[180:181], v[110:111] neg_lo:[0,1] neg_hi:[0,1]
	v_pk_add_f32 v[178:179], v[182:183], v[102:103] op_sel:[0,1] op_sel_hi:[1,0] neg_lo:[0,1]
	v_pk_add_f32 v[106:107], v[182:183], v[102:103] op_sel:[0,1] op_sel_hi:[1,0] neg_hi:[0,1]
	v_pk_add_f32 v[184:185], v[108:109], v[112:113]
	v_pk_add_f32 v[168:169], v[108:109], v[112:113] neg_lo:[0,1] neg_hi:[0,1]
	v_pk_add_f32 v[126:127], v[176:177], v[114:115]
	v_pk_add_f32 v[118:119], v[176:177], v[114:115] neg_lo:[0,1] neg_hi:[0,1]
	v_pk_add_f32 v[108:109], v[184:185], v[126:127]
	v_pk_add_f32 v[112:113], v[184:185], v[126:127] neg_lo:[0,1] neg_hi:[0,1]
	v_pk_add_f32 v[176:177], v[168:169], v[118:119] op_sel:[0,1] op_sel_hi:[1,0] neg_lo:[0,1]
	v_pk_add_f32 v[114:115], v[168:169], v[118:119] op_sel:[0,1] op_sel_hi:[1,0] neg_hi:[0,1]
	v_pk_add_f32 v[186:187], v[116:117], v[120:121] op_sel:[0,1] op_sel_hi:[1,0] neg_lo:[0,1]
	v_pk_add_f32 v[188:189], v[116:117], v[120:121] op_sel:[0,1] op_sel_hi:[1,0] neg_hi:[0,1]
	v_pk_add_f32 v[180:181], v[166:167], v[122:123]
	v_pk_add_f32 v[182:183], v[166:167], v[122:123] neg_lo:[0,1] neg_hi:[0,1]
	v_pk_add_f32 v[116:117], v[186:187], v[180:181]
	v_pk_add_f32 v[120:121], v[186:187], v[180:181] neg_lo:[0,1] neg_hi:[0,1]
	v_pk_add_f32 v[166:167], v[188:189], v[182:183] op_sel:[0,1] op_sel_hi:[1,0] neg_lo:[0,1]
	v_pk_add_f32 v[122:123], v[188:189], v[182:183] op_sel:[0,1] op_sel_hi:[1,0] neg_hi:[0,1]
	v_pk_add_f32 v[110:111], v[124:125], v[128:129]
	v_pk_add_f32 v[102:103], v[124:125], v[128:129] neg_lo:[0,1] neg_hi:[0,1]
	v_pk_add_f32 v[184:185], v[174:175], v[130:131]
	v_pk_add_f32 v[168:169], v[174:175], v[130:131] neg_lo:[0,1] neg_hi:[0,1]
	v_pk_add_f32 v[124:125], v[110:111], v[184:185]
	v_pk_add_f32 v[128:129], v[110:111], v[184:185] neg_lo:[0,1] neg_hi:[0,1]
	v_pk_add_f32 v[174:175], v[102:103], v[168:169] op_sel:[0,1] op_sel_hi:[1,0] neg_lo:[0,1]
	v_pk_add_f32 v[130:131], v[102:103], v[168:169] op_sel:[0,1] op_sel_hi:[1,0] neg_hi:[0,1]
	v_mov_b32_e32 v126, v100
	v_mov_b32_e32 v127, v101
	v_pk_mul_f32 v[180:181], v[108:109], v[36:37] op_sel:[1,1] op_sel_hi:[0,1]
	v_pk_fma_f32 v[118:119], v[108:109], v[36:37], v[180:181] op_sel_hi:[1,0,1] neg_hi:[0,0,1]
	v_pk_fma_f32 v[108:109], v[108:109], v[36:37], v[180:181] op_sel_hi:[1,0,1] neg_hi:[0,0,1]
	v_pk_mul_f32 v[182:183], v[116:117], v[38:39] op_sel:[1,1] op_sel_hi:[0,1]
	v_pk_fma_f32 v[186:187], v[116:117], v[38:39], v[182:183] op_sel_hi:[1,0,1] neg_hi:[0,0,1]
	v_pk_fma_f32 v[116:117], v[116:117], v[38:39], v[182:183] op_sel_hi:[1,0,1] neg_hi:[0,0,1]
	v_pk_mul_f32 v[110:111], v[124:125], v[40:41] op_sel:[1,1] op_sel_hi:[0,1]
	v_pk_fma_f32 v[188:189], v[124:125], v[40:41], v[110:111] op_sel_hi:[1,0,1] neg_hi:[0,0,1]
	v_pk_fma_f32 v[124:125], v[124:125], v[40:41], v[110:111] op_sel_hi:[1,0,1] neg_hi:[0,0,1]
	s_nop 1
	v_permlane32_swap_b32_e32 v100, v126
	v_permlane32_swap_b32_e32 v101, v127
	v_permlane32_swap_b32_e32 v108, v118
	v_permlane32_swap_b32_e32 v109, v119
	v_permlane32_swap_b32_e32 v116, v186
	v_permlane32_swap_b32_e32 v117, v187
	v_permlane32_swap_b32_e32 v124, v188
	v_permlane32_swap_b32_e32 v125, v189
	v_pk_fma_f32 v[100:101], v[126:127], v[190:191], v[100:101] op_sel_hi:[1,0,1]
	ds_write_b64 v198, v[100:101]
	v_pk_fma_f32 v[108:109], v[118:119], v[190:191], v[108:109] op_sel_hi:[1,0,1]
	ds_write_b64 v198, v[108:109] offset:8
	v_pk_fma_f32 v[116:117], v[186:187], v[190:191], v[116:117] op_sel_hi:[1,0,1]
	ds_write_b64 v198, v[116:117] offset:16
	v_pk_fma_f32 v[124:125], v[188:189], v[190:191], v[124:125] op_sel_hi:[1,0,1]
	ds_write_b64 v198, v[124:125] offset:24
	v_pk_mul_f32 v[182:183], v[178:179], v[42:43] op_sel:[1,1] op_sel_hi:[0,1]
	v_pk_fma_f32 v[102:103], v[178:179], v[42:43], v[182:183] op_sel_hi:[1,0,1] neg_hi:[0,0,1]
; #define LAS __attribute__((address_space(3)))
; __device__ __forceinline__ f32x2 cmulc(f32x2 a, f32x2 b) { return (f32x2){a.x * b.x + a.y * b.y, a.y * b.x - a.x * b.y}; }
; __device__ __forceinline__ void fft_inv2(LAS f32x2* B, const LAS f32x2* TW2, int tid) {
;     asm volatile("" : "+v"(tid));
;     const int b = tid >> 5, n2 = tid & 31, base = 512 * b + n2; f32x2 x[16];
;     x[0] = B[fpad(base)];
; #pragma unroll
;     for (int k = 1; k < 16; ++k) x[k] = cmulc(B[fpad(base + 32 * k)], TW2[k * 32 + n2]);
; template <int MODE> __device__ __forceinline__ void fft_pair32(LAS f32x2* B, const LAS f32x2* F, int wave, int lane) {
;     ...
;     for (int j = 0; j < 16; ++j) { const f32x2 w = {hi ? CS[j] : 1.f, hi ? -SN[j] : 0.f}; const f32x2 u = j == 0 ? v[j] : cmulc(v[j], w);
;         const auto rx = __builtin_amdgcn_permlane32_swap(__float_as_uint(u.x), __float_as_uint(u.x), false, false);
;         const auto ry = __builtin_amdgcn_permlane32_swap(__float_as_uint(u.y), __float_as_uint(u.y), false, false);
;         const f32x2 a = {__uint_as_float(rx[0]), __uint_as_float(ry[0])}, b = {__uint_as_float(rx[1]), __uint_as_float(ry[1])};
;         p[16 * hi + j] = a + b * sg; }
	v_pk_fma_f32 v[178:179], v[178:179], v[42:43], v[182:183] op_sel_hi:[1,0,1] neg_hi:[0,0,1]
	v_pk_mul_f32 v[110:111], v[176:177], v[44:45] op_sel:[1,1] op_sel_hi:[0,1]
	v_pk_fma_f32 v[184:185], v[176:177], v[44:45], v[110:111] op_sel_hi:[1,0,1] neg_hi:[0,0,1]
	v_pk_fma_f32 v[176:177], v[176:177], v[44:45], v[110:111] op_sel_hi:[1,0,1] neg_hi:[0,0,1]
	v_pk_mul_f32 v[126:127], v[166:167], v[46:47] op_sel:[1,1] op_sel_hi:[0,1]
	v_pk_fma_f32 v[168:169], v[166:167], v[46:47], v[126:127] op_sel_hi:[1,0,1] neg_hi:[0,0,1]
	v_pk_fma_f32 v[166:167], v[166:167], v[46:47], v[126:127] op_sel_hi:[1,0,1] neg_hi:[0,0,1]
	v_pk_mul_f32 v[118:119], v[174:175], v[48:49] op_sel:[1,1] op_sel_hi:[0,1]
	v_pk_fma_f32 v[180:181], v[174:175], v[48:49], v[118:119] op_sel_hi:[1,0,1] neg_hi:[0,0,1]
	v_pk_fma_f32 v[174:175], v[174:175], v[48:49], v[118:119] op_sel_hi:[1,0,1] neg_hi:[0,0,1]
	s_nop 1
	v_permlane32_swap_b32_e32 v178, v102
	v_permlane32_swap_b32_e32 v179, v103
	v_permlane32_swap_b32_e32 v176, v184
	v_permlane32_swap_b32_e32 v177, v185
	v_permlane32_swap_b32_e32 v166, v168
	v_permlane32_swap_b32_e32 v167, v169
	v_permlane32_swap_b32_e32 v174, v180
	v_permlane32_swap_b32_e32 v175, v181
	v_pk_fma_f32 v[178:179], v[102:103], v[190:191], v[178:179] op_sel_hi:[1,0,1]
	ds_write_b64 v198, v[178:179] offset:32
	v_pk_fma_f32 v[176:177], v[184:185], v[190:191], v[176:177] op_sel_hi:[1,0,1]
	ds_write_b64 v198, v[176:177] offset:40
	v_pk_fma_f32 v[166:167], v[168:169], v[190:191], v[166:167] op_sel_hi:[1,0,1]
	ds_write_b64 v198, v[166:167] offset:48
	v_pk_fma_f32 v[174:175], v[180:181], v[190:191], v[174:175] op_sel_hi:[1,0,1]
	ds_write_b64 v198, v[174:175] offset:56
	v_pk_mul_f32 v[126:127], v[104:105], v[50:51] op_sel:[1,1] op_sel_hi:[0,1]
	v_pk_fma_f32 v[186:187], v[104:105], v[50:51], v[126:127] op_sel_hi:[1,0,1] neg_hi:[0,0,1]
	v_pk_fma_f32 v[104:105], v[104:105], v[50:51], v[126:127] op_sel_hi:[1,0,1] neg_hi:[0,0,1]
	v_pk_mul_f32 v[118:119], v[112:113], v[52:53] op_sel:[1,1] op_sel_hi:[0,1]
	v_pk_fma_f32 v[188:189], v[112:113], v[52:53], v[118:119] op_sel_hi:[1,0,1] neg_hi:[0,0,1]
	v_pk_fma_f32 v[112:113], v[112:113], v[52:53], v[118:119] op_sel_hi:[1,0,1] neg_hi:[0,0,1]
	v_pk_mul_f32 v[102:103], v[120:121], v[54:55] op_sel:[1,1] op_sel_hi:[0,1]
	v_pk_fma_f32 v[182:183], v[120:121], v[54:55], v[102:103] op_sel_hi:[1,0,1] neg_hi:[0,0,1]
	v_pk_fma_f32 v[120:121], v[120:121], v[54:55], v[102:103] op_sel_hi:[1,0,1] neg_hi:[0,0,1]
	v_pk_mul_f32 v[184:185], v[128:129], v[90:91] op_sel:[1,1] op_sel_hi:[0,1]
	v_pk_fma_f32 v[110:111], v[128:129], v[90:91], v[184:185] op_sel_hi:[1,0,1] neg_hi:[0,0,1]
	v_pk_fma_f32 v[128:129], v[128:129], v[90:91], v[184:185] op_sel_hi:[1,0,1] neg_hi:[0,0,1]
	s_nop 1
	v_permlane32_swap_b32_e32 v104, v186
	v_permlane32_swap_b32_e32 v105, v187
	v_permlane32_swap_b32_e32 v112, v188
	v_permlane32_swap_b32_e32 v113, v189
	v_permlane32_swap_b32_e32 v120, v182
	v_permlane32_swap_b32_e32 v121, v183
	v_permlane32_swap_b32_e32 v128, v110
	v_permlane32_swap_b32_e32 v129, v111
	v_pk_fma_f32 v[104:105], v[186:187], v[190:191], v[104:105] op_sel_hi:[1,0,1]
	ds_write_b64 v198, v[104:105] offset:64
	v_pk_fma_f32 v[112:113], v[188:189], v[190:191], v[112:113] op_sel_hi:[1,0,1]
	ds_write_b64 v198, v[112:113] offset:72
	v_pk_fma_f32 v[120:121], v[182:183], v[190:191], v[120:121] op_sel_hi:[1,0,1]
	ds_write_b64 v198, v[120:121] offset:80
	v_pk_fma_f32 v[128:129], v[110:111], v[190:191], v[128:129] op_sel_hi:[1,0,1]
	ds_write_b64 v198, v[128:129] offset:88
	v_pk_mul_f32 v[102:103], v[106:107], v[92:93] op_sel:[1,1] op_sel_hi:[0,1]
	v_pk_fma_f32 v[168:169], v[106:107], v[92:93], v[102:103] op_sel_hi:[1,0,1] neg_hi:[0,0,1]
	v_pk_fma_f32 v[106:107], v[106:107], v[92:93], v[102:103] op_sel_hi:[1,0,1] neg_hi:[0,0,1]
	v_pk_mul_f32 v[184:185], v[114:115], v[94:95] op_sel:[1,1] op_sel_hi:[0,1]
	v_pk_fma_f32 v[180:181], v[114:115], v[94:95], v[184:185] op_sel_hi:[1,0,1] neg_hi:[0,0,1]
	v_pk_fma_f32 v[114:115], v[114:115], v[94:95], v[184:185] op_sel_hi:[1,0,1] neg_hi:[0,0,1]
	v_pk_mul_f32 v[186:187], v[122:123], v[96:97] op_sel:[1,1] op_sel_hi:[0,1]
	v_pk_fma_f32 v[126:127], v[122:123], v[96:97], v[186:187] op_sel_hi:[1,0,1] neg_hi:[0,0,1]
	v_pk_fma_f32 v[122:123], v[122:123], v[96:97], v[186:187] op_sel_hi:[1,0,1] neg_hi:[0,0,1]
	v_pk_mul_f32 v[188:189], v[130:131], v[98:99] op_sel:[1,1] op_sel_hi:[0,1]
	v_pk_fma_f32 v[118:119], v[130:131], v[98:99], v[188:189] op_sel_hi:[1,0,1] neg_hi:[0,0,1]
	v_pk_fma_f32 v[130:131], v[130:131], v[98:99], v[188:189] op_sel_hi:[1,0,1] neg_hi:[0,0,1]
	s_nop 1
	v_permlane32_swap_b32_e32 v106, v168
	v_permlane32_swap_b32_e32 v107, v169
	v_permlane32_swap_b32_e32 v114, v180
	v_permlane32_swap_b32_e32 v115, v181
	v_permlane32_swap_b32_e32 v122, v126
	v_permlane32_swap_b32_e32 v123, v127
	v_permlane32_swap_b32_e32 v130, v118
	v_permlane32_swap_b32_e32 v131, v119
	v_pk_fma_f32 v[106:107], v[168:169], v[190:191], v[106:107] op_sel_hi:[1,0,1]
	ds_write_b64 v198, v[106:107] offset:96
	v_pk_fma_f32 v[114:115], v[180:181], v[190:191], v[114:115] op_sel_hi:[1,0,1]
	ds_write_b64 v198, v[114:115] offset:104
	v_pk_fma_f32 v[122:123], v[126:127], v[190:191], v[122:123] op_sel_hi:[1,0,1]
	ds_write_b64 v198, v[122:123] offset:112
	v_pk_fma_f32 v[130:131], v[118:119], v[190:191], v[130:131] op_sel_hi:[1,0,1]
	ds_write_b64 v198, v[130:131] offset:120
	s_waitcnt lgkmcnt(0)
	ds_read_b64 v[100:101], v5
	ds_read_b64 v[108:109], v5 offset:264
	ds_read_b64 v[182:183], v56 offset:256
	ds_read_b64 v[116:117], v5 offset:528
	ds_read_b64 v[110:111], v56 offset:512
	ds_read_b64 v[124:125], v5 offset:792
	ds_read_b64 v[102:103], v56 offset:768
	ds_read_b64 v[178:179], v5 offset:1056
	ds_read_b64 v[184:185], v56 offset:1024
	ds_read_b64 v[176:177], v5 offset:1320
	ds_read_b64 v[186:187], v56 offset:1280
	s_waitcnt lgkmcnt(8)
; #define LAS __attribute__((address_space(3)))
; __device__ __forceinline__ f32x2 cmulc(f32x2 a, f32x2 b) { return (f32x2){a.x * b.x + a.y * b.y, a.y * b.x - a.x * b.y}; }
; template <bool INV> __device__ __forceinline__ f32x2 cmul_tw(f32x2 a, f32x2 w) { return INV ? cmulc(a, w) : cmul(a, w); }
; template <bool INV> __device__ __forceinline__ void dft16(f32x2 (&x)[16]) {
;     constexpr float C1 = 0.92387953251128674f, S1 = 0.38268343236508977f, C2 = 0.70710678118654752f;
; #pragma unroll
;     for (int b = 0; b < 4; ++b) dft4<INV>(x[b], x[4 + b], x[8 + b], x[12 + b]);
;     const f32x2 w1 = {C1, -S1}, w2 = {C2, -C2}, w3 = {S1, -C1}, w4 = {0.f, -1.f}, w6 = {-C2, -C2}, w9 = {-C1, S1};
;     x[4 * 1 + 1] = cmul_tw<INV>(x[5], w1); x[4 * 1 + 2] = cmul_tw<INV>(x[6], w2); x[4 * 1 + 3] = cmul_tw<INV>(x[7], w3);
;     x[4 * 2 + 1] = cmul_tw<INV>(x[9], w2); x[4 * 2 + 2] = cmul_tw<INV>(x[10], w4); x[4 * 2 + 3] = cmul_tw<INV>(x[11], w6);
;     x[4 * 3 + 1] = cmul_tw<INV>(x[13], w3); x[4 * 3 + 2] = cmul_tw<INV>(x[14], w6); x[4 * 3 + 3] = cmul_tw<INV>(x[15], w9);
; #pragma unroll
;     for (int c = 0; c < 4; ++c) dft4<INV>(x[4 * c], x[4 * c + 1], x[4 * c + 2], x[4 * c + 3]);
; __device__ __forceinline__ void fft_inv2(LAS f32x2* B, const LAS f32x2* TW2, int tid) {
;     asm volatile("" : "+v"(tid));
;     const int b = tid >> 5, n2 = tid & 31, base = 512 * b + n2; f32x2 x[16];
;     x[0] = B[fpad(base)];
; #pragma unroll
;     for (int k = 1; k < 16; ++k) x[k] = cmulc(B[fpad(base + 32 * k)], TW2[k * 32 + n2]);
;     dft16<true>(x);
	v_pk_mul_f32 v[188:189], v[108:109], v[182:183] op_sel:[1,1] op_sel_hi:[0,1]
	v_pk_fma_f32 v[108:109], v[108:109], v[182:183], v[188:189] op_sel_hi:[1,0,1] neg_hi:[0,0,1]
	s_waitcnt lgkmcnt(6)
	v_pk_mul_f32 v[168:169], v[116:117], v[110:111] op_sel:[1,1] op_sel_hi:[0,1]
	v_pk_fma_f32 v[116:117], v[116:117], v[110:111], v[168:169] op_sel_hi:[1,0,1] neg_hi:[0,0,1]
	s_waitcnt lgkmcnt(4)
	v_pk_mul_f32 v[180:181], v[124:125], v[102:103] op_sel:[1,1] op_sel_hi:[0,1]
	v_pk_fma_f32 v[124:125], v[124:125], v[102:103], v[180:181] op_sel_hi:[1,0,1] neg_hi:[0,0,1]
	s_waitcnt lgkmcnt(2)
	v_pk_mul_f32 v[126:127], v[178:179], v[184:185] op_sel:[1,1] op_sel_hi:[0,1]
	v_pk_fma_f32 v[178:179], v[178:179], v[184:185], v[126:127] op_sel_hi:[1,0,1] neg_hi:[0,0,1]
	s_waitcnt lgkmcnt(0)
	v_pk_mul_f32 v[118:119], v[176:177], v[186:187] op_sel:[1,1] op_sel_hi:[0,1]
	v_pk_fma_f32 v[176:177], v[176:177], v[186:187], v[118:119] op_sel_hi:[1,0,1] neg_hi:[0,0,1]
	ds_read_b64 v[166:167], v5 offset:1584
	ds_read_b64 v[188:189], v56 offset:1536
	ds_read_b64 v[174:175], v5 offset:1848
	ds_read_b64 v[168:169], v56 offset:1792
	ds_read_b64 v[104:105], v5 offset:2112
	ds_read_b64 v[180:181], v56 offset:2048
	ds_read_b64 v[112:113], v5 offset:2376
	ds_read_b64 v[126:127], v56 offset:2304
	ds_read_b64 v[120:121], v5 offset:2640
	ds_read_b64 v[118:119], v56 offset:2560
	s_waitcnt lgkmcnt(8)
	v_pk_mul_f32 v[182:183], v[166:167], v[188:189] op_sel:[1,1] op_sel_hi:[0,1]
	v_pk_fma_f32 v[166:167], v[166:167], v[188:189], v[182:183] op_sel_hi:[1,0,1] neg_hi:[0,0,1]
	s_waitcnt lgkmcnt(6)
	v_pk_mul_f32 v[110:111], v[174:175], v[168:169] op_sel:[1,1] op_sel_hi:[0,1]
	v_pk_fma_f32 v[174:175], v[174:175], v[168:169], v[110:111] op_sel_hi:[1,0,1] neg_hi:[0,0,1]
	s_waitcnt lgkmcnt(4)
	v_pk_mul_f32 v[102:103], v[104:105], v[180:181] op_sel:[1,1] op_sel_hi:[0,1]
	v_pk_fma_f32 v[104:105], v[104:105], v[180:181], v[102:103] op_sel_hi:[1,0,1] neg_hi:[0,0,1]
	s_waitcnt lgkmcnt(2)
	v_pk_mul_f32 v[184:185], v[112:113], v[126:127] op_sel:[1,1] op_sel_hi:[0,1]
	v_pk_fma_f32 v[112:113], v[112:113], v[126:127], v[184:185] op_sel_hi:[1,0,1] neg_hi:[0,0,1]
	s_waitcnt lgkmcnt(0)
	v_pk_mul_f32 v[186:187], v[120:121], v[118:119] op_sel:[1,1] op_sel_hi:[0,1]
	v_pk_fma_f32 v[120:121], v[120:121], v[118:119], v[186:187] op_sel_hi:[1,0,1] neg_hi:[0,0,1]
	ds_read_b64 v[128:129], v5 offset:2904
	ds_read_b64 v[182:183], v56 offset:2816
	ds_read_b64 v[106:107], v5 offset:3168
	ds_read_b64 v[110:111], v56 offset:3072
	ds_read_b64 v[114:115], v5 offset:3432
	ds_read_b64 v[102:103], v56 offset:3328
	ds_read_b64 v[122:123], v5 offset:3696
	ds_read_b64 v[184:185], v56 offset:3584
	ds_read_b64 v[130:131], v5 offset:3960
	ds_read_b64 v[186:187], v56 offset:3840
	s_waitcnt lgkmcnt(8)
	v_pk_mul_f32 v[188:189], v[128:129], v[182:183] op_sel:[1,1] op_sel_hi:[0,1]
	v_pk_fma_f32 v[128:129], v[128:129], v[182:183], v[188:189] op_sel_hi:[1,0,1] neg_hi:[0,0,1]
	s_waitcnt lgkmcnt(6)
	v_pk_mul_f32 v[168:169], v[106:107], v[110:111] op_sel:[1,1] op_sel_hi:[0,1]
	v_pk_fma_f32 v[106:107], v[106:107], v[110:111], v[168:169] op_sel_hi:[1,0,1] neg_hi:[0,0,1]
	s_waitcnt lgkmcnt(4)
	v_pk_mul_f32 v[180:181], v[114:115], v[102:103] op_sel:[1,1] op_sel_hi:[0,1]
	v_pk_fma_f32 v[114:115], v[114:115], v[102:103], v[180:181] op_sel_hi:[1,0,1] neg_hi:[0,0,1]
	s_waitcnt lgkmcnt(2)
	v_pk_mul_f32 v[126:127], v[122:123], v[184:185] op_sel:[1,1] op_sel_hi:[0,1]
	v_pk_fma_f32 v[122:123], v[122:123], v[184:185], v[126:127] op_sel_hi:[1,0,1] neg_hi:[0,0,1]
	s_waitcnt lgkmcnt(0)
	v_pk_mul_f32 v[118:119], v[130:131], v[186:187] op_sel:[1,1] op_sel_hi:[0,1]
	v_pk_fma_f32 v[130:131], v[130:131], v[186:187], v[118:119] op_sel_hi:[1,0,1] neg_hi:[0,0,1]
	v_pk_add_f32 v[188:189], v[100:101], v[104:105]
	v_pk_add_f32 v[168:169], v[100:101], v[104:105] neg_lo:[0,1] neg_hi:[0,1]
	v_pk_add_f32 v[180:181], v[178:179], v[106:107]
	v_pk_add_f32 v[126:127], v[178:179], v[106:107] neg_lo:[0,1] neg_hi:[0,1]
	v_pk_add_f32 v[100:101], v[188:189], v[180:181]
	v_pk_add_f32 v[104:105], v[188:189], v[180:181] neg_lo:[0,1] neg_hi:[0,1]
	v_pk_add_f32 v[178:179], v[168:169], v[126:127] op_sel:[0,1] op_sel_hi:[1,0] neg_lo:[0,1]
	v_pk_add_f32 v[106:107], v[168:169], v[126:127] op_sel:[0,1] op_sel_hi:[1,0] neg_hi:[0,1]
	v_pk_add_f32 v[118:119], v[108:109], v[112:113]
	v_pk_add_f32 v[182:183], v[108:109], v[112:113] neg_lo:[0,1] neg_hi:[0,1]
	v_pk_add_f32 v[110:111], v[176:177], v[114:115]
	v_pk_add_f32 v[102:103], v[176:177], v[114:115] neg_lo:[0,1] neg_hi:[0,1]
	v_pk_add_f32 v[108:109], v[118:119], v[110:111]
	v_pk_add_f32 v[112:113], v[118:119], v[110:111] neg_lo:[0,1] neg_hi:[0,1]
	v_pk_add_f32 v[176:177], v[182:183], v[102:103] op_sel:[0,1] op_sel_hi:[1,0] neg_lo:[0,1]
	v_pk_add_f32 v[114:115], v[182:183], v[102:103] op_sel:[0,1] op_sel_hi:[1,0] neg_hi:[0,1]
	v_pk_add_f32 v[184:185], v[116:117], v[120:121]
	v_pk_add_f32 v[186:187], v[116:117], v[120:121] neg_lo:[0,1] neg_hi:[0,1]
	v_pk_add_f32 v[188:189], v[166:167], v[122:123]
	v_pk_add_f32 v[168:169], v[166:167], v[122:123] neg_lo:[0,1] neg_hi:[0,1]
	v_pk_add_f32 v[116:117], v[184:185], v[188:189]
	v_pk_add_f32 v[120:121], v[184:185], v[188:189] neg_lo:[0,1] neg_hi:[0,1]
	v_pk_add_f32 v[166:167], v[186:187], v[168:169] op_sel:[0,1] op_sel_hi:[1,0] neg_lo:[0,1]
	v_pk_add_f32 v[122:123], v[186:187], v[168:169] op_sel:[0,1] op_sel_hi:[1,0] neg_hi:[0,1]
	v_pk_add_f32 v[180:181], v[124:125], v[128:129]
	v_pk_add_f32 v[126:127], v[124:125], v[128:129] neg_lo:[0,1] neg_hi:[0,1]
	v_pk_add_f32 v[118:119], v[174:175], v[130:131]
	v_pk_add_f32 v[182:183], v[174:175], v[130:131] neg_lo:[0,1] neg_hi:[0,1]
	v_pk_add_f32 v[124:125], v[180:181], v[118:119]
; template <bool INV> __device__ __forceinline__ f32x2 cmul_tw(f32x2 a, f32x2 w) { return INV ? cmulc(a, w) : cmul(a, w); }
; template <bool INV> __device__ __forceinline__ void dft16(f32x2 (&x)[16]) {
;     ...
;     x[4 * 1 + 1] = cmul_tw<INV>(x[5], w1); x[4 * 1 + 2] = cmul_tw<INV>(x[6], w2); x[4 * 1 + 3] = cmul_tw<INV>(x[7], w3);
;     x[4 * 2 + 1] = cmul_tw<INV>(x[9], w2); x[4 * 2 + 2] = cmul_tw<INV>(x[10], w4); x[4 * 2 + 3] = cmul_tw<INV>(x[11], w6);
;     x[4 * 3 + 1] = cmul_tw<INV>(x[13], w3); x[4 * 3 + 2] = cmul_tw<INV>(x[14], w6); x[4 * 3 + 3] = cmul_tw<INV>(x[15], w9);
; #pragma unroll
;     for (int c = 0; c < 4; ++c) dft4<INV>(x[4 * c], x[4 * c + 1], x[4 * c + 2], x[4 * c + 3]);
;     f32x2 y[16];
; #pragma unroll
;     for (int k = 0; k < 16; ++k) y[k] = x[4 * (k & 3) + (k >> 2)];
; #pragma unroll
;     for (int k = 0; k < 16; ++k) x[k] = y[k];
; __device__ __forceinline__ void fft_inv2(LAS f32x2* B, const LAS f32x2* TW2, int tid) {
;     ...
; #pragma unroll
;     for (int r = 0; r < 16; ++r) B[fpad(base + 32 * r)] = x[r];
; }
	v_pk_add_f32 v[128:129], v[180:181], v[118:119] neg_lo:[0,1] neg_hi:[0,1]
	v_pk_add_f32 v[174:175], v[126:127], v[182:183] op_sel:[0,1] op_sel_hi:[1,0] neg_lo:[0,1]
	v_pk_add_f32 v[130:131], v[126:127], v[182:183] op_sel:[0,1] op_sel_hi:[1,0] neg_hi:[0,1]
	v_pk_mul_f32 v[110:111], v[176:177], s[68:69] op_sel:[1,1] op_sel_hi:[0,1]
	v_pk_fma_f32 v[176:177], v[176:177], s[68:69], v[110:111] op_sel_hi:[1,0,1] neg_hi:[0,0,1]
	v_pk_mul_f32 v[102:103], v[166:167], s[84:85] op_sel:[1,1] op_sel_hi:[0,1]
	v_pk_fma_f32 v[166:167], v[166:167], s[84:85], v[102:103] op_sel_hi:[1,0,1] neg_hi:[0,0,1]
	v_pk_mul_f32 v[184:185], v[174:175], s[88:89] op_sel:[1,1] op_sel_hi:[0,1]
	v_pk_fma_f32 v[174:175], v[174:175], s[88:89], v[184:185] op_sel_hi:[1,0,1] neg_hi:[0,0,1]
	v_pk_mul_f32 v[186:187], v[112:113], s[84:85] op_sel:[1,1] op_sel_hi:[0,1]
	v_pk_fma_f32 v[112:113], v[112:113], s[84:85], v[186:187] op_sel_hi:[1,0,1] neg_hi:[0,0,1]
	v_pk_mul_f32 v[188:189], v[128:129], s[90:91] op_sel:[1,1] op_sel_hi:[0,1]
	v_pk_fma_f32 v[128:129], v[128:129], s[90:91], v[188:189] op_sel_hi:[1,0,1] neg_hi:[0,0,1]
	v_pk_mul_f32 v[168:169], v[114:115], s[88:89] op_sel:[1,1] op_sel_hi:[0,1]
	v_pk_fma_f32 v[114:115], v[114:115], s[88:89], v[168:169] op_sel_hi:[1,0,1] neg_hi:[0,0,1]
	v_pk_mul_f32 v[180:181], v[122:123], s[90:91] op_sel:[1,1] op_sel_hi:[0,1]
	v_pk_fma_f32 v[122:123], v[122:123], s[90:91], v[180:181] op_sel_hi:[1,0,1] neg_hi:[0,0,1]
	v_pk_mul_f32 v[126:127], v[130:131], s[98:99] op_sel:[1,1] op_sel_hi:[0,1]
	v_pk_fma_f32 v[130:131], v[130:131], s[98:99], v[126:127] op_sel_hi:[1,0,1] neg_hi:[0,0,1]
	v_pk_add_f32 v[118:119], v[100:101], v[116:117]
	v_pk_add_f32 v[182:183], v[100:101], v[116:117] neg_lo:[0,1] neg_hi:[0,1]
	v_pk_add_f32 v[110:111], v[108:109], v[124:125]
	v_pk_add_f32 v[102:103], v[108:109], v[124:125] neg_lo:[0,1] neg_hi:[0,1]
	v_pk_add_f32 v[100:101], v[118:119], v[110:111]
	v_pk_add_f32 v[116:117], v[118:119], v[110:111] neg_lo:[0,1] neg_hi:[0,1]
	v_pk_add_f32 v[108:109], v[182:183], v[102:103] op_sel:[0,1] op_sel_hi:[1,0] neg_lo:[0,1]
	v_pk_add_f32 v[124:125], v[182:183], v[102:103] op_sel:[0,1] op_sel_hi:[1,0] neg_hi:[0,1]
	v_pk_add_f32 v[184:185], v[178:179], v[166:167]
	v_pk_add_f32 v[186:187], v[178:179], v[166:167] neg_lo:[0,1] neg_hi:[0,1]
	v_pk_add_f32 v[188:189], v[176:177], v[174:175]
	v_pk_add_f32 v[168:169], v[176:177], v[174:175] neg_lo:[0,1] neg_hi:[0,1]
	v_pk_add_f32 v[178:179], v[184:185], v[188:189]
	v_pk_add_f32 v[166:167], v[184:185], v[188:189] neg_lo:[0,1] neg_hi:[0,1]
	v_pk_add_f32 v[176:177], v[186:187], v[168:169] op_sel:[0,1] op_sel_hi:[1,0] neg_lo:[0,1]
	v_pk_add_f32 v[174:175], v[186:187], v[168:169] op_sel:[0,1] op_sel_hi:[1,0] neg_hi:[0,1]
	v_pk_add_f32 v[180:181], v[104:105], v[120:121] op_sel:[0,1] op_sel_hi:[1,0] neg_lo:[0,1]
	v_pk_add_f32 v[126:127], v[104:105], v[120:121] op_sel:[0,1] op_sel_hi:[1,0] neg_hi:[0,1]
	v_pk_add_f32 v[118:119], v[112:113], v[128:129]
	v_pk_add_f32 v[182:183], v[112:113], v[128:129] neg_lo:[0,1] neg_hi:[0,1]
	v_pk_add_f32 v[104:105], v[180:181], v[118:119]
	v_pk_add_f32 v[120:121], v[180:181], v[118:119] neg_lo:[0,1] neg_hi:[0,1]
	v_pk_add_f32 v[112:113], v[126:127], v[182:183] op_sel:[0,1] op_sel_hi:[1,0] neg_lo:[0,1]
	v_pk_add_f32 v[128:129], v[126:127], v[182:183] op_sel:[0,1] op_sel_hi:[1,0] neg_hi:[0,1]
	v_pk_add_f32 v[110:111], v[106:107], v[122:123]
	v_pk_add_f32 v[102:103], v[106:107], v[122:123] neg_lo:[0,1] neg_hi:[0,1]
	v_pk_add_f32 v[184:185], v[114:115], v[130:131]
	v_pk_add_f32 v[186:187], v[114:115], v[130:131] neg_lo:[0,1] neg_hi:[0,1]
	v_pk_add_f32 v[106:107], v[110:111], v[184:185]
	v_pk_add_f32 v[122:123], v[110:111], v[184:185] neg_lo:[0,1] neg_hi:[0,1]
	v_pk_add_f32 v[114:115], v[102:103], v[186:187] op_sel:[0,1] op_sel_hi:[1,0] neg_lo:[0,1]
	v_pk_add_f32 v[130:131], v[102:103], v[186:187] op_sel:[0,1] op_sel_hi:[1,0] neg_hi:[0,1]
	ds_write_b64 v5, v[100:101]
	ds_write_b64 v5, v[178:179] offset:264
	ds_write_b64 v5, v[104:105] offset:528
	ds_write_b64 v5, v[106:107] offset:792
	ds_write_b64 v5, v[108:109] offset:1056
	ds_write_b64 v5, v[176:177] offset:1320
	ds_write_b64 v5, v[112:113] offset:1584
	ds_write_b64 v5, v[114:115] offset:1848
	ds_write_b64 v5, v[116:117] offset:2112
	ds_write_b64 v5, v[166:167] offset:2376
	ds_write_b64 v5, v[120:121] offset:2640
	ds_write_b64 v5, v[122:123] offset:2904
	ds_write_b64 v5, v[124:125] offset:3168
	ds_write_b64 v5, v[174:175] offset:3432
	ds_write_b64 v5, v[128:129] offset:3696
	ds_write_b64 v5, v[130:131] offset:3960
	s_waitcnt lgkmcnt(0)
	s_barrier
; #define LAS __attribute__((address_space(3)))
; __device__ __forceinline__ f32x2 cmulc(f32x2 a, f32x2 b) { return (f32x2){a.x * b.x + a.y * b.y, a.y * b.x - a.x * b.y}; }
; __device__ __forceinline__ void dft16_inv_lo(f32x2 (&x)[16]) {
;     constexpr float C1 = 0.92387953251128674f, S1 = 0.38268343236508977f, C2 = 0.70710678118654752f;
; #pragma unroll
;     for (int b = 0; b < 4; ++b) dft4<true>(x[b], x[4 + b], x[8 + b], x[12 + b]);
;     const f32x2 w1 = {C1, -S1}, w2 = {C2, -C2}, w3 = {S1, -C1}, w4 = {0.f, -1.f}, w6 = {-C2, -C2}, w9 = {-C1, S1};
;     x[5] = cmulc(x[5], w1); x[6] = cmulc(x[6], w2); x[7] = cmulc(x[7], w3);
;     x[9] = cmulc(x[9], w2); x[10] = cmulc(x[10], w4); x[11] = cmulc(x[11], w6);
;     x[13] = cmulc(x[13], w3); x[14] = cmulc(x[14], w6); x[15] = cmulc(x[15], w9);
; __device__ __forceinline__ void fft_inv1(f32x2 (&x)[16], const LAS f32x2* B, int n2, const f32x2 (&w)[16]) {
;     asm volatile("" : "+v"(n2));
;     x[0] = B[fpad(n2)];
; #pragma unroll
;     for (int k = 1; k < 16; ++k) x[k] = cmulc(B[fpad(512 * k + n2)], w[k]);
;     dft16_inv_lo(x);
; }
	ds_read_b64 v[100:101], v3
	ds_read_b64 v[108:109], v3 offset:16896
	ds_read_b64 v[116:117], v3 offset:33792
	ds_read_b64 v[124:125], v3 offset:50688
	ds_read_b64 v[178:179], v3 offset:4224
	ds_read_b64 v[176:177], v3 offset:21120
	ds_read_b64 v[166:167], v3 offset:38016
	ds_read_b64 v[174:175], v3 offset:54912
	ds_read_b64 v[104:105], v3 offset:8448
	ds_read_b64 v[112:113], v3 offset:25344
	ds_read_b64 v[120:121], v3 offset:42240
	ds_read_b64 v[128:129], v3 offset:59136
	ds_read_b64 v[106:107], v3 offset:12672
	ds_read_b64 v[114:115], v3 offset:29568
	ds_read_b64 v[122:123], v3 offset:46464
	ds_read_b64 v[130:131], v3 offset:63360
	s_waitcnt lgkmcnt(14)
	v_pk_mul_f32 v[188:189], v[108:109], v[12:13] op_sel:[1,1] op_sel_hi:[0,1]
	v_pk_fma_f32 v[108:109], v[108:109], v[12:13], v[188:189] op_sel_hi:[1,0,1] neg_hi:[0,0,1]
	s_waitcnt lgkmcnt(13)
	v_pk_mul_f32 v[168:169], v[116:117], v[20:21] op_sel:[1,1] op_sel_hi:[0,1]
	v_pk_fma_f32 v[116:117], v[116:117], v[20:21], v[168:169] op_sel_hi:[1,0,1] neg_hi:[0,0,1]
	s_waitcnt lgkmcnt(12)
	v_pk_mul_f32 v[180:181], v[124:125], v[28:29] op_sel:[1,1] op_sel_hi:[0,1]
	v_pk_fma_f32 v[124:125], v[124:125], v[28:29], v[180:181] op_sel_hi:[1,0,1] neg_hi:[0,0,1]
	s_waitcnt lgkmcnt(11)
	v_pk_mul_f32 v[126:127], v[178:179], v[6:7] op_sel:[1,1] op_sel_hi:[0,1]
	v_pk_fma_f32 v[178:179], v[178:179], v[6:7], v[126:127] op_sel_hi:[1,0,1] neg_hi:[0,0,1]
	s_waitcnt lgkmcnt(10)
	v_pk_mul_f32 v[118:119], v[176:177], v[14:15] op_sel:[1,1] op_sel_hi:[0,1]
	v_pk_fma_f32 v[176:177], v[176:177], v[14:15], v[118:119] op_sel_hi:[1,0,1] neg_hi:[0,0,1]
	s_waitcnt lgkmcnt(9)
	v_pk_mul_f32 v[182:183], v[166:167], v[22:23] op_sel:[1,1] op_sel_hi:[0,1]
	v_pk_fma_f32 v[166:167], v[166:167], v[22:23], v[182:183] op_sel_hi:[1,0,1] neg_hi:[0,0,1]
	s_waitcnt lgkmcnt(8)
	v_pk_mul_f32 v[110:111], v[174:175], v[30:31] op_sel:[1,1] op_sel_hi:[0,1]
	v_pk_fma_f32 v[174:175], v[174:175], v[30:31], v[110:111] op_sel_hi:[1,0,1] neg_hi:[0,0,1]
	s_waitcnt lgkmcnt(7)
	v_pk_mul_f32 v[102:103], v[104:105], v[8:9] op_sel:[1,1] op_sel_hi:[0,1]
	v_pk_fma_f32 v[104:105], v[104:105], v[8:9], v[102:103] op_sel_hi:[1,0,1] neg_hi:[0,0,1]
	s_waitcnt lgkmcnt(6)
	v_pk_mul_f32 v[184:185], v[112:113], v[16:17] op_sel:[1,1] op_sel_hi:[0,1]
	v_pk_fma_f32 v[112:113], v[112:113], v[16:17], v[184:185] op_sel_hi:[1,0,1] neg_hi:[0,0,1]
	s_waitcnt lgkmcnt(5)
	v_pk_mul_f32 v[186:187], v[120:121], v[24:25] op_sel:[1,1] op_sel_hi:[0,1]
	v_pk_fma_f32 v[120:121], v[120:121], v[24:25], v[186:187] op_sel_hi:[1,0,1] neg_hi:[0,0,1]
	s_waitcnt lgkmcnt(4)
	v_pk_mul_f32 v[188:189], v[128:129], v[32:33] op_sel:[1,1] op_sel_hi:[0,1]
	v_pk_fma_f32 v[128:129], v[128:129], v[32:33], v[188:189] op_sel_hi:[1,0,1] neg_hi:[0,0,1]
	s_waitcnt lgkmcnt(3)
	v_pk_mul_f32 v[168:169], v[106:107], v[10:11] op_sel:[1,1] op_sel_hi:[0,1]
	v_pk_fma_f32 v[106:107], v[106:107], v[10:11], v[168:169] op_sel_hi:[1,0,1] neg_hi:[0,0,1]
	s_waitcnt lgkmcnt(2)
	v_pk_mul_f32 v[180:181], v[114:115], v[18:19] op_sel:[1,1] op_sel_hi:[0,1]
	v_pk_fma_f32 v[114:115], v[114:115], v[18:19], v[180:181] op_sel_hi:[1,0,1] neg_hi:[0,0,1]
	s_waitcnt lgkmcnt(1)
	v_pk_mul_f32 v[126:127], v[122:123], v[26:27] op_sel:[1,1] op_sel_hi:[0,1]
	v_pk_fma_f32 v[122:123], v[122:123], v[26:27], v[126:127] op_sel_hi:[1,0,1] neg_hi:[0,0,1]
	s_waitcnt lgkmcnt(0)
	v_pk_mul_f32 v[118:119], v[130:131], v[34:35] op_sel:[1,1] op_sel_hi:[0,1]
	v_pk_fma_f32 v[130:131], v[130:131], v[34:35], v[118:119] op_sel_hi:[1,0,1] neg_hi:[0,0,1]
	v_pk_add_f32 v[182:183], v[100:101], v[116:117]
	v_pk_add_f32 v[110:111], v[100:101], v[116:117] neg_lo:[0,1] neg_hi:[0,1]
	v_pk_add_f32 v[102:103], v[108:109], v[124:125]
	v_pk_add_f32 v[184:185], v[108:109], v[124:125] neg_lo:[0,1] neg_hi:[0,1]
	v_pk_add_f32 v[100:101], v[182:183], v[102:103]
	v_pk_add_f32 v[116:117], v[182:183], v[102:103] neg_lo:[0,1] neg_hi:[0,1]
	v_pk_add_f32 v[108:109], v[110:111], v[184:185] op_sel:[0,1] op_sel_hi:[1,0] neg_lo:[0,1]
	v_pk_add_f32 v[124:125], v[110:111], v[184:185] op_sel:[0,1] op_sel_hi:[1,0] neg_hi:[0,1]
	v_pk_add_f32 v[186:187], v[178:179], v[166:167]
	v_pk_add_f32 v[188:189], v[178:179], v[166:167] neg_lo:[0,1] neg_hi:[0,1]
	v_pk_add_f32 v[168:169], v[176:177], v[174:175]
	v_pk_add_f32 v[180:181], v[176:177], v[174:175] neg_lo:[0,1] neg_hi:[0,1]
	v_pk_add_f32 v[178:179], v[186:187], v[168:169]
	v_pk_add_f32 v[166:167], v[186:187], v[168:169] neg_lo:[0,1] neg_hi:[0,1]
	v_pk_add_f32 v[176:177], v[188:189], v[180:181] op_sel:[0,1] op_sel_hi:[1,0] neg_lo:[0,1]
	v_pk_add_f32 v[174:175], v[188:189], v[180:181] op_sel:[0,1] op_sel_hi:[1,0] neg_hi:[0,1]
	v_pk_add_f32 v[126:127], v[104:105], v[120:121]
	v_pk_add_f32 v[118:119], v[104:105], v[120:121] neg_lo:[0,1] neg_hi:[0,1]
	v_pk_add_f32 v[182:183], v[112:113], v[128:129]
	v_pk_add_f32 v[110:111], v[112:113], v[128:129] neg_lo:[0,1] neg_hi:[0,1]
	v_pk_add_f32 v[104:105], v[126:127], v[182:183]
	v_pk_add_f32 v[120:121], v[126:127], v[182:183] neg_lo:[0,1] neg_hi:[0,1]
	v_pk_add_f32 v[112:113], v[118:119], v[110:111] op_sel:[0,1] op_sel_hi:[1,0] neg_lo:[0,1]
	v_pk_add_f32 v[128:129], v[118:119], v[110:111] op_sel:[0,1] op_sel_hi:[1,0] neg_hi:[0,1]
	v_pk_add_f32 v[102:103], v[106:107], v[122:123]
	v_pk_add_f32 v[184:185], v[106:107], v[122:123] neg_lo:[0,1] neg_hi:[0,1]
	v_pk_add_f32 v[186:187], v[114:115], v[130:131]
	v_pk_add_f32 v[188:189], v[114:115], v[130:131] neg_lo:[0,1] neg_hi:[0,1]
	v_pk_add_f32 v[106:107], v[102:103], v[186:187]
	v_pk_add_f32 v[122:123], v[102:103], v[186:187] neg_lo:[0,1] neg_hi:[0,1]
	v_pk_add_f32 v[114:115], v[184:185], v[188:189] op_sel:[0,1] op_sel_hi:[1,0] neg_lo:[0,1]
; __device__ __forceinline__ f32x2 cmulc(f32x2 a, f32x2 b) { return (f32x2){a.x * b.x + a.y * b.y, a.y * b.x - a.x * b.y}; }
; #define WG_SYNC() do { asm volatile("s_waitcnt lgkmcnt(0)" ::: "memory"); __builtin_amdgcn_s_barrier(); asm volatile("" ::: "memory"); } while (0)
; __device__ __forceinline__ void dft16_inv_lo(f32x2 (&x)[16]) {
;     ...
;     x[5] = cmulc(x[5], w1); x[6] = cmulc(x[6], w2); x[7] = cmulc(x[7], w3);
;     x[9] = cmulc(x[9], w2); x[10] = cmulc(x[10], w4); x[11] = cmulc(x[11], w6);
;     x[13] = cmulc(x[13], w3); x[14] = cmulc(x[14], w6); x[15] = cmulc(x[15], w9);
;     f32x2 y[8];
; #pragma unroll
;     for (int c = 0; c < 4; ++c) { const f32x2 t0 = x[4 * c] + x[4 * c + 2], t1 = x[4 * c] - x[4 * c + 2], t2 = x[4 * c + 1] + x[4 * c + 3], t3 = x[4 * c + 1] - x[4 * c + 3];
;         y[c] = t0 + t2; y[4 + c] = t1 + (f32x2){-t3.y, t3.x}; }
; #pragma unroll
;     for (int k = 0; k < 8; ++k) x[k] = y[k];
; __device__ __forceinline__ void hyena_fft(LAS unsigned char* lds, int layer, int G, const int wave_s) {
;     ...
;             { const float fb0 = fbias[c];
; #pragma unroll
;               for (int r = 0; r < 8; ++r) { uz[r][0] = ux[r][0] * (x[r].x + fb0 * uz[r][0]); uz[r][1] = ux[r][1] * (x[r].y + fb0 * uz[r][1]); } }
;             WG_SYNC();
;             hy_stage(pl0, PHY, (HY / 4) + unit, jc, tid);
;             WG_SYNC();
	v_pk_add_f32 v[130:131], v[184:185], v[188:189] op_sel:[0,1] op_sel_hi:[1,0] neg_hi:[0,1]
	v_pk_mul_f32 v[168:169], v[176:177], s[68:69] op_sel:[1,1] op_sel_hi:[0,1]
	v_pk_fma_f32 v[176:177], v[176:177], s[68:69], v[168:169] op_sel_hi:[1,0,1] neg_hi:[0,0,1]
	v_pk_mul_f32 v[180:181], v[112:113], s[84:85] op_sel:[1,1] op_sel_hi:[0,1]
	v_pk_fma_f32 v[112:113], v[112:113], s[84:85], v[180:181] op_sel_hi:[1,0,1] neg_hi:[0,0,1]
	v_pk_mul_f32 v[126:127], v[114:115], s[88:89] op_sel:[1,1] op_sel_hi:[0,1]
	v_pk_fma_f32 v[114:115], v[114:115], s[88:89], v[126:127] op_sel_hi:[1,0,1] neg_hi:[0,0,1]
	v_pk_mul_f32 v[118:119], v[166:167], s[84:85] op_sel:[1,1] op_sel_hi:[0,1]
	v_pk_fma_f32 v[166:167], v[166:167], s[84:85], v[118:119] op_sel_hi:[1,0,1] neg_hi:[0,0,1]
	v_pk_mul_f32 v[182:183], v[122:123], s[90:91] op_sel:[1,1] op_sel_hi:[0,1]
	v_pk_fma_f32 v[122:123], v[122:123], s[90:91], v[182:183] op_sel_hi:[1,0,1] neg_hi:[0,0,1]
	v_pk_mul_f32 v[110:111], v[174:175], s[88:89] op_sel:[1,1] op_sel_hi:[0,1]
	v_pk_fma_f32 v[174:175], v[174:175], s[88:89], v[110:111] op_sel_hi:[1,0,1] neg_hi:[0,0,1]
	v_pk_mul_f32 v[102:103], v[128:129], s[90:91] op_sel:[1,1] op_sel_hi:[0,1]
	v_pk_fma_f32 v[128:129], v[128:129], s[90:91], v[102:103] op_sel_hi:[1,0,1] neg_hi:[0,0,1]
	v_pk_mul_f32 v[184:185], v[130:131], s[98:99] op_sel:[1,1] op_sel_hi:[0,1]
	v_pk_fma_f32 v[130:131], v[130:131], s[98:99], v[184:185] op_sel_hi:[1,0,1] neg_hi:[0,0,1]
	v_pk_add_f32 v[186:187], v[100:101], v[104:105]
	v_pk_add_f32 v[188:189], v[100:101], v[104:105] neg_lo:[0,1] neg_hi:[0,1]
	v_pk_add_f32 v[168:169], v[178:179], v[106:107]
	v_pk_add_f32 v[180:181], v[178:179], v[106:107] neg_lo:[0,1] neg_hi:[0,1]
	v_pk_add_f32 v[100:101], v[186:187], v[168:169]
	v_pk_add_f32 v[178:179], v[188:189], v[180:181] op_sel:[0,1] op_sel_hi:[1,0] neg_lo:[0,1]
	v_pk_add_f32 v[126:127], v[108:109], v[112:113]
	v_pk_add_f32 v[118:119], v[108:109], v[112:113] neg_lo:[0,1] neg_hi:[0,1]
	v_pk_add_f32 v[182:183], v[176:177], v[114:115]
	v_pk_add_f32 v[110:111], v[176:177], v[114:115] neg_lo:[0,1] neg_hi:[0,1]
	v_pk_add_f32 v[108:109], v[126:127], v[182:183]
	v_pk_add_f32 v[176:177], v[118:119], v[110:111] op_sel:[0,1] op_sel_hi:[1,0] neg_lo:[0,1]
	v_pk_add_f32 v[102:103], v[116:117], v[120:121] op_sel:[0,1] op_sel_hi:[1,0] neg_lo:[0,1]
	v_pk_add_f32 v[184:185], v[116:117], v[120:121] op_sel:[0,1] op_sel_hi:[1,0] neg_hi:[0,1]
	v_pk_add_f32 v[186:187], v[166:167], v[122:123]
	v_pk_add_f32 v[188:189], v[166:167], v[122:123] neg_lo:[0,1] neg_hi:[0,1]
	v_pk_add_f32 v[116:117], v[102:103], v[186:187]
	v_pk_add_f32 v[166:167], v[184:185], v[188:189] op_sel:[0,1] op_sel_hi:[1,0] neg_lo:[0,1]
	v_pk_add_f32 v[168:169], v[124:125], v[128:129]
	v_pk_add_f32 v[180:181], v[124:125], v[128:129] neg_lo:[0,1] neg_hi:[0,1]
	v_pk_add_f32 v[126:127], v[174:175], v[130:131]
	v_pk_add_f32 v[118:119], v[174:175], v[130:131] neg_lo:[0,1] neg_hi:[0,1]
	v_pk_add_f32 v[124:125], v[168:169], v[126:127]
	v_pk_add_f32 v[174:175], v[180:181], v[118:119] op_sel:[0,1] op_sel_hi:[1,0] neg_lo:[0,1]
	s_load_dword s35, s[50:51], 0x0
	s_waitcnt lgkmcnt(0)
	v_mov_b32_e32 v194, s35
	v_pk_fma_f32 v[182:183], v[132:133], v[194:195], v[100:101] op_sel_hi:[1,0,1]
	v_pk_mul_f32 v[132:133], v[148:149], v[182:183]
	v_pk_fma_f32 v[110:111], v[134:135], v[194:195], v[108:109] op_sel_hi:[1,0,1]
	v_pk_mul_f32 v[134:135], v[150:151], v[110:111]
	v_pk_fma_f32 v[102:103], v[136:137], v[194:195], v[116:117] op_sel_hi:[1,0,1]
	v_pk_mul_f32 v[136:137], v[152:153], v[102:103]
	v_pk_fma_f32 v[184:185], v[138:139], v[194:195], v[124:125] op_sel_hi:[1,0,1]
	v_pk_mul_f32 v[138:139], v[154:155], v[184:185]
	v_pk_fma_f32 v[186:187], v[140:141], v[194:195], v[178:179] op_sel_hi:[1,0,1]
	v_pk_mul_f32 v[140:141], v[158:159], v[186:187]
	v_pk_fma_f32 v[188:189], v[142:143], v[194:195], v[176:177] op_sel_hi:[1,0,1]
	v_pk_mul_f32 v[142:143], v[160:161], v[188:189]
	v_pk_fma_f32 v[168:169], v[144:145], v[194:195], v[166:167] op_sel_hi:[1,0,1]
	v_pk_mul_f32 v[144:145], v[162:163], v[168:169]
	v_pk_fma_f32 v[180:181], v[146:147], v[194:195], v[174:175] op_sel_hi:[1,0,1]
	v_pk_mul_f32 v[146:147], v[164:165], v[180:181]
	s_waitcnt lgkmcnt(0)
	s_barrier
	s_waitcnt vmcnt(7)
	v_perm_b32 v126, 0, v58, s15
	v_perm_b32 v127, 0, v60, s15
	ds_write_b64 v206, v[126:127]
	s_waitcnt vmcnt(6)
	v_perm_b32 v118, 0, v62, s15
	v_perm_b32 v119, 0, v64, s15
	ds_write_b64 v206, v[118:119] offset:4096
	s_waitcnt vmcnt(5)
	v_perm_b32 v182, 0, v66, s15
	v_perm_b32 v183, 0, v68, s15
	ds_write_b64 v206, v[182:183] offset:8192
	s_waitcnt vmcnt(4)
	v_perm_b32 v110, 0, v70, s15
	v_perm_b32 v111, 0, v72, s15
	ds_write_b64 v206, v[110:111] offset:12288
	s_waitcnt vmcnt(3)
	v_perm_b32 v102, 0, v74, s15
	v_perm_b32 v103, 0, v76, s15
	ds_write_b64 v206, v[102:103] offset:16384
	s_waitcnt vmcnt(2)
	v_perm_b32 v184, 0, v78, s15
	v_perm_b32 v185, 0, v80, s15
	ds_write_b64 v206, v[184:185] offset:20480
	s_waitcnt vmcnt(1)
	v_perm_b32 v186, 0, v82, s15
	v_perm_b32 v187, 0, v84, s15
	ds_write_b64 v206, v[186:187] offset:24576
	s_waitcnt vmcnt(0)
	v_perm_b32 v188, 0, v86, s15
	v_perm_b32 v189, 0, v88, s15
	ds_write_b64 v206, v[188:189] offset:28672
	s_waitcnt lgkmcnt(0)
	s_barrier
; #define LAS __attribute__((address_space(3)))
; __device__ __forceinline__ void hy_sconv(const LAS float* plane, float w0, float w1, float w2, float cb, int n2, float (&u)[8][2]) {
;     asm volatile("" : "+v"(n2));
; #pragma unroll
;     for (int r = 0; r < 8; ++r)
; #pragma unroll
;         for (int b = 0; b < 2; ++b) { const int t = n2 + 512 * r, row = b * SEQ + t;
;             float a = cb + w1 * plane[row];
;             if (t > 0) a += w0 * plane[row - 1];
;             if (t < SEQ - 1) a += w2 * plane[row + 1];
;             u[r][b] = a; }
; }
	v_mov_b32_e32 v168, s17
	v_mov_b32_e32 v169, s23
	v_mov_b32_e32 v180, s25
	v_mov_b32_e32 v181, s26
	ds_read_b32 v126, v208
	ds_read_b32 v118, v210
	ds_read_b32 v182, v208 offset:4
	ds_read_b32 v127, v208 offset:16384
	ds_read_b32 v119, v210 offset:16384
	ds_read_b32 v183, v208 offset:16388
	ds_read_b32 v110, v208 offset:2048
	ds_read_b32 v102, v208 offset:2044
	ds_read_b32 v184, v208 offset:2052
	ds_read_b32 v111, v208 offset:18432
	ds_read_b32 v103, v208 offset:18428
	ds_read_b32 v185, v208 offset:18436
	s_waitcnt lgkmcnt(10)
	v_cndmask_b32_e64 v118, v118, 0, s[10:11]
	s_waitcnt lgkmcnt(7)
	v_cndmask_b32_e64 v119, v119, 0, s[10:11]
	v_pk_fma_f32 v[148:149], v[168:169], v[126:127], v[180:181] op_sel:[1,0,1]
	v_pk_fma_f32 v[148:149], v[168:169], v[118:119], v[148:149] op_sel_hi:[0,1,1]
	s_waitcnt lgkmcnt(6)
	v_pk_fma_f32 v[148:149], v[180:181], v[182:183], v[148:149] op_sel_hi:[0,1,1]
	s_waitcnt lgkmcnt(2)
	v_pk_fma_f32 v[150:151], v[168:169], v[110:111], v[180:181] op_sel:[1,0,1]
	s_waitcnt lgkmcnt(1)
	v_pk_fma_f32 v[150:151], v[168:169], v[102:103], v[150:151] op_sel_hi:[0,1,1]
	s_waitcnt lgkmcnt(0)
	v_pk_fma_f32 v[150:151], v[180:181], v[184:185], v[150:151] op_sel_hi:[0,1,1]
	ds_read_b32 v186, v208 offset:4096
	ds_read_b32 v188, v208 offset:4092
	ds_read_b32 v126, v208 offset:4100
	ds_read_b32 v187, v208 offset:20480
	ds_read_b32 v189, v208 offset:20476
	ds_read_b32 v127, v208 offset:20484
	ds_read_b32 v118, v208 offset:6144
	ds_read_b32 v182, v208 offset:6140
	ds_read_b32 v110, v208 offset:6148
	ds_read_b32 v119, v208 offset:22528
	ds_read_b32 v183, v208 offset:22524
	ds_read_b32 v111, v208 offset:22532
	s_waitcnt lgkmcnt(8)
	v_pk_fma_f32 v[152:153], v[168:169], v[186:187], v[180:181] op_sel:[1,0,1]
	s_waitcnt lgkmcnt(7)
	v_pk_fma_f32 v[152:153], v[168:169], v[188:189], v[152:153] op_sel_hi:[0,1,1]
	s_waitcnt lgkmcnt(6)
	v_pk_fma_f32 v[152:153], v[180:181], v[126:127], v[152:153] op_sel_hi:[0,1,1]
	s_waitcnt lgkmcnt(2)
	v_pk_fma_f32 v[154:155], v[168:169], v[118:119], v[180:181] op_sel:[1,0,1]
	s_waitcnt lgkmcnt(1)
	v_pk_fma_f32 v[154:155], v[168:169], v[182:183], v[154:155] op_sel_hi:[0,1,1]
	s_waitcnt lgkmcnt(0)
	v_pk_fma_f32 v[154:155], v[180:181], v[110:111], v[154:155] op_sel_hi:[0,1,1]
	ds_read_b32 v102, v208 offset:8192
	ds_read_b32 v184, v208 offset:8188
	ds_read_b32 v186, v208 offset:8196
	ds_read_b32 v103, v208 offset:24576
	ds_read_b32 v185, v208 offset:24572
	ds_read_b32 v187, v208 offset:24580
	ds_read_b32 v188, v208 offset:10240
	ds_read_b32 v126, v208 offset:10236
	ds_read_b32 v118, v208 offset:10244
	ds_read_b32 v189, v208 offset:26624
	ds_read_b32 v127, v208 offset:26620
	ds_read_b32 v119, v208 offset:26628
	s_waitcnt lgkmcnt(8)
	v_pk_fma_f32 v[158:159], v[168:169], v[102:103], v[180:181] op_sel:[1,0,1]
	s_waitcnt lgkmcnt(7)
	v_pk_fma_f32 v[158:159], v[168:169], v[184:185], v[158:159] op_sel_hi:[0,1,1]
	s_waitcnt lgkmcnt(6)
	v_pk_fma_f32 v[158:159], v[180:181], v[186:187], v[158:159] op_sel_hi:[0,1,1]
	s_waitcnt lgkmcnt(2)
	v_pk_fma_f32 v[160:161], v[168:169], v[188:189], v[180:181] op_sel:[1,0,1]
	s_waitcnt lgkmcnt(1)
	v_pk_fma_f32 v[160:161], v[168:169], v[126:127], v[160:161] op_sel_hi:[0,1,1]
	s_waitcnt lgkmcnt(0)
	v_pk_fma_f32 v[160:161], v[180:181], v[118:119], v[160:161] op_sel_hi:[0,1,1]
	ds_read_b32 v182, v208 offset:12288
	ds_read_b32 v110, v208 offset:12284
	ds_read_b32 v102, v208 offset:12292
	ds_read_b32 v183, v208 offset:28672
	ds_read_b32 v111, v208 offset:28668
	ds_read_b32 v103, v208 offset:28676
	ds_read_b32 v184, v208 offset:14336
	ds_read_b32 v186, v208 offset:14332
	ds_read_b32 v188, v208 offset:14340
	ds_read_b32 v185, v208 offset:30720
	ds_read_b32 v187, v208 offset:30716
	ds_read_b32 v189, v208 offset:30724
	s_waitcnt lgkmcnt(8)
	v_pk_fma_f32 v[162:163], v[168:169], v[182:183], v[180:181] op_sel:[1,0,1]
	s_waitcnt lgkmcnt(7)
	v_pk_fma_f32 v[162:163], v[168:169], v[110:111], v[162:163] op_sel_hi:[0,1,1]
	s_waitcnt lgkmcnt(6)
	v_pk_fma_f32 v[162:163], v[180:181], v[102:103], v[162:163] op_sel_hi:[0,1,1]
	s_waitcnt lgkmcnt(3)
	v_cndmask_b32_e64 v188, v188, 0, s[28:29]
	s_waitcnt lgkmcnt(0)
	v_cndmask_b32_e64 v189, v189, 0, s[28:29]
	v_pk_fma_f32 v[164:165], v[168:169], v[184:185], v[180:181] op_sel:[1,0,1]
	v_pk_fma_f32 v[164:165], v[168:169], v[186:187], v[164:165] op_sel_hi:[0,1,1]
	v_pk_fma_f32 v[164:165], v[180:181], v[188:189], v[164:165] op_sel_hi:[0,1,1]
	s_waitcnt lgkmcnt(0)
	s_barrier
; __device__ __forceinline__ f32x2 cmul(f32x2 a, f32x2 b) { return (f32x2){a.x * b.x - a.y * b.y, a.x * b.y + a.y * b.x}; }
; __device__ __forceinline__ void dft16_fwd_lo(f32x2 (&x)[16]) {
;     constexpr float C1 = 0.92387953251128674f, S1 = 0.38268343236508977f, C2 = 0.70710678118654752f;
; #pragma unroll
;     for (int b = 0; b < 4; ++b) { const f32x2 x0 = x[b], x1 = x[4 + b]; const f32x2 j1 = {x1.y, -x1.x};
;         x[b] = x0 + x1; x[4 + b] = x0 + j1; x[8 + b] = x0 - x1; x[12 + b] = x0 - j1; }
;     const f32x2 w1 = {C1, -S1}, w2 = {C2, -C2}, w3 = {S1, -C1}, w4 = {0.f, -1.f}, w6 = {-C2, -C2}, w9 = {-C1, S1};
;     x[5] = cmul(x[5], w1); x[6] = cmul(x[6], w2); x[7] = cmul(x[7], w3);
;     x[9] = cmul(x[9], w2); x[10] = cmul(x[10], w4); x[11] = cmul(x[11], w6);
;     x[13] = cmul(x[13], w3); x[14] = cmul(x[14], w6); x[15] = cmul(x[15], w9);
; #pragma unroll
;     for (int c = 0; c < 4; ++c) dft4<false>(x[4 * c], x[4 * c + 1], x[4 * c + 2], x[4 * c + 3]);
; __device__ __forceinline__ void hyena_fft(LAS unsigned char* lds, int layer, int G, const int wave_s) {
;     ...
;             for (int r = 0; r < 8; ++r) { x[r] = (f32x2){uz[r][0], uz[r][1]}; x[r + 8] = (f32x2){0.f, 0.f}; }
	v_pk_add_f32 v[104:105], v[132:133], v[140:141] neg_lo:[0,1] neg_hi:[0,1]
	v_pk_add_f32 v[106:107], v[132:133], v[140:141] op_sel:[0,1] op_sel_hi:[1,0] neg_lo:[0,1]
	v_pk_add_f32 v[126:127], v[132:133], v[140:141] op_sel:[0,1] op_sel_hi:[1,0] neg_hi:[0,1]
	v_pk_add_f32 v[100:101], v[132:133], v[140:141]
	v_pk_add_f32 v[112:113], v[134:135], v[142:143] neg_lo:[0,1] neg_hi:[0,1]
	v_pk_add_f32 v[114:115], v[134:135], v[142:143] op_sel:[0,1] op_sel_hi:[1,0] neg_lo:[0,1]
	v_pk_add_f32 v[118:119], v[134:135], v[142:143] op_sel:[0,1] op_sel_hi:[1,0] neg_hi:[0,1]
	v_pk_add_f32 v[108:109], v[134:135], v[142:143]
	v_pk_add_f32 v[120:121], v[136:137], v[144:145] neg_lo:[0,1] neg_hi:[0,1]
	v_pk_add_f32 v[122:123], v[136:137], v[144:145] op_sel:[0,1] op_sel_hi:[1,0] neg_lo:[0,1]
	v_pk_add_f32 v[182:183], v[136:137], v[144:145] op_sel:[0,1] op_sel_hi:[1,0] neg_hi:[0,1]
	v_pk_add_f32 v[116:117], v[136:137], v[144:145]
	v_pk_add_f32 v[128:129], v[138:139], v[146:147] neg_lo:[0,1] neg_hi:[0,1]
	v_pk_add_f32 v[130:131], v[138:139], v[146:147] op_sel:[0,1] op_sel_hi:[1,0] neg_lo:[0,1]
	v_pk_add_f32 v[110:111], v[138:139], v[146:147] op_sel:[0,1] op_sel_hi:[1,0] neg_hi:[0,1]
	v_pk_add_f32 v[124:125], v[138:139], v[146:147]
	v_pk_mul_f32 v[102:103], v[118:119], s[68:69] op_sel:[1,1] op_sel_hi:[0,1]
	v_pk_fma_f32 v[118:119], v[118:119], s[68:69], v[102:103] op_sel_hi:[1,0,1] neg_lo:[0,0,1]
	v_pk_mul_f32 v[184:185], v[182:183], s[84:85] op_sel:[1,1] op_sel_hi:[0,1]
	v_pk_fma_f32 v[182:183], v[182:183], s[84:85], v[184:185] op_sel_hi:[1,0,1] neg_lo:[0,0,1]
	v_pk_mul_f32 v[186:187], v[110:111], s[88:89] op_sel:[1,1] op_sel_hi:[0,1]
	v_pk_fma_f32 v[110:111], v[110:111], s[88:89], v[186:187] op_sel_hi:[1,0,1] neg_lo:[0,0,1]
	v_pk_mul_f32 v[188:189], v[112:113], s[84:85] op_sel:[1,1] op_sel_hi:[0,1]
	v_pk_fma_f32 v[112:113], v[112:113], s[84:85], v[188:189] op_sel_hi:[1,0,1] neg_lo:[0,0,1]
	v_pk_mul_f32 v[168:169], v[128:129], s[90:91] op_sel:[1,1] op_sel_hi:[0,1]
	v_pk_fma_f32 v[128:129], v[128:129], s[90:91], v[168:169] op_sel_hi:[1,0,1] neg_lo:[0,0,1]
	v_pk_mul_f32 v[180:181], v[114:115], s[88:89] op_sel:[1,1] op_sel_hi:[0,1]
	v_pk_fma_f32 v[114:115], v[114:115], s[88:89], v[180:181] op_sel_hi:[1,0,1] neg_lo:[0,0,1]
	v_pk_mul_f32 v[178:179], v[122:123], s[90:91] op_sel:[1,1] op_sel_hi:[0,1]
	v_pk_fma_f32 v[122:123], v[122:123], s[90:91], v[178:179] op_sel_hi:[1,0,1] neg_lo:[0,0,1]
	v_pk_mul_f32 v[176:177], v[130:131], s[98:99] op_sel:[1,1] op_sel_hi:[0,1]
	v_pk_fma_f32 v[130:131], v[130:131], s[98:99], v[176:177] op_sel_hi:[1,0,1] neg_lo:[0,0,1]
	v_pk_add_f32 v[166:167], v[100:101], v[116:117]
	v_pk_add_f32 v[174:175], v[100:101], v[116:117] neg_lo:[0,1] neg_hi:[0,1]
	v_pk_add_f32 v[102:103], v[108:109], v[124:125]
	v_pk_add_f32 v[184:185], v[108:109], v[124:125] neg_lo:[0,1] neg_hi:[0,1]
	v_pk_add_f32 v[100:101], v[166:167], v[102:103]
	v_pk_add_f32 v[116:117], v[166:167], v[102:103] neg_lo:[0,1] neg_hi:[0,1]
	v_pk_add_f32 v[108:109], v[174:175], v[184:185] op_sel:[0,1] op_sel_hi:[1,0] neg_hi:[0,1]
	v_pk_add_f32 v[124:125], v[174:175], v[184:185] op_sel:[0,1] op_sel_hi:[1,0] neg_lo:[0,1]
	v_pk_add_f32 v[186:187], v[126:127], v[182:183]
	v_pk_add_f32 v[188:189], v[126:127], v[182:183] neg_lo:[0,1] neg_hi:[0,1]
	v_pk_add_f32 v[168:169], v[118:119], v[110:111]
	v_pk_add_f32 v[180:181], v[118:119], v[110:111] neg_lo:[0,1] neg_hi:[0,1]
	v_pk_add_f32 v[126:127], v[186:187], v[168:169]
	v_pk_add_f32 v[182:183], v[186:187], v[168:169] neg_lo:[0,1] neg_hi:[0,1]
	v_pk_add_f32 v[118:119], v[188:189], v[180:181] op_sel:[0,1] op_sel_hi:[1,0] neg_hi:[0,1]
	v_pk_add_f32 v[110:111], v[188:189], v[180:181] op_sel:[0,1] op_sel_hi:[1,0] neg_lo:[0,1]
	v_pk_add_f32 v[178:179], v[104:105], v[120:121] op_sel:[0,1] op_sel_hi:[1,0] neg_hi:[0,1]
	v_pk_add_f32 v[176:177], v[104:105], v[120:121] op_sel:[0,1] op_sel_hi:[1,0] neg_lo:[0,1]
	v_pk_add_f32 v[166:167], v[112:113], v[128:129]
	v_pk_add_f32 v[174:175], v[112:113], v[128:129] neg_lo:[0,1] neg_hi:[0,1]
	v_pk_add_f32 v[104:105], v[178:179], v[166:167]
; __device__ __forceinline__ f32x2 cmul(f32x2 a, f32x2 b) { return (f32x2){a.x * b.x - a.y * b.y, a.x * b.y + a.y * b.x}; }
; __device__ __forceinline__ void dft16_fwd_lo(f32x2 (&x)[16]) {
;     ...
; #pragma unroll
;     for (int c = 0; c < 4; ++c) dft4<false>(x[4 * c], x[4 * c + 1], x[4 * c + 2], x[4 * c + 3]);
;     f32x2 y[16];
; #pragma unroll
;     for (int k = 0; k < 16; ++k) y[k] = x[4 * (k & 3) + (k >> 2)];
; #pragma unroll
;     for (int k = 0; k < 16; ++k) x[k] = y[k];
; template <bool LO> __device__ __forceinline__ void fft_fwd1(f32x2 (&x)[16], LAS f32x2* B, int n2, const f32x2 (&w)[16]) {
;     ...
;     B[fpad(n2)] = x[0];
; #pragma unroll
;     for (int k = 1; k < 16; ++k) B[fpad(512 * k + n2)] = cmul(x[k], w[k]);
	v_pk_add_f32 v[120:121], v[178:179], v[166:167] neg_lo:[0,1] neg_hi:[0,1]
	v_pk_add_f32 v[112:113], v[176:177], v[174:175] op_sel:[0,1] op_sel_hi:[1,0] neg_hi:[0,1]
	v_pk_add_f32 v[128:129], v[176:177], v[174:175] op_sel:[0,1] op_sel_hi:[1,0] neg_lo:[0,1]
	v_pk_add_f32 v[102:103], v[106:107], v[122:123]
	v_pk_add_f32 v[184:185], v[106:107], v[122:123] neg_lo:[0,1] neg_hi:[0,1]
	v_pk_add_f32 v[186:187], v[114:115], v[130:131]
	v_pk_add_f32 v[188:189], v[114:115], v[130:131] neg_lo:[0,1] neg_hi:[0,1]
	v_pk_add_f32 v[106:107], v[102:103], v[186:187]
	v_pk_add_f32 v[122:123], v[102:103], v[186:187] neg_lo:[0,1] neg_hi:[0,1]
	v_pk_add_f32 v[114:115], v[184:185], v[188:189] op_sel:[0,1] op_sel_hi:[1,0] neg_hi:[0,1]
	v_pk_add_f32 v[130:131], v[184:185], v[188:189] op_sel:[0,1] op_sel_hi:[1,0] neg_lo:[0,1]
	ds_write_b64 v3, v[100:101]
	v_pk_mul_f32 v[180:181], v[126:127], v[6:7] op_sel:[1,1] op_sel_hi:[0,1]
	v_pk_fma_f32 v[168:169], v[126:127], v[6:7], v[180:181] op_sel_hi:[1,0,1] neg_lo:[0,0,1]
	ds_write_b64 v3, v[168:169] offset:4224
	v_pk_mul_f32 v[176:177], v[104:105], v[8:9] op_sel:[1,1] op_sel_hi:[0,1]
	v_pk_fma_f32 v[178:179], v[104:105], v[8:9], v[176:177] op_sel_hi:[1,0,1] neg_lo:[0,0,1]
	ds_write_b64 v3, v[178:179] offset:8448
	v_pk_mul_f32 v[174:175], v[106:107], v[10:11] op_sel:[1,1] op_sel_hi:[0,1]
	v_pk_fma_f32 v[166:167], v[106:107], v[10:11], v[174:175] op_sel_hi:[1,0,1] neg_lo:[0,0,1]
	ds_write_b64 v3, v[166:167] offset:12672
	v_pk_mul_f32 v[184:185], v[108:109], v[12:13] op_sel:[1,1] op_sel_hi:[0,1]
	v_pk_fma_f32 v[102:103], v[108:109], v[12:13], v[184:185] op_sel_hi:[1,0,1] neg_lo:[0,0,1]
	ds_write_b64 v3, v[102:103] offset:16896
	v_pk_mul_f32 v[188:189], v[118:119], v[14:15] op_sel:[1,1] op_sel_hi:[0,1]
	v_pk_fma_f32 v[186:187], v[118:119], v[14:15], v[188:189] op_sel_hi:[1,0,1] neg_lo:[0,0,1]
	ds_write_b64 v3, v[186:187] offset:21120
	v_pk_mul_f32 v[168:169], v[112:113], v[16:17] op_sel:[1,1] op_sel_hi:[0,1]
	v_pk_fma_f32 v[180:181], v[112:113], v[16:17], v[168:169] op_sel_hi:[1,0,1] neg_lo:[0,0,1]
	ds_write_b64 v3, v[180:181] offset:25344
	v_pk_mul_f32 v[178:179], v[114:115], v[18:19] op_sel:[1,1] op_sel_hi:[0,1]
	v_pk_fma_f32 v[176:177], v[114:115], v[18:19], v[178:179] op_sel_hi:[1,0,1] neg_lo:[0,0,1]
	ds_write_b64 v3, v[176:177] offset:29568
	v_pk_mul_f32 v[166:167], v[116:117], v[20:21] op_sel:[1,1] op_sel_hi:[0,1]
	v_pk_fma_f32 v[174:175], v[116:117], v[20:21], v[166:167] op_sel_hi:[1,0,1] neg_lo:[0,0,1]
	ds_write_b64 v3, v[174:175] offset:33792
	v_pk_mul_f32 v[102:103], v[182:183], v[22:23] op_sel:[1,1] op_sel_hi:[0,1]
	v_pk_fma_f32 v[184:185], v[182:183], v[22:23], v[102:103] op_sel_hi:[1,0,1] neg_lo:[0,0,1]
	ds_write_b64 v3, v[184:185] offset:38016
	v_pk_mul_f32 v[186:187], v[120:121], v[24:25] op_sel:[1,1] op_sel_hi:[0,1]
	v_pk_fma_f32 v[188:189], v[120:121], v[24:25], v[186:187] op_sel_hi:[1,0,1] neg_lo:[0,0,1]
	ds_write_b64 v3, v[188:189] offset:42240
	v_pk_mul_f32 v[180:181], v[122:123], v[26:27] op_sel:[1,1] op_sel_hi:[0,1]
	v_pk_fma_f32 v[168:169], v[122:123], v[26:27], v[180:181] op_sel_hi:[1,0,1] neg_lo:[0,0,1]
	ds_write_b64 v3, v[168:169] offset:46464
	v_pk_mul_f32 v[176:177], v[124:125], v[28:29] op_sel:[1,1] op_sel_hi:[0,1]
	v_pk_fma_f32 v[178:179], v[124:125], v[28:29], v[176:177] op_sel_hi:[1,0,1] neg_lo:[0,0,1]
	ds_write_b64 v3, v[178:179] offset:50688
	v_pk_mul_f32 v[174:175], v[110:111], v[30:31] op_sel:[1,1] op_sel_hi:[0,1]
	v_pk_fma_f32 v[166:167], v[110:111], v[30:31], v[174:175] op_sel_hi:[1,0,1] neg_lo:[0,0,1]
	ds_write_b64 v3, v[166:167] offset:54912
	v_pk_mul_f32 v[184:185], v[128:129], v[32:33] op_sel:[1,1] op_sel_hi:[0,1]
	v_pk_fma_f32 v[102:103], v[128:129], v[32:33], v[184:185] op_sel_hi:[1,0,1] neg_lo:[0,0,1]
	ds_write_b64 v3, v[102:103] offset:59136
	v_pk_mul_f32 v[188:189], v[130:131], v[34:35] op_sel:[1,1] op_sel_hi:[0,1]
	v_pk_fma_f32 v[186:187], v[130:131], v[34:35], v[188:189] op_sel_hi:[1,0,1] neg_lo:[0,0,1]
	ds_write_b64 v3, v[186:187] offset:63360
	s_waitcnt lgkmcnt(0)
	s_barrier
	s_cbranch_vccz .Lhfft_st10
	s_sleep 16
